# speedup vs baseline: 1.0017x; 1.0017x over previous
; #define PG8_STAGE(bufoff, gbase, voff) do { _Pragma("unroll") for (int _i = 0; _i < 2; ++_i) \
;         __builtin_amdgcn_global_load_lds((const unsigned*)((const char*)(gbase) + (voff)[_i]), (LAS unsigned*)(lds + (bufoff) + ldsw + _i * 8192), 16, 0, 0); } while (0)
; #define PG8_LDA(dst, b, h) do { _Pragma("unroll") for (int m = 0; m < 4; ++m) _Pragma("unroll") for (int k = 0; k < 2; ++k) dst[m][k] = *(const LAS bf16x8*)(lds + PG8_SA(b, h) + aoff + m * 2048 + k * 1024); } while (0)
; #define PG8_WAIT_L(n) asm volatile("s_waitcnt lgkmcnt(" #n ")" ::: "memory")
; #define PG8_BAR __builtin_amdgcn_s_barrier()
; #define PG8_SCHED __builtin_amdgcn_sched_barrier(0)
;     ...
;         const bool has_next = S.next(ui + 1, nxt);
;         const char* nA = has_next ? (const char*)g.A + (size_t)nxt.pm * tstep + (size_t)nxt.k0 * kstep : cA; const char* nB = has_next ? (const char*)g.Bt + (size_t)nxt.pn * tstep + (size_t)nxt.k0 * kstep : cB;
;         const int nt = cur.nt;
;         for (int t = 0; t < nt; t += 2) {
;             const bool last = (t == nt - 2);
;             if (last && has_next && gate != nullptr && nxt.pm >= 32) {
;                 if (tid < 64) { unsigned sp = 0;
;                     while ((unsigned)__builtin_amdgcn_readfirstlane(__hip_atomic_load(gate, __ATOMIC_RELAXED, __HIP_MEMORY_SCOPE_AGENT)) < gate_need) { __builtin_amdgcn_s_sleep(2); if (++sp > (1u << 20)) break; }
;                     __builtin_amdgcn_fence(__ATOMIC_ACQUIRE, "agent"); asm volatile("s_waitcnt vmcnt(0)" ::: "memory"); }
;                 asm volatile("" ::: "memory"); PG8_BAR; asm volatile("" ::: "memory");
;             }
;             const char* a1 = cA + (size_t)(t + 1) * kstep;
;             const char* a2 = last ? nA : cA + (size_t)(t + 2) * kstep; const char* b2 = last ? nB : cB + (size_t)(t + 2) * kstep;
;             const char* a3 = a2 + kstep; const char* b3 = b2 + kstep;
;             PG8_LDB(B0, 0, 0); PG8_SCHED; PG8_LDA(At, 0, 0); PG8_STAGE(PG8_SA(1, 1), a1 + hstep, voffA);
;             PG8_WAIT_L(8); PG8_BAR; PG8_WAIT_L(0); PG8_MMA(0, 0, At, B0); PG8_BAR; PG8_SCHED;
;             PG8_LDB(B1, 0, 1); PG8_STAGE(PG8_SB(0, 0), b2, voffB);
;             PG8_BAR; PG8_WAIT_L(0); PG8_MMA(0, 1, At, B1); PG8_BAR;
;             PG8_LDA(At, 0, 1); PG8_STAGE(PG8_SA(0, 0), a2, voffA);
;             PG8_BAR; PG8_WAIT_L(0); PG8_MMA(1, 0, At, B0); PG8_BAR; PG8_SCHED;
.LBB0_120:
	s_add_i32 s44, s2, 2
	s_add_u32 s10, s8, 0x100
	s_addc_u32 s11, s9, 0
	s_add_i32 s35, 0, 0x10000
	v_add_u32_e32 v156, s35, v145
	ds_read_b128 v[140:143], v156
	ds_read_b128 v[148:151], v156 offset:1024
	ds_read_b128 v[152:155], v156 offset:2048
	ds_read_b128 v[156:159], v156 offset:3072
	s_cmp_eq_u32 s41, s2
	s_cselect_b32 s2, s6, s10
	s_cselect_b32 s3, s7, s11
	s_cselect_b32 s13, s19, s43
	s_cselect_b32 s12, s18, s42
	v_lshl_add_u64 v[192:193], s[8:9], 0, v[136:137]
	s_add_i32 m0, s21, 0xc000
	ds_read_b128 v[160:163], v147
	ds_read_b128 v[164:167], v147 offset:1024
	ds_read_b128 v[168:171], v147 offset:2048
	ds_read_b128 v[172:175], v147 offset:3072
	ds_read_b128 v[176:179], v147 offset:4096
	ds_read_b128 v[180:183], v147 offset:5120
	ds_read_b128 v[184:187], v147 offset:6144
	ds_read_b128 v[188:191], v147 offset:7168
	global_load_lds_dwordx4 v[192:193], off
	v_lshl_add_u64 v[192:193], s[8:9], 0, v[138:139]
	s_add_i32 m0, s21, 0xe000
	s_nop 0
	global_load_lds_dwordx4 v[192:193], off
	s_waitcnt lgkmcnt(8)
	s_barrier
	s_waitcnt lgkmcnt(0)
	s_waitcnt lgkmcnt(0)
	v_mfma_f32_16x16x32_bf16 v[126:129], v[140:143], v[160:163], v[126:129]
	v_mfma_f32_16x16x32_bf16 v[122:125], v[152:155], v[160:163], v[122:125]
	v_mfma_f32_16x16x32_bf16 v[110:113], v[140:143], v[168:171], v[110:113]
	v_mfma_f32_16x16x32_bf16 v[106:109], v[152:155], v[168:171], v[106:109]
	v_mfma_f32_16x16x32_bf16 v[94:97], v[140:143], v[176:179], v[94:97]
	v_mfma_f32_16x16x32_bf16 v[90:93], v[152:155], v[176:179], v[90:93]
	v_mfma_f32_16x16x32_bf16 v[78:81], v[140:143], v[184:187], v[78:81]
	v_mfma_f32_16x16x32_bf16 v[74:77], v[152:155], v[184:187], v[74:77]
	v_mfma_f32_16x16x32_bf16 v[126:129], v[148:151], v[164:167], v[126:129]
	v_mfma_f32_16x16x32_bf16 v[122:125], v[156:159], v[164:167], v[122:125]
	v_mfma_f32_16x16x32_bf16 v[110:113], v[148:151], v[172:175], v[110:113]
	v_mfma_f32_16x16x32_bf16 v[106:109], v[156:159], v[172:175], v[106:109]
	v_mfma_f32_16x16x32_bf16 v[94:97], v[148:151], v[180:183], v[94:97]
	v_mfma_f32_16x16x32_bf16 v[90:93], v[156:159], v[180:183], v[90:93]
	v_mfma_f32_16x16x32_bf16 v[78:81], v[148:151], v[188:191], v[78:81]
	v_mfma_f32_16x16x32_bf16 v[74:77], v[156:159], v[188:191], v[74:77]
	s_barrier
	s_add_i32 s45, 0, 0x14000
	v_add_u32_e32 v208, s45, v145
	s_add_i32 s8, s35, s20
	ds_read_b128 v[192:195], v208
	ds_read_b128 v[196:199], v208 offset:1024
	ds_read_b128 v[220:223], v208 offset:2048
	ds_read_b128 v[224:227], v208 offset:3072
	v_lshl_add_u64 v[208:209], s[12:13], 0, v[64:65]
	s_mov_b32 m0, s8
	v_lshl_add_u64 v[210:211], s[12:13], 0, v[134:135]
	global_load_lds_dwordx4 v[208:209], off
	s_add_i32 m0, s8, 0x2000
	s_nop 0
	global_load_lds_dwordx4 v[210:211], off
	s_barrier
	s_waitcnt lgkmcnt(0)
	s_waitcnt lgkmcnt(0)
	v_mfma_f32_16x16x32_bf16 v[118:121], v[192:195], v[160:163], v[118:121]
	v_mfma_f32_16x16x32_bf16 v[114:117], v[220:223], v[160:163], v[114:117]
	v_mfma_f32_16x16x32_bf16 v[102:105], v[192:195], v[168:171], v[102:105]
	v_mfma_f32_16x16x32_bf16 v[98:101], v[220:223], v[168:171], v[98:101]
	v_mfma_f32_16x16x32_bf16 v[86:89], v[192:195], v[176:179], v[86:89]
	v_mfma_f32_16x16x32_bf16 v[82:85], v[220:223], v[176:179], v[82:85]
	v_mfma_f32_16x16x32_bf16 v[70:73], v[192:195], v[184:187], v[70:73]
	v_mfma_f32_16x16x32_bf16 v[66:69], v[220:223], v[184:187], v[66:69]
	v_mfma_f32_16x16x32_bf16 v[118:121], v[196:199], v[164:167], v[118:121]
	v_mfma_f32_16x16x32_bf16 v[114:117], v[224:227], v[164:167], v[114:117]
	v_mfma_f32_16x16x32_bf16 v[102:105], v[196:199], v[172:175], v[102:105]
	v_mfma_f32_16x16x32_bf16 v[98:101], v[224:227], v[172:175], v[98:101]
	v_mfma_f32_16x16x32_bf16 v[86:89], v[196:199], v[180:183], v[86:89]
	v_mfma_f32_16x16x32_bf16 v[82:85], v[224:227], v[180:183], v[82:85]
	v_mfma_f32_16x16x32_bf16 v[70:73], v[196:199], v[188:191], v[70:73]
	v_mfma_f32_16x16x32_bf16 v[66:69], v[224:227], v[188:191], v[66:69]
	s_mov_b32 m0, s21
	v_lshl_add_u64 v[212:213], s[2:3], 0, v[130:131]
	s_barrier
	ds_read_b128 v[160:163], v147 offset:16384
	ds_read_b128 v[164:167], v147 offset:17408
	ds_read_b128 v[168:171], v147 offset:18432
	ds_read_b128 v[172:175], v147 offset:19456
	ds_read_b128 v[176:179], v147 offset:20480
	ds_read_b128 v[180:183], v147 offset:21504
	ds_read_b128 v[184:187], v147 offset:22528
	ds_read_b128 v[188:191], v147 offset:23552
	global_load_lds_dwordx4 v[212:213], off
	v_lshl_add_u64 v[214:215], s[2:3], 0, v[132:133]
	s_mov_b32 m0, s22
	s_nop 0
	global_load_lds_dwordx4 v[214:215], off
	s_barrier
	s_waitcnt lgkmcnt(0)
	s_waitcnt lgkmcnt(0)
	v_mfma_f32_16x16x32_bf16 v[60:63], v[140:143], v[160:163], v[60:63]
	v_mfma_f32_16x16x32_bf16 v[56:59], v[152:155], v[160:163], v[56:59]
	v_mfma_f32_16x16x32_bf16 v[44:47], v[140:143], v[168:171], v[44:47]
	v_mfma_f32_16x16x32_bf16 v[40:43], v[152:155], v[168:171], v[40:43]
	v_mfma_f32_16x16x32_bf16 v[28:31], v[140:143], v[176:179], v[28:31]
	v_mfma_f32_16x16x32_bf16 v[24:27], v[152:155], v[176:179], v[24:27]
	v_mfma_f32_16x16x32_bf16 v[12:15], v[140:143], v[184:187], v[12:15]
	v_mfma_f32_16x16x32_bf16 v[8:11], v[152:155], v[184:187], v[8:11]
	v_mfma_f32_16x16x32_bf16 v[60:63], v[148:151], v[164:167], v[60:63]
	v_mfma_f32_16x16x32_bf16 v[56:59], v[156:159], v[164:167], v[56:59]
	v_mfma_f32_16x16x32_bf16 v[44:47], v[148:151], v[172:175], v[44:47]
	v_mfma_f32_16x16x32_bf16 v[40:43], v[156:159], v[172:175], v[40:43]
	v_mfma_f32_16x16x32_bf16 v[28:31], v[148:151], v[180:183], v[28:31]
	v_mfma_f32_16x16x32_bf16 v[24:27], v[156:159], v[180:183], v[24:27]
	v_mfma_f32_16x16x32_bf16 v[12:15], v[148:151], v[188:191], v[12:15]
	v_mfma_f32_16x16x32_bf16 v[8:11], v[156:159], v[188:191], v[8:11]
	s_barrier
; #define PG8_STAGE(bufoff, gbase, voff) do { _Pragma("unroll") for (int _i = 0; _i < 2; ++_i) \
;         __builtin_amdgcn_global_load_lds((const unsigned*)((const char*)(gbase) + (voff)[_i]), (LAS unsigned*)(lds + (bufoff) + ldsw + _i * 8192), 16, 0, 0); } while (0)
; #define PG8_LDA(dst, b, h) do { _Pragma("unroll") for (int m = 0; m < 4; ++m) _Pragma("unroll") for (int k = 0; k < 2; ++k) dst[m][k] = *(const LAS bf16x8*)(lds + PG8_SA(b, h) + aoff + m * 2048 + k * 1024); } while (0)
; #define PG8_LDB(dst, b, h) do { _Pragma("unroll") for (int n = 0; n < 2; ++n) _Pragma("unroll") for (int k = 0; k < 2; ++k) dst[n][k] = *(const LAS bf16x8*)(lds + PG8_SB(b, h) + boff + n * 2048 + k * 1024); } while (0)
; #define PG8_MMA(ai, bj, At, Bt) do { __builtin_amdgcn_s_setprio(1); _Pragma("unroll") for (int m = 0; m < 4; ++m) _Pragma("unroll") for (int n = 0; n < 2; ++n) _Pragma("unroll") for (int k = 0; k < 2; ++k) \
;         acc[ai][bj][m][n] = __builtin_amdgcn_mfma_f32_16x16x32_bf16(Bt[n][k], At[m][k], acc[ai][bj][m][n], 0, 0, 0); __builtin_amdgcn_s_setprio(0); } while (0)
; #define PG8_WAIT_V(n) asm volatile("s_waitcnt vmcnt(" #n ")" ::: "memory")
; #define PG8_WAIT_L(n) asm volatile("s_waitcnt lgkmcnt(" #n ")" ::: "memory")
; #define PG8_BAR __builtin_amdgcn_s_barrier()
; #define PG8_SCHED __builtin_amdgcn_sched_barrier(0)
;     ...
;             PG8_BAR; PG8_WAIT_L(0); PG8_MMA(1, 0, At, B0); PG8_BAR; PG8_SCHED;
;             PG8_STAGE(PG8_SB(0, 1), b2 + hstep, voffB);
;             PG8_WAIT_V(6); PG8_BAR; PG8_MMA(1, 1, At, B1); PG8_BAR;
;             PG8_LDB(B0, 1, 0); PG8_SCHED; PG8_LDA(At, 1, 0); PG8_STAGE(PG8_SA(0, 1), a2 + hstep, voffA);
;             PG8_WAIT_L(8); PG8_BAR; PG8_WAIT_L(0); PG8_MMA(0, 0, At, B0); PG8_BAR; PG8_SCHED;
;             PG8_LDB(B1, 1, 1); PG8_STAGE(PG8_SB(1, 0), b3, voffB);
;             PG8_BAR; PG8_WAIT_L(0); PG8_MMA(0, 1, At, B1); PG8_BAR;
;             PG8_LDA(At, 1, 1); PG8_STAGE(PG8_SA(1, 0), a3, voffA);
;             PG8_BAR; PG8_WAIT_L(0); PG8_MMA(1, 0, At, B0); PG8_BAR; PG8_SCHED;
	s_add_u32 s8, s12, 0x84000
	s_addc_u32 s9, s13, 0
	s_add_i32 s35, s45, s20
	v_lshl_add_u64 v[140:141], s[8:9], 0, v[64:65]
	s_mov_b32 m0, s35
	s_nop 0
	global_load_lds_dwordx4 v[140:141], off
	v_lshl_add_u64 v[140:141], s[8:9], 0, v[134:135]
	s_add_i32 m0, s35, 0x2000
	s_nop 0
	global_load_lds_dwordx4 v[140:141], off
	s_waitcnt vmcnt(6)
	s_barrier
	v_mfma_f32_16x16x32_bf16 v[52:55], v[192:195], v[160:163], v[52:55]
	v_mfma_f32_16x16x32_bf16 v[48:51], v[220:223], v[160:163], v[48:51]
	v_mfma_f32_16x16x32_bf16 v[36:39], v[192:195], v[168:171], v[36:39]
	v_mfma_f32_16x16x32_bf16 v[32:35], v[220:223], v[168:171], v[32:35]
	v_mfma_f32_16x16x32_bf16 v[20:23], v[192:195], v[176:179], v[20:23]
	v_mfma_f32_16x16x32_bf16 v[16:19], v[220:223], v[176:179], v[16:19]
	v_mfma_f32_16x16x32_bf16 v[4:7], v[192:195], v[184:187], v[4:7]
	v_mfma_f32_16x16x32_bf16 v[0:3], v[220:223], v[184:187], v[0:3]
	v_mfma_f32_16x16x32_bf16 v[52:55], v[196:199], v[164:167], v[52:55]
	v_mfma_f32_16x16x32_bf16 v[48:51], v[224:227], v[164:167], v[48:51]
	v_mfma_f32_16x16x32_bf16 v[36:39], v[196:199], v[172:175], v[36:39]
	v_mfma_f32_16x16x32_bf16 v[32:35], v[224:227], v[172:175], v[32:35]
	v_mfma_f32_16x16x32_bf16 v[20:23], v[196:199], v[180:183], v[20:23]
	v_mfma_f32_16x16x32_bf16 v[16:19], v[224:227], v[180:183], v[16:19]
	v_mfma_f32_16x16x32_bf16 v[4:7], v[196:199], v[188:191], v[4:7]
	v_mfma_f32_16x16x32_bf16 v[0:3], v[224:227], v[188:191], v[0:3]
	s_add_i32 s8, 0, 0x18000
	v_add_u32_e32 v156, s8, v145
	s_barrier
	ds_read_b128 v[140:143], v156
	ds_read_b128 v[148:151], v156 offset:1024
	ds_read_b128 v[152:155], v156 offset:2048
	ds_read_b128 v[156:159], v156 offset:3072
	s_add_u32 s2, s2, 0x84000
	s_addc_u32 s3, s3, 0
	s_mov_b32 m0, s23
	v_lshl_add_u64 v[192:193], s[2:3], 0, v[130:131]
	ds_read_b128 v[160:163], v147 offset:32768
	ds_read_b128 v[164:167], v147 offset:33792
	ds_read_b128 v[168:171], v147 offset:34816
	ds_read_b128 v[172:175], v147 offset:35840
	ds_read_b128 v[176:179], v147 offset:36864
	ds_read_b128 v[180:183], v147 offset:37888
	ds_read_b128 v[184:187], v147 offset:38912
	ds_read_b128 v[188:191], v147 offset:39936
	global_load_lds_dwordx4 v[192:193], off
	v_lshl_add_u64 v[192:193], s[2:3], 0, v[132:133]
	s_mov_b32 m0, s24
	s_nop 0
	global_load_lds_dwordx4 v[192:193], off
	s_waitcnt lgkmcnt(8)
	s_barrier
	s_waitcnt lgkmcnt(0)
	s_waitcnt lgkmcnt(0)
	v_mfma_f32_16x16x32_bf16 v[126:129], v[140:143], v[160:163], v[126:129]
	v_mfma_f32_16x16x32_bf16 v[122:125], v[152:155], v[160:163], v[122:125]
	v_mfma_f32_16x16x32_bf16 v[110:113], v[140:143], v[168:171], v[110:113]
	v_mfma_f32_16x16x32_bf16 v[106:109], v[152:155], v[168:171], v[106:109]
	v_mfma_f32_16x16x32_bf16 v[94:97], v[140:143], v[176:179], v[94:97]
	v_mfma_f32_16x16x32_bf16 v[90:93], v[152:155], v[176:179], v[90:93]
	v_mfma_f32_16x16x32_bf16 v[78:81], v[140:143], v[184:187], v[78:81]
	v_mfma_f32_16x16x32_bf16 v[74:77], v[152:155], v[184:187], v[74:77]
	v_mfma_f32_16x16x32_bf16 v[126:129], v[148:151], v[164:167], v[126:129]
	v_mfma_f32_16x16x32_bf16 v[122:125], v[156:159], v[164:167], v[122:125]
	v_mfma_f32_16x16x32_bf16 v[110:113], v[148:151], v[172:175], v[110:113]
	v_mfma_f32_16x16x32_bf16 v[106:109], v[156:159], v[172:175], v[106:109]
	v_mfma_f32_16x16x32_bf16 v[94:97], v[148:151], v[180:183], v[94:97]
	v_mfma_f32_16x16x32_bf16 v[90:93], v[156:159], v[180:183], v[90:93]
	v_mfma_f32_16x16x32_bf16 v[78:81], v[148:151], v[188:191], v[78:81]
	v_mfma_f32_16x16x32_bf16 v[74:77], v[156:159], v[188:191], v[74:77]
	s_barrier
	s_add_i32 s9, 0, 0x1c000
	s_add_i32 s2, s8, s20
	v_add_u32_e32 v219, s9, v145
	v_lshl_add_u64 v[208:209], v[208:209], 0, s[16:17]
	s_mov_b32 m0, s2
	ds_read_b128 v[192:195], v219
	ds_read_b128 v[196:199], v219 offset:1024
	ds_read_b128 v[220:223], v219 offset:2048
	ds_read_b128 v[224:227], v219 offset:3072
	global_load_lds_dwordx4 v[208:209], off
	v_lshl_add_u64 v[208:209], v[210:211], 0, s[16:17]
	s_add_i32 m0, s2, 0x2000
	s_nop 0
	global_load_lds_dwordx4 v[208:209], off
	s_barrier
	s_waitcnt lgkmcnt(0)
	s_waitcnt lgkmcnt(0)
	v_mfma_f32_16x16x32_bf16 v[118:121], v[192:195], v[160:163], v[118:121]
	v_mfma_f32_16x16x32_bf16 v[114:117], v[220:223], v[160:163], v[114:117]
	v_mfma_f32_16x16x32_bf16 v[102:105], v[192:195], v[168:171], v[102:105]
	v_mfma_f32_16x16x32_bf16 v[98:101], v[220:223], v[168:171], v[98:101]
	v_mfma_f32_16x16x32_bf16 v[86:89], v[192:195], v[176:179], v[86:89]
	v_mfma_f32_16x16x32_bf16 v[82:85], v[220:223], v[176:179], v[82:85]
	v_mfma_f32_16x16x32_bf16 v[70:73], v[192:195], v[184:187], v[70:73]
	v_mfma_f32_16x16x32_bf16 v[66:69], v[220:223], v[184:187], v[66:69]
	v_mfma_f32_16x16x32_bf16 v[118:121], v[196:199], v[164:167], v[118:121]
	v_mfma_f32_16x16x32_bf16 v[114:117], v[224:227], v[164:167], v[114:117]
	v_mfma_f32_16x16x32_bf16 v[102:105], v[196:199], v[172:175], v[102:105]
	v_mfma_f32_16x16x32_bf16 v[98:101], v[224:227], v[172:175], v[98:101]
	v_mfma_f32_16x16x32_bf16 v[86:89], v[196:199], v[180:183], v[86:89]
	v_mfma_f32_16x16x32_bf16 v[82:85], v[224:227], v[180:183], v[82:85]
	v_mfma_f32_16x16x32_bf16 v[70:73], v[196:199], v[188:191], v[70:73]
	v_mfma_f32_16x16x32_bf16 v[66:69], v[224:227], v[188:191], v[66:69]
	s_mov_b32 m0, s25
	v_lshl_add_u64 v[208:209], v[212:213], 0, s[16:17]
	s_barrier
	ds_read_b128 v[160:163], v147 offset:49152
	ds_read_b128 v[164:167], v147 offset:50176
	ds_read_b128 v[168:171], v147 offset:51200
	ds_read_b128 v[172:175], v147 offset:52224
	ds_read_b128 v[176:179], v147 offset:53248
	ds_read_b128 v[180:183], v147 offset:54272
	ds_read_b128 v[184:187], v147 offset:55296
	ds_read_b128 v[188:191], v147 offset:56320
	global_load_lds_dwordx4 v[208:209], off
	v_lshl_add_u64 v[208:209], v[214:215], 0, s[16:17]
	s_mov_b32 m0, s26
	s_nop 0
	global_load_lds_dwordx4 v[208:209], off
	s_barrier
; __device__ __forceinline__ unsigned cvt_pk_bf16(float lo, float hi) { unsigned r; asm volatile("v_cvt_pk_bf16_f32 %0, %1, %2" : "=v"(r) : "v"(lo), "v"(hi)); return r; }
; #define PG8_STAGE(bufoff, gbase, voff) do { _Pragma("unroll") for (int _i = 0; _i < 2; ++_i) \
;         __builtin_amdgcn_global_load_lds((const unsigned*)((const char*)(gbase) + (voff)[_i]), (LAS unsigned*)(lds + (bufoff) + ldsw + _i * 8192), 16, 0, 0); } while (0)
; #define PG8_MMA(ai, bj, At, Bt) do { __builtin_amdgcn_s_setprio(1); _Pragma("unroll") for (int m = 0; m < 4; ++m) _Pragma("unroll") for (int n = 0; n < 2; ++n) _Pragma("unroll") for (int k = 0; k < 2; ++k) \
;         acc[ai][bj][m][n] = __builtin_amdgcn_mfma_f32_16x16x32_bf16(Bt[n][k], At[m][k], acc[ai][bj][m][n], 0, 0, 0); __builtin_amdgcn_s_setprio(0); } while (0)
; #define PG8_WAIT_V(n) asm volatile("s_waitcnt vmcnt(" #n ")" ::: "memory")
; #define PG8_WAIT_L(n) asm volatile("s_waitcnt lgkmcnt(" #n ")" ::: "memory")
; #define PG8_BAR __builtin_amdgcn_s_barrier()
; #define PG8_SCHED __builtin_amdgcn_sched_barrier(0)
;     __device__ __forceinline__ void operator()(const f32x4 (&acc)[2][2][4][2], const Unit& u, int wr, int wc, int fr, int fq) const {
;         const int row0 = u.pm * BM + wr * 64 + fr, col0 = u.pn * BM + wc * 32 + 8 * fq;
; #pragma unroll
;         for (int ai = 0; ai < 2; ++ai)
; #pragma unroll
;             for (int m = 0; m < 4; ++m) { bf16_t* rowp = O + (size_t)(row0 + ai * HALF + m * 16) * LDF + col0;
; #pragma unroll
;                 for (int bj = 0; bj < 2; ++bj) { f32x4 v0 = acc[ai][bj][m][0], v1 = acc[ai][bj][m][1];
; #pragma unroll
;                     for (int j = 0; j < 4; ++j) { const float a = fmaxf(v0[j], 0.f), b = fmaxf(v1[j], 0.f); v0[j] = a * a; v1[j] = b * b; }
;                     u32x4 w; w.x = cvt_pk_bf16(v0[0], v0[1]); w.y = cvt_pk_bf16(v0[2], v0[3]); w.z = cvt_pk_bf16(v1[0], v1[1]); w.w = cvt_pk_bf16(v1[2], v1[3]);
;                     *(u32x4*)(rowp + bj * HALF) = w; } }
;     ...
;             PG8_BAR; PG8_WAIT_L(0); PG8_MMA(1, 0, At, B0); PG8_BAR; PG8_SCHED;
;             PG8_STAGE(PG8_SB(1, 1), b3 + hstep, voffB);
;             PG8_WAIT_V(6); PG8_BAR; PG8_MMA(1, 1, At, B1); PG8_BAR;
;         }
	s_waitcnt lgkmcnt(0)
	s_waitcnt lgkmcnt(0)
	v_mfma_f32_16x16x32_bf16 v[60:63], v[140:143], v[160:163], v[60:63]
	v_mfma_f32_16x16x32_bf16 v[56:59], v[152:155], v[160:163], v[56:59]
	v_mfma_f32_16x16x32_bf16 v[44:47], v[140:143], v[168:171], v[44:47]
	v_mfma_f32_16x16x32_bf16 v[40:43], v[152:155], v[168:171], v[40:43]
	v_mfma_f32_16x16x32_bf16 v[28:31], v[140:143], v[176:179], v[28:31]
	v_mfma_f32_16x16x32_bf16 v[24:27], v[152:155], v[176:179], v[24:27]
	v_mfma_f32_16x16x32_bf16 v[12:15], v[140:143], v[184:187], v[12:15]
	v_mfma_f32_16x16x32_bf16 v[8:11], v[152:155], v[184:187], v[8:11]
	v_mfma_f32_16x16x32_bf16 v[60:63], v[148:151], v[164:167], v[60:63]
	v_mfma_f32_16x16x32_bf16 v[56:59], v[156:159], v[164:167], v[56:59]
	v_mfma_f32_16x16x32_bf16 v[44:47], v[148:151], v[172:175], v[44:47]
	v_mfma_f32_16x16x32_bf16 v[40:43], v[156:159], v[172:175], v[40:43]
	v_mfma_f32_16x16x32_bf16 v[28:31], v[148:151], v[180:183], v[28:31]
	v_mfma_f32_16x16x32_bf16 v[24:27], v[156:159], v[180:183], v[24:27]
	v_mfma_f32_16x16x32_bf16 v[12:15], v[148:151], v[188:191], v[12:15]
	v_mfma_f32_16x16x32_bf16 v[8:11], v[156:159], v[188:191], v[8:11]
	s_barrier
	s_add_u32 s2, s12, 0x84080
	s_addc_u32 s3, s13, 0
	s_add_i32 s8, s9, s20
	v_lshl_add_u64 v[140:141], s[2:3], 0, v[64:65]
	s_mov_b32 m0, s8
	s_nop 0
	global_load_lds_dwordx4 v[140:141], off
	v_lshl_add_u64 v[140:141], s[2:3], 0, v[134:135]
	s_add_i32 m0, s8, 0x2000
	s_nop 0
	global_load_lds_dwordx4 v[140:141], off
	s_waitcnt vmcnt(6)
	s_barrier
	v_mfma_f32_16x16x32_bf16 v[52:55], v[192:195], v[160:163], v[52:55]
	v_mfma_f32_16x16x32_bf16 v[48:51], v[220:223], v[160:163], v[48:51]
	v_mfma_f32_16x16x32_bf16 v[36:39], v[192:195], v[168:171], v[36:39]
	v_mfma_f32_16x16x32_bf16 v[32:35], v[220:223], v[168:171], v[32:35]
	v_mfma_f32_16x16x32_bf16 v[20:23], v[192:195], v[176:179], v[20:23]
	v_mfma_f32_16x16x32_bf16 v[16:19], v[220:223], v[176:179], v[16:19]
	v_mfma_f32_16x16x32_bf16 v[4:7], v[192:195], v[184:187], v[4:7]
	v_mfma_f32_16x16x32_bf16 v[0:3], v[220:223], v[184:187], v[0:3]
	v_mfma_f32_16x16x32_bf16 v[52:55], v[196:199], v[164:167], v[52:55]
	v_mfma_f32_16x16x32_bf16 v[48:51], v[224:227], v[164:167], v[48:51]
	v_mfma_f32_16x16x32_bf16 v[36:39], v[196:199], v[172:175], v[36:39]
	v_mfma_f32_16x16x32_bf16 v[32:35], v[224:227], v[172:175], v[32:35]
	v_mfma_f32_16x16x32_bf16 v[20:23], v[196:199], v[180:183], v[20:23]
	v_mfma_f32_16x16x32_bf16 v[16:19], v[224:227], v[180:183], v[16:19]
	v_mfma_f32_16x16x32_bf16 v[4:7], v[196:199], v[188:191], v[4:7]
	v_mfma_f32_16x16x32_bf16 v[0:3], v[224:227], v[188:191], v[0:3]
	s_add_u32 s42, s42, 0x100
	s_addc_u32 s43, s43, 0
	s_cmp_ge_u32 s44, s40
	s_mov_b64 s[8:9], s[10:11]
	s_mov_b32 s2, s44
	s_barrier
	s_cbranch_scc0 .LBB0_120
	v_max_f32_e32 v122, 0, v122
	v_lshl_or_b32 v142, s37, 8, v146
	v_mul_f32_e32 v151, v122, v122
	v_max_f32_e32 v122, v127, v127
	v_max_f32_e32 v123, 0, v123
	v_max_f32_e32 v124, 0, v124
	v_lshl_add_u32 v150, s38, 8, v144
	v_ashrrev_i32_e32 v143, 31, v142
	v_mov_b64_e32 v[140:141], s[80:81]
	s_movk_i32 s8, 0x4080
	v_max_f32_e32 v122, 0, v122
	v_mul_f32_e32 v127, v123, v123
	v_max_f32_e32 v123, v128, v128
	v_mul_f32_e32 v128, v124, v124
	v_max_f32_e32 v124, v129, v129
	v_mad_i64_i32 v[148:149], s[2:3], v150, s8, v[140:141]
	v_lshlrev_b64 v[142:143], 1, v[142:143]
	v_max_f32_e32 v126, 0, v126
	v_mul_f32_e32 v122, v122, v122
	v_max_f32_e32 v123, 0, v123
	v_max_f32_e32 v124, 0, v124
	v_max_f32_e32 v125, 0, v125
	v_lshl_add_u64 v[148:149], v[148:149], 0, v[142:143]
	v_mul_f32_e32 v126, v126, v126
	v_mul_f32_e32 v123, v123, v123
	v_mul_f32_e32 v124, v124, v124
	v_mul_f32_e32 v125, v125, v125
	v_cvt_pk_bf16_f32 v122, v126, v122
	v_max_f32_e32 v114, 0, v114
	v_max_f32_e32 v115, 0, v115
	v_max_f32_e32 v116, 0, v116
	v_cvt_pk_bf16_f32 v123, v123, v124
	v_cvt_pk_bf16_f32 v124, v151, v127
	v_cvt_pk_bf16_f32 v125, v128, v125
	global_store_dwordx4 v[148:149], v[122:125], off
	s_nop 1
	v_mul_f32_e32 v122, v114, v114
	v_max_f32_e32 v114, v119, v119
	v_mul_f32_e32 v119, v115, v115
	v_max_f32_e32 v115, v120, v120
	v_mul_f32_e32 v120, v116, v116
	v_max_f32_e32 v116, v121, v121
	v_max_f32_e32 v114, 0, v114
	v_max_f32_e32 v115, 0, v115
	v_max_f32_e32 v116, 0, v116
	v_max_f32_e32 v118, 0, v118
	v_mul_f32_e32 v114, v114, v114
	v_mul_f32_e32 v115, v115, v115
	v_max_f32_e32 v117, 0, v117
	v_mul_f32_e32 v116, v116, v116
	v_mul_f32_e32 v118, v118, v118
	v_mul_f32_e32 v117, v117, v117
	v_cvt_pk_bf16_f32 v114, v118, v114
	v_cvt_pk_bf16_f32 v115, v115, v116
	v_cvt_pk_bf16_f32 v116, v122, v119
	v_max_f32_e32 v106, 0, v106
	v_cvt_pk_bf16_f32 v117, v120, v117
	global_store_dwordx4 v[148:149], v[114:117], off offset:256
	s_nop 1
	v_max_f32_e32 v107, 0, v107
	v_max_f32_e32 v108, 0, v108
	v_mul_f32_e32 v116, v106, v106
	v_max_f32_e32 v106, v111, v111
	v_or_b32_e32 v114, 16, v150
	v_max_f32_e32 v106, 0, v106
	v_mul_f32_e32 v111, v107, v107
	v_max_f32_e32 v107, v112, v112
	v_mul_f32_e32 v112, v108, v108
	v_max_f32_e32 v108, v113, v113
	v_mad_i64_i32 v[114:115], s[2:3], v114, s8, v[140:141]
	v_max_f32_e32 v110, 0, v110
	v_mul_f32_e32 v106, v106, v106
	v_max_f32_e32 v107, 0, v107
	v_max_f32_e32 v108, 0, v108
	v_max_f32_e32 v109, 0, v109
	v_lshl_add_u64 v[114:115], v[114:115], 0, v[142:143]
	v_mul_f32_e32 v110, v110, v110
	v_mul_f32_e32 v107, v107, v107
	v_mul_f32_e32 v108, v108, v108
	v_mul_f32_e32 v109, v109, v109
	v_cvt_pk_bf16_f32 v106, v110, v106
	v_max_f32_e32 v98, 0, v98
	v_max_f32_e32 v99, 0, v99
	v_max_f32_e32 v100, 0, v100
	v_cvt_pk_bf16_f32 v107, v107, v108
	v_cvt_pk_bf16_f32 v108, v116, v111
	v_cvt_pk_bf16_f32 v109, v112, v109
	global_store_dwordx4 v[114:115], v[106:109], off
; __device__ __forceinline__ unsigned cvt_pk_bf16(float lo, float hi) { unsigned r; asm volatile("v_cvt_pk_bf16_f32 %0, %1, %2" : "=v"(r) : "v"(lo), "v"(hi)); return r; }
;     __device__ __forceinline__ void operator()(const f32x4 (&acc)[2][2][4][2], const Unit& u, int wr, int wc, int fr, int fq) const {
;         const int row0 = u.pm * BM + wr * 64 + fr, col0 = u.pn * BM + wc * 32 + 8 * fq;
; #pragma unroll
;         for (int ai = 0; ai < 2; ++ai)
; #pragma unroll
;             for (int m = 0; m < 4; ++m) { bf16_t* rowp = O + (size_t)(row0 + ai * HALF + m * 16) * LDF + col0;
; #pragma unroll
;                 for (int bj = 0; bj < 2; ++bj) { f32x4 v0 = acc[ai][bj][m][0], v1 = acc[ai][bj][m][1];
; #pragma unroll
;                     for (int j = 0; j < 4; ++j) { const float a = fmaxf(v0[j], 0.f), b = fmaxf(v1[j], 0.f); v0[j] = a * a; v1[j] = b * b; }
;                     u32x4 w; w.x = cvt_pk_bf16(v0[0], v0[1]); w.y = cvt_pk_bf16(v0[2], v0[3]); w.z = cvt_pk_bf16(v1[0], v1[1]); w.w = cvt_pk_bf16(v1[2], v1[3]);
;                     *(u32x4*)(rowp + bj * HALF) = w; } }
	s_nop 1
	v_mul_f32_e32 v106, v98, v98
	v_max_f32_e32 v98, v103, v103
	v_mul_f32_e32 v103, v99, v99
	v_max_f32_e32 v99, v104, v104
	v_mul_f32_e32 v104, v100, v100
	v_max_f32_e32 v100, v105, v105
	v_max_f32_e32 v98, 0, v98
	v_max_f32_e32 v99, 0, v99
	v_max_f32_e32 v100, 0, v100
	v_max_f32_e32 v102, 0, v102
	v_mul_f32_e32 v98, v98, v98
	v_mul_f32_e32 v99, v99, v99
	v_max_f32_e32 v101, 0, v101
	v_mul_f32_e32 v100, v100, v100
	v_mul_f32_e32 v102, v102, v102
	v_mul_f32_e32 v101, v101, v101
	v_cvt_pk_bf16_f32 v98, v102, v98
	v_cvt_pk_bf16_f32 v99, v99, v100
	v_cvt_pk_bf16_f32 v100, v106, v103
	v_max_f32_e32 v90, 0, v90
	v_cvt_pk_bf16_f32 v101, v104, v101
	global_store_dwordx4 v[114:115], v[98:101], off offset:256
	s_nop 1
	v_max_f32_e32 v91, 0, v91
	v_max_f32_e32 v92, 0, v92
	v_mul_f32_e32 v100, v90, v90
	v_max_f32_e32 v90, v95, v95
	v_or_b32_e32 v98, 32, v150
	v_max_f32_e32 v90, 0, v90
	v_mul_f32_e32 v95, v91, v91
	v_max_f32_e32 v91, v96, v96
	v_mul_f32_e32 v96, v92, v92
	v_max_f32_e32 v92, v97, v97
	v_mad_i64_i32 v[98:99], s[2:3], v98, s8, v[140:141]
	v_max_f32_e32 v94, 0, v94
	v_mul_f32_e32 v90, v90, v90
	v_max_f32_e32 v91, 0, v91
	v_max_f32_e32 v92, 0, v92
	v_max_f32_e32 v93, 0, v93
	v_lshl_add_u64 v[98:99], v[98:99], 0, v[142:143]
	v_mul_f32_e32 v94, v94, v94
	v_mul_f32_e32 v91, v91, v91
	v_mul_f32_e32 v92, v92, v92
	v_mul_f32_e32 v93, v93, v93
	v_cvt_pk_bf16_f32 v90, v94, v90
	v_max_f32_e32 v82, 0, v82
	v_max_f32_e32 v83, 0, v83
	v_max_f32_e32 v84, 0, v84
	v_cvt_pk_bf16_f32 v91, v91, v92
	v_cvt_pk_bf16_f32 v92, v100, v95
	v_cvt_pk_bf16_f32 v93, v96, v93
	global_store_dwordx4 v[98:99], v[90:93], off
	s_nop 1
	v_mul_f32_e32 v90, v82, v82
	v_max_f32_e32 v82, v87, v87
	v_mul_f32_e32 v87, v83, v83
	v_max_f32_e32 v83, v88, v88
	v_mul_f32_e32 v88, v84, v84
	v_max_f32_e32 v84, v89, v89
	v_max_f32_e32 v82, 0, v82
	v_max_f32_e32 v83, 0, v83
	v_max_f32_e32 v84, 0, v84
	v_max_f32_e32 v86, 0, v86
	v_mul_f32_e32 v82, v82, v82
	v_mul_f32_e32 v83, v83, v83
	v_max_f32_e32 v85, 0, v85
	v_mul_f32_e32 v84, v84, v84
	v_mul_f32_e32 v86, v86, v86
	v_mul_f32_e32 v85, v85, v85
	v_cvt_pk_bf16_f32 v82, v86, v82
	v_cvt_pk_bf16_f32 v83, v83, v84
	v_cvt_pk_bf16_f32 v84, v90, v87
	v_max_f32_e32 v74, 0, v74
	v_cvt_pk_bf16_f32 v85, v88, v85
	global_store_dwordx4 v[98:99], v[82:85], off offset:256
	s_nop 1
	v_max_f32_e32 v75, 0, v75
	v_max_f32_e32 v76, 0, v76
	v_mul_f32_e32 v84, v74, v74
	v_max_f32_e32 v74, v79, v79
	v_or_b32_e32 v82, 48, v150
	v_max_f32_e32 v74, 0, v74
	v_mul_f32_e32 v79, v75, v75
	v_max_f32_e32 v75, v80, v80
	v_mul_f32_e32 v80, v76, v76
	v_max_f32_e32 v76, v81, v81
	v_mad_i64_i32 v[82:83], s[2:3], v82, s8, v[140:141]
	v_max_f32_e32 v78, 0, v78
	v_mul_f32_e32 v74, v74, v74
	v_max_f32_e32 v75, 0, v75
	v_max_f32_e32 v76, 0, v76
	v_max_f32_e32 v77, 0, v77
	v_lshl_add_u64 v[82:83], v[82:83], 0, v[142:143]
	v_mul_f32_e32 v78, v78, v78
	v_mul_f32_e32 v75, v75, v75
	v_mul_f32_e32 v76, v76, v76
	v_mul_f32_e32 v77, v77, v77
	v_cvt_pk_bf16_f32 v74, v78, v74
	v_max_f32_e32 v66, 0, v66
	v_max_f32_e32 v67, 0, v67
	v_max_f32_e32 v68, 0, v68
	v_cvt_pk_bf16_f32 v75, v75, v76
	v_cvt_pk_bf16_f32 v76, v84, v79
	v_cvt_pk_bf16_f32 v77, v80, v77
	global_store_dwordx4 v[82:83], v[74:77], off
	s_nop 1
	v_mul_f32_e32 v74, v66, v66
	v_max_f32_e32 v66, v71, v71
	v_mul_f32_e32 v71, v67, v67
	v_max_f32_e32 v67, v72, v72
	v_mul_f32_e32 v72, v68, v68
	v_max_f32_e32 v68, v73, v73
	v_max_f32_e32 v66, 0, v66
	v_max_f32_e32 v67, 0, v67
	v_max_f32_e32 v68, 0, v68
	v_max_f32_e32 v70, 0, v70
	v_mul_f32_e32 v66, v66, v66
	v_mul_f32_e32 v67, v67, v67
	v_max_f32_e32 v69, 0, v69
	v_mul_f32_e32 v68, v68, v68
	v_mul_f32_e32 v70, v70, v70
	v_mul_f32_e32 v69, v69, v69
	v_cvt_pk_bf16_f32 v66, v70, v66
	v_cvt_pk_bf16_f32 v67, v67, v68
	v_cvt_pk_bf16_f32 v68, v74, v71
	v_max_f32_e32 v56, 0, v56
	v_cvt_pk_bf16_f32 v69, v72, v69
	global_store_dwordx4 v[82:83], v[66:69], off offset:256
	s_nop 1
	v_max_f32_e32 v57, 0, v57
	v_max_f32_e32 v58, 0, v58
	v_mul_f32_e32 v68, v56, v56
	v_max_f32_e32 v56, v61, v61
	v_add_u32_e32 v66, 0x80, v150
	v_max_f32_e32 v56, 0, v56
	v_mul_f32_e32 v61, v57, v57
	v_max_f32_e32 v57, v62, v62
	v_mul_f32_e32 v62, v58, v58
	v_max_f32_e32 v58, v63, v63
	v_mad_i64_i32 v[66:67], s[2:3], v66, s8, v[140:141]
	v_max_f32_e32 v60, 0, v60
	v_mul_f32_e32 v56, v56, v56
	v_max_f32_e32 v57, 0, v57
	v_max_f32_e32 v58, 0, v58
	v_max_f32_e32 v59, 0, v59
	v_lshl_add_u64 v[66:67], v[66:67], 0, v[142:143]
	v_mul_f32_e32 v60, v60, v60
	v_mul_f32_e32 v57, v57, v57
	v_mul_f32_e32 v58, v58, v58
	v_mul_f32_e32 v59, v59, v59
	v_cvt_pk_bf16_f32 v56, v60, v56
	v_max_f32_e32 v48, 0, v48
	v_max_f32_e32 v49, 0, v49
	v_max_f32_e32 v50, 0, v50
	v_cvt_pk_bf16_f32 v57, v57, v58
	v_cvt_pk_bf16_f32 v58, v68, v61
	v_cvt_pk_bf16_f32 v59, v62, v59
	global_store_dwordx4 v[66:67], v[56:59], off
	s_nop 1
	v_mul_f32_e32 v56, v48, v48
	v_max_f32_e32 v48, v53, v53
	v_mul_f32_e32 v53, v49, v49
	v_max_f32_e32 v49, v54, v54
	v_mul_f32_e32 v54, v50, v50
	v_max_f32_e32 v50, v55, v55
	v_max_f32_e32 v48, 0, v48
	v_max_f32_e32 v49, 0, v49
	v_max_f32_e32 v50, 0, v50
	v_max_f32_e32 v52, 0, v52
	v_mul_f32_e32 v48, v48, v48
	v_mul_f32_e32 v49, v49, v49
	v_max_f32_e32 v51, 0, v51
	v_mul_f32_e32 v50, v50, v50
	v_mul_f32_e32 v52, v52, v52
	v_mul_f32_e32 v51, v51, v51
	v_cvt_pk_bf16_f32 v48, v52, v48
; __device__ __forceinline__ unsigned cvt_pk_bf16(float lo, float hi) { unsigned r; asm volatile("v_cvt_pk_bf16_f32 %0, %1, %2" : "=v"(r) : "v"(lo), "v"(hi)); return r; }
; #define PG8_WAIT_V(n) asm volatile("s_waitcnt vmcnt(" #n ")" ::: "memory")
; #define PG8_BAR __builtin_amdgcn_s_barrier()
;     __device__ __forceinline__ void operator()(const f32x4 (&acc)[2][2][4][2], const Unit& u, int wr, int wc, int fr, int fq) const {
;         const int row0 = u.pm * BM + wr * 64 + fr, col0 = u.pn * BM + wc * 32 + 8 * fq;
; #pragma unroll
;         for (int ai = 0; ai < 2; ++ai)
; #pragma unroll
;             for (int m = 0; m < 4; ++m) { bf16_t* rowp = O + (size_t)(row0 + ai * HALF + m * 16) * LDF + col0;
; #pragma unroll
;                 for (int bj = 0; bj < 2; ++bj) { f32x4 v0 = acc[ai][bj][m][0], v1 = acc[ai][bj][m][1];
; #pragma unroll
;                     for (int j = 0; j < 4; ++j) { const float a = fmaxf(v0[j], 0.f), b = fmaxf(v1[j], 0.f); v0[j] = a * a; v1[j] = b * b; }
;                     u32x4 w; w.x = cvt_pk_bf16(v0[0], v0[1]); w.y = cvt_pk_bf16(v0[2], v0[3]); w.z = cvt_pk_bf16(v1[0], v1[1]); w.w = cvt_pk_bf16(v1[2], v1[3]);
;                     *(u32x4*)(rowp + bj * HALF) = w; } }
;     ...
;         if (!has_next) break;
; #pragma unroll
;         for (int a = 0; a < 2; ++a)
; #pragma unroll
;             for (int b = 0; b < 2; ++b)
; #pragma unroll
;                 for (int m = 0; m < 4; ++m)
; #pragma unroll
;                     for (int n = 0; n < 2; ++n) acc[a][b][m][n] = (f32x4){0.f, 0.f, 0.f, 0.f};
;         cur = nxt; cA = nA; cB = nB; ++ui;
;     }
;     PG8_WAIT_V(0);
;     if (wr == 0) PG8_BAR;
	v_cvt_pk_bf16_f32 v49, v49, v50
	v_cvt_pk_bf16_f32 v50, v56, v53
	v_max_f32_e32 v40, 0, v40
	v_cvt_pk_bf16_f32 v51, v54, v51
	global_store_dwordx4 v[66:67], v[48:51], off offset:256
	s_nop 1
	v_max_f32_e32 v41, 0, v41
	v_max_f32_e32 v42, 0, v42
	v_mul_f32_e32 v50, v40, v40
	v_max_f32_e32 v40, v45, v45
	v_add_u32_e32 v48, 0x90, v150
	v_max_f32_e32 v40, 0, v40
	v_mul_f32_e32 v45, v41, v41
	v_max_f32_e32 v41, v46, v46
	v_mul_f32_e32 v46, v42, v42
	v_max_f32_e32 v42, v47, v47
	v_mad_i64_i32 v[48:49], s[2:3], v48, s8, v[140:141]
	v_max_f32_e32 v44, 0, v44
	v_mul_f32_e32 v40, v40, v40
	v_max_f32_e32 v41, 0, v41
	v_max_f32_e32 v42, 0, v42
	v_max_f32_e32 v43, 0, v43
	v_lshl_add_u64 v[48:49], v[48:49], 0, v[142:143]
	v_mul_f32_e32 v44, v44, v44
	v_mul_f32_e32 v41, v41, v41
	v_mul_f32_e32 v42, v42, v42
	v_mul_f32_e32 v43, v43, v43
	v_cvt_pk_bf16_f32 v40, v44, v40
	v_max_f32_e32 v32, 0, v32
	v_max_f32_e32 v33, 0, v33
	v_max_f32_e32 v34, 0, v34
	v_cvt_pk_bf16_f32 v41, v41, v42
	v_cvt_pk_bf16_f32 v42, v50, v45
	v_cvt_pk_bf16_f32 v43, v46, v43
	global_store_dwordx4 v[48:49], v[40:43], off
	s_nop 1
	v_mul_f32_e32 v40, v32, v32
	v_max_f32_e32 v32, v37, v37
	v_mul_f32_e32 v37, v33, v33
	v_max_f32_e32 v33, v38, v38
	v_mul_f32_e32 v38, v34, v34
	v_max_f32_e32 v34, v39, v39
	v_max_f32_e32 v32, 0, v32
	v_max_f32_e32 v33, 0, v33
	v_max_f32_e32 v34, 0, v34
	v_max_f32_e32 v36, 0, v36
	v_mul_f32_e32 v32, v32, v32
	v_mul_f32_e32 v33, v33, v33
	v_max_f32_e32 v35, 0, v35
	v_mul_f32_e32 v34, v34, v34
	v_mul_f32_e32 v36, v36, v36
	v_mul_f32_e32 v35, v35, v35
	v_cvt_pk_bf16_f32 v32, v36, v32
	v_cvt_pk_bf16_f32 v33, v33, v34
	v_cvt_pk_bf16_f32 v34, v40, v37
	v_max_f32_e32 v24, 0, v24
	v_cvt_pk_bf16_f32 v35, v38, v35
	global_store_dwordx4 v[48:49], v[32:35], off offset:256
	s_nop 1
	v_max_f32_e32 v25, 0, v25
	v_max_f32_e32 v26, 0, v26
	v_mul_f32_e32 v34, v24, v24
	v_max_f32_e32 v24, v29, v29
	v_add_u32_e32 v32, 0xa0, v150
	v_max_f32_e32 v24, 0, v24
	v_mul_f32_e32 v29, v25, v25
	v_max_f32_e32 v25, v30, v30
	v_mul_f32_e32 v30, v26, v26
	v_max_f32_e32 v26, v31, v31
	v_mad_i64_i32 v[32:33], s[2:3], v32, s8, v[140:141]
	v_max_f32_e32 v28, 0, v28
	v_mul_f32_e32 v24, v24, v24
	v_max_f32_e32 v25, 0, v25
	v_max_f32_e32 v26, 0, v26
	v_max_f32_e32 v27, 0, v27
	v_lshl_add_u64 v[32:33], v[32:33], 0, v[142:143]
	v_mul_f32_e32 v28, v28, v28
	v_mul_f32_e32 v25, v25, v25
	v_mul_f32_e32 v26, v26, v26
	v_mul_f32_e32 v27, v27, v27
	v_cvt_pk_bf16_f32 v24, v28, v24
	v_max_f32_e32 v16, 0, v16
	v_max_f32_e32 v17, 0, v17
	v_max_f32_e32 v18, 0, v18
	v_cvt_pk_bf16_f32 v25, v25, v26
	v_cvt_pk_bf16_f32 v26, v34, v29
	v_cvt_pk_bf16_f32 v27, v30, v27
	global_store_dwordx4 v[32:33], v[24:27], off
	s_nop 1
	v_mul_f32_e32 v24, v16, v16
	v_max_f32_e32 v16, v21, v21
	v_mul_f32_e32 v21, v17, v17
	v_max_f32_e32 v17, v22, v22
	v_mul_f32_e32 v22, v18, v18
	v_max_f32_e32 v18, v23, v23
	v_max_f32_e32 v16, 0, v16
	v_max_f32_e32 v17, 0, v17
	v_max_f32_e32 v18, 0, v18
	v_max_f32_e32 v20, 0, v20
	v_mul_f32_e32 v16, v16, v16
	v_mul_f32_e32 v17, v17, v17
	v_max_f32_e32 v19, 0, v19
	v_mul_f32_e32 v18, v18, v18
	v_mul_f32_e32 v20, v20, v20
	v_mul_f32_e32 v19, v19, v19
	v_cvt_pk_bf16_f32 v16, v20, v16
	v_cvt_pk_bf16_f32 v17, v17, v18
	v_cvt_pk_bf16_f32 v18, v24, v21
	v_max_f32_e32 v8, 0, v8
	v_cvt_pk_bf16_f32 v19, v22, v19
	global_store_dwordx4 v[32:33], v[16:19], off offset:256
	s_nop 1
	v_max_f32_e32 v9, 0, v9
	v_max_f32_e32 v10, 0, v10
	v_mul_f32_e32 v18, v8, v8
	v_max_f32_e32 v8, v13, v13
	v_add_u32_e32 v16, 0xb0, v150
	v_max_f32_e32 v8, 0, v8
	v_mul_f32_e32 v13, v9, v9
	v_max_f32_e32 v9, v14, v14
	v_mul_f32_e32 v14, v10, v10
	v_max_f32_e32 v10, v15, v15
	v_mad_i64_i32 v[16:17], s[2:3], v16, s8, v[140:141]
	v_max_f32_e32 v12, 0, v12
	v_mul_f32_e32 v8, v8, v8
	v_max_f32_e32 v9, 0, v9
	v_max_f32_e32 v10, 0, v10
	v_max_f32_e32 v11, 0, v11
	v_lshl_add_u64 v[16:17], v[16:17], 0, v[142:143]
	v_mul_f32_e32 v12, v12, v12
	v_mul_f32_e32 v9, v9, v9
	v_mul_f32_e32 v10, v10, v10
	v_mul_f32_e32 v11, v11, v11
	v_cvt_pk_bf16_f32 v8, v12, v8
	v_max_f32_e32 v0, 0, v0
	v_max_f32_e32 v1, 0, v1
	v_max_f32_e32 v2, 0, v2
	v_cvt_pk_bf16_f32 v9, v9, v10
	v_cvt_pk_bf16_f32 v10, v18, v13
	v_cvt_pk_bf16_f32 v11, v14, v11
	global_store_dwordx4 v[16:17], v[8:11], off
	s_nop 1
	v_mul_f32_e32 v8, v0, v0
	v_max_f32_e32 v0, v5, v5
	v_mul_f32_e32 v5, v1, v1
	v_max_f32_e32 v1, v6, v6
	v_mul_f32_e32 v6, v2, v2
	v_max_f32_e32 v2, v7, v7
	v_max_f32_e32 v0, 0, v0
	v_max_f32_e32 v1, 0, v1
	v_max_f32_e32 v2, 0, v2
	v_max_f32_e32 v3, 0, v3
	v_max_f32_e32 v4, 0, v4
	v_mul_f32_e32 v0, v0, v0
	v_mul_f32_e32 v1, v1, v1
	v_mul_f32_e32 v2, v2, v2
	v_mul_f32_e32 v3, v3, v3
	s_and_b64 vcc, exec, s[4:5]
	s_mov_b32 s38, s34
	s_mov_b32 s37, s36
	s_mov_b32 s40, s39
	s_mov_b64 s[10:11], s[18:19]
	s_mov_b64 s[8:9], s[6:7]
	s_mov_b32 s18, s33
	v_readlane_b32 s35, v251, 41
	v_mul_f32_e32 v4, v4, v4
	v_cvt_pk_bf16_f32 v0, v4, v0
	v_cvt_pk_bf16_f32 v1, v1, v2
	v_cvt_pk_bf16_f32 v2, v8, v5
	v_cvt_pk_bf16_f32 v3, v6, v3
	global_store_dwordx4 v[16:17], v[0:3], off offset:256
	s_nop 1
	s_cbranch_vccz .LBB0_96
	s_waitcnt vmcnt(0)
	v_readlane_b32 s40, v251, 24
	v_readlane_b32 s28, v252, 58
	s_cmpk_gt_u32 s15, 0xff
	s_movk_i32 s27, 0x1000
	v_readlane_b32 s41, v251, 25
	v_readlane_b32 s29, v252, 59
	s_cbranch_scc1 .LBB0_124
	s_barrier

; #define PG8_STAGE(bufoff, gbase, voff) do { _Pragma("unroll") for (int _i = 0; _i < 2; ++_i) \
;         __builtin_amdgcn_global_load_lds((const unsigned*)((const char*)(gbase) + (voff)[_i]), (LAS unsigned*)(lds + (bufoff) + ldsw + _i * 8192), 16, 0, 0); } while (0)
; #define PG8_LDA(dst, b, h) do { _Pragma("unroll") for (int m = 0; m < 4; ++m) _Pragma("unroll") for (int k = 0; k < 2; ++k) dst[m][k] = *(const LAS bf16x8*)(lds + PG8_SA(b, h) + aoff + m * 2048 + k * 1024); } while (0)
; #define PG8_LDB(dst, b, h) do { _Pragma("unroll") for (int n = 0; n < 2; ++n) _Pragma("unroll") for (int k = 0; k < 2; ++k) dst[n][k] = *(const LAS bf16x8*)(lds + PG8_SB(b, h) + boff + n * 2048 + k * 1024); } while (0)
; #define PG8_WAIT_L(n) asm volatile("s_waitcnt lgkmcnt(" #n ")" ::: "memory")
; #define PG8_BAR __builtin_amdgcn_s_barrier()
; #define PG8_SCHED __builtin_amdgcn_sched_barrier(0)
;     ...
;         for (int t = 0; t < nt; t += 2) {
;             const bool last = (t == nt - 2);
;             if (last && has_next && gate != nullptr && nxt.pm >= 32) {
;                 if (tid < 64) { unsigned sp = 0;
;                     while ((unsigned)__builtin_amdgcn_readfirstlane(__hip_atomic_load(gate, __ATOMIC_RELAXED, __HIP_MEMORY_SCOPE_AGENT)) < gate_need) { __builtin_amdgcn_s_sleep(2); if (++sp > (1u << 20)) break; }
;                     __builtin_amdgcn_fence(__ATOMIC_ACQUIRE, "agent"); asm volatile("s_waitcnt vmcnt(0)" ::: "memory"); }
;                 asm volatile("" ::: "memory"); PG8_BAR; asm volatile("" ::: "memory");
;             }
;             const char* a1 = cA + (size_t)(t + 1) * kstep;
;             const char* a2 = last ? nA : cA + (size_t)(t + 2) * kstep; const char* b2 = last ? nB : cB + (size_t)(t + 2) * kstep;
;             const char* a3 = a2 + kstep; const char* b3 = b2 + kstep;
;             PG8_LDB(B0, 0, 0); PG8_SCHED; PG8_LDA(At, 0, 0); PG8_STAGE(PG8_SA(1, 1), a1 + hstep, voffA);
;             PG8_WAIT_L(8); PG8_BAR; PG8_WAIT_L(0); PG8_MMA(0, 0, At, B0); PG8_BAR; PG8_SCHED;
;             PG8_LDB(B1, 0, 1); PG8_STAGE(PG8_SB(0, 0), b2, voffB);
;             PG8_BAR; PG8_WAIT_L(0); PG8_MMA(0, 1, At, B1); PG8_BAR;
;             PG8_LDA(At, 0, 1); PG8_STAGE(PG8_SA(0, 0), a2, voffA);
;             PG8_BAR; PG8_WAIT_L(0); PG8_MMA(1, 0, At, B0); PG8_BAR; PG8_SCHED;
.LBB0_146:
	s_add_u32 s2, s8, 0xe515c080
	s_addc_u32 s3, s9, -1
	s_cmp_lg_u32 s27, 28
	s_cselect_b32 s10, s2, 0
	s_cselect_b32 s11, s3, 0
	s_add_u32 s2, s6, s10
	s_addc_u32 s3, s7, s11
	s_add_i32 s28, 0, 0x10000
	v_add_u32_e32 v156, s28, v142
	ds_read_b128 v[144:147], v156
	ds_read_b128 v[148:151], v156 offset:1024
	ds_read_b128 v[152:155], v156 offset:2048
	ds_read_b128 v[156:159], v156 offset:3072
	s_add_u32 s10, s4, s10
	s_addc_u32 s11, s5, s11
	v_lshl_add_u64 v[192:193], v[136:137], 0, s[8:9]
	s_add_i32 m0, s20, 0xc000
	ds_read_b128 v[160:163], v143
	ds_read_b128 v[164:167], v143 offset:1024
	ds_read_b128 v[168:171], v143 offset:2048
	ds_read_b128 v[172:175], v143 offset:3072
	ds_read_b128 v[176:179], v143 offset:4096
	ds_read_b128 v[180:183], v143 offset:5120
	ds_read_b128 v[184:187], v143 offset:6144
	ds_read_b128 v[188:191], v143 offset:7168
	global_load_lds_dwordx4 v[192:193], off
	v_lshl_add_u64 v[192:193], v[138:139], 0, s[8:9]
	s_add_i32 m0, s20, 0xe000
	s_nop 0
	global_load_lds_dwordx4 v[192:193], off
	s_waitcnt lgkmcnt(8)
	s_barrier
	s_waitcnt lgkmcnt(0)
	s_waitcnt lgkmcnt(0)
	v_mfma_f32_16x16x32_bf16 v[126:129], v[144:147], v[160:163], v[126:129]
	v_mfma_f32_16x16x32_bf16 v[122:125], v[152:155], v[160:163], v[122:125]
	v_mfma_f32_16x16x32_bf16 v[110:113], v[144:147], v[168:171], v[110:113]
	v_mfma_f32_16x16x32_bf16 v[106:109], v[152:155], v[168:171], v[106:109]
	v_mfma_f32_16x16x32_bf16 v[94:97], v[144:147], v[176:179], v[94:97]
	v_mfma_f32_16x16x32_bf16 v[90:93], v[152:155], v[176:179], v[90:93]
	v_mfma_f32_16x16x32_bf16 v[78:81], v[144:147], v[184:187], v[78:81]
	v_mfma_f32_16x16x32_bf16 v[74:77], v[152:155], v[184:187], v[74:77]
	v_mfma_f32_16x16x32_bf16 v[126:129], v[148:151], v[164:167], v[126:129]
	v_mfma_f32_16x16x32_bf16 v[122:125], v[156:159], v[164:167], v[122:125]
	v_mfma_f32_16x16x32_bf16 v[110:113], v[148:151], v[172:175], v[110:113]
	v_mfma_f32_16x16x32_bf16 v[106:109], v[156:159], v[172:175], v[106:109]
	v_mfma_f32_16x16x32_bf16 v[94:97], v[148:151], v[180:183], v[94:97]
	v_mfma_f32_16x16x32_bf16 v[90:93], v[156:159], v[180:183], v[90:93]
	v_mfma_f32_16x16x32_bf16 v[78:81], v[148:151], v[188:191], v[78:81]
	v_mfma_f32_16x16x32_bf16 v[74:77], v[156:159], v[188:191], v[74:77]
	s_barrier
	s_add_i32 s31, 0, 0x14000
	s_add_i32 s28, s28, s15
	v_add_u32_e32 v208, s31, v142
	v_lshl_add_u64 v[228:229], s[10:11], 0, v[64:65]
	s_mov_b32 m0, s28
	ds_read_b128 v[192:195], v208
	ds_read_b128 v[196:199], v208 offset:1024
	ds_read_b128 v[220:223], v208 offset:2048
	ds_read_b128 v[224:227], v208 offset:3072
	global_load_lds_dwordx4 v[228:229], off
	v_lshl_add_u64 v[230:231], s[10:11], 0, v[130:131]
	s_add_i32 m0, s28, 0x2000
	s_nop 0
	global_load_lds_dwordx4 v[230:231], off
	s_barrier
	s_waitcnt lgkmcnt(0)
	s_waitcnt lgkmcnt(0)
	v_mfma_f32_16x16x32_bf16 v[118:121], v[192:195], v[160:163], v[118:121]
	v_mfma_f32_16x16x32_bf16 v[114:117], v[220:223], v[160:163], v[114:117]
	v_mfma_f32_16x16x32_bf16 v[102:105], v[192:195], v[168:171], v[102:105]
	v_mfma_f32_16x16x32_bf16 v[98:101], v[220:223], v[168:171], v[98:101]
	v_mfma_f32_16x16x32_bf16 v[86:89], v[192:195], v[176:179], v[86:89]
	v_mfma_f32_16x16x32_bf16 v[82:85], v[220:223], v[176:179], v[82:85]
	v_mfma_f32_16x16x32_bf16 v[70:73], v[192:195], v[184:187], v[70:73]
	v_mfma_f32_16x16x32_bf16 v[66:69], v[220:223], v[184:187], v[66:69]
	v_mfma_f32_16x16x32_bf16 v[118:121], v[196:199], v[164:167], v[118:121]
	v_mfma_f32_16x16x32_bf16 v[114:117], v[224:227], v[164:167], v[114:117]
	v_mfma_f32_16x16x32_bf16 v[102:105], v[196:199], v[172:175], v[102:105]
	v_mfma_f32_16x16x32_bf16 v[98:101], v[224:227], v[172:175], v[98:101]
	v_mfma_f32_16x16x32_bf16 v[86:89], v[196:199], v[180:183], v[86:89]
	v_mfma_f32_16x16x32_bf16 v[82:85], v[224:227], v[180:183], v[82:85]
	v_mfma_f32_16x16x32_bf16 v[70:73], v[196:199], v[188:191], v[70:73]
	v_mfma_f32_16x16x32_bf16 v[66:69], v[224:227], v[188:191], v[66:69]
	s_mov_b32 m0, s20
	v_lshl_add_u64 v[232:233], s[2:3], 0, v[134:135]
	s_barrier
	ds_read_b128 v[160:163], v143 offset:16384
	ds_read_b128 v[164:167], v143 offset:17408
	ds_read_b128 v[168:171], v143 offset:18432
	ds_read_b128 v[172:175], v143 offset:19456
	ds_read_b128 v[176:179], v143 offset:20480
	ds_read_b128 v[180:183], v143 offset:21504
	ds_read_b128 v[184:187], v143 offset:22528
	ds_read_b128 v[188:191], v143 offset:23552
	global_load_lds_dwordx4 v[232:233], off
	v_lshl_add_u64 v[234:235], s[2:3], 0, v[132:133]
	s_mov_b32 m0, s21
	s_nop 0
	global_load_lds_dwordx4 v[234:235], off
	s_barrier
	s_waitcnt lgkmcnt(0)
	s_waitcnt lgkmcnt(0)
	v_mfma_f32_16x16x32_bf16 v[60:63], v[144:147], v[160:163], v[60:63]
	v_mfma_f32_16x16x32_bf16 v[56:59], v[152:155], v[160:163], v[56:59]
	v_mfma_f32_16x16x32_bf16 v[44:47], v[144:147], v[168:171], v[44:47]
	v_mfma_f32_16x16x32_bf16 v[40:43], v[152:155], v[168:171], v[40:43]
	v_mfma_f32_16x16x32_bf16 v[28:31], v[144:147], v[176:179], v[28:31]
	v_mfma_f32_16x16x32_bf16 v[24:27], v[152:155], v[176:179], v[24:27]
	v_mfma_f32_16x16x32_bf16 v[12:15], v[144:147], v[184:187], v[12:15]
	v_mfma_f32_16x16x32_bf16 v[8:11], v[152:155], v[184:187], v[8:11]
	v_mfma_f32_16x16x32_bf16 v[60:63], v[148:151], v[164:167], v[60:63]
	v_mfma_f32_16x16x32_bf16 v[56:59], v[156:159], v[164:167], v[56:59]
	v_mfma_f32_16x16x32_bf16 v[44:47], v[148:151], v[172:175], v[44:47]
	v_mfma_f32_16x16x32_bf16 v[40:43], v[156:159], v[172:175], v[40:43]
	v_mfma_f32_16x16x32_bf16 v[28:31], v[148:151], v[180:183], v[28:31]
	v_mfma_f32_16x16x32_bf16 v[24:27], v[156:159], v[180:183], v[24:27]
	v_mfma_f32_16x16x32_bf16 v[12:15], v[148:151], v[188:191], v[12:15]
	v_mfma_f32_16x16x32_bf16 v[8:11], v[156:159], v[188:191], v[8:11]
	s_barrier
; #define PG8_STAGE(bufoff, gbase, voff) do { _Pragma("unroll") for (int _i = 0; _i < 2; ++_i) \
;         __builtin_amdgcn_global_load_lds((const unsigned*)((const char*)(gbase) + (voff)[_i]), (LAS unsigned*)(lds + (bufoff) + ldsw + _i * 8192), 16, 0, 0); } while (0)
; #define PG8_LDA(dst, b, h) do { _Pragma("unroll") for (int m = 0; m < 4; ++m) _Pragma("unroll") for (int k = 0; k < 2; ++k) dst[m][k] = *(const LAS bf16x8*)(lds + PG8_SA(b, h) + aoff + m * 2048 + k * 1024); } while (0)
; #define PG8_LDB(dst, b, h) do { _Pragma("unroll") for (int n = 0; n < 2; ++n) _Pragma("unroll") for (int k = 0; k < 2; ++k) dst[n][k] = *(const LAS bf16x8*)(lds + PG8_SB(b, h) + boff + n * 2048 + k * 1024); } while (0)
; #define PG8_MMA(ai, bj, At, Bt) do { __builtin_amdgcn_s_setprio(1); _Pragma("unroll") for (int m = 0; m < 4; ++m) _Pragma("unroll") for (int n = 0; n < 2; ++n) _Pragma("unroll") for (int k = 0; k < 2; ++k) \
;         acc[ai][bj][m][n] = __builtin_amdgcn_mfma_f32_16x16x32_bf16(Bt[n][k], At[m][k], acc[ai][bj][m][n], 0, 0, 0); __builtin_amdgcn_s_setprio(0); } while (0)
; #define PG8_WAIT_V(n) asm volatile("s_waitcnt vmcnt(" #n ")" ::: "memory")
; #define PG8_WAIT_L(n) asm volatile("s_waitcnt lgkmcnt(" #n ")" ::: "memory")
; #define PG8_BAR __builtin_amdgcn_s_barrier()
; #define PG8_SCHED __builtin_amdgcn_sched_barrier(0)
;     ...
;             PG8_BAR; PG8_WAIT_L(0); PG8_MMA(1, 0, At, B0); PG8_BAR; PG8_SCHED;
;             PG8_STAGE(PG8_SB(0, 1), b2 + hstep, voffB);
;             PG8_WAIT_V(6); PG8_BAR; PG8_MMA(1, 1, At, B1); PG8_BAR;
;             PG8_LDB(B0, 1, 0); PG8_SCHED; PG8_LDA(At, 1, 0); PG8_STAGE(PG8_SA(0, 1), a2 + hstep, voffA);
;             PG8_WAIT_L(8); PG8_BAR; PG8_WAIT_L(0); PG8_MMA(0, 0, At, B0); PG8_BAR; PG8_SCHED;
;             PG8_LDB(B1, 1, 1); PG8_STAGE(PG8_SB(1, 0), b3, voffB);
;             PG8_BAR; PG8_WAIT_L(0); PG8_MMA(0, 1, At, B1); PG8_BAR;
;             PG8_LDA(At, 1, 1); PG8_STAGE(PG8_SA(1, 0), a3, voffA);
;             PG8_BAR; PG8_WAIT_L(0); PG8_MMA(1, 0, At, B0); PG8_BAR; PG8_SCHED;
	s_add_u32 s28, s10, 0x84000
	s_addc_u32 s29, s11, 0
	s_add_i32 s31, s31, s15
	v_lshl_add_u64 v[144:145], s[28:29], 0, v[64:65]
	s_mov_b32 m0, s31
	s_nop 0
	global_load_lds_dwordx4 v[144:145], off
	v_lshl_add_u64 v[144:145], s[28:29], 0, v[130:131]
	s_add_i32 m0, s31, 0x2000
	s_nop 0
	global_load_lds_dwordx4 v[144:145], off
	s_waitcnt vmcnt(6)
	s_barrier
	v_mfma_f32_16x16x32_bf16 v[52:55], v[192:195], v[160:163], v[52:55]
	v_mfma_f32_16x16x32_bf16 v[48:51], v[220:223], v[160:163], v[48:51]
	v_mfma_f32_16x16x32_bf16 v[36:39], v[192:195], v[168:171], v[36:39]
	v_mfma_f32_16x16x32_bf16 v[32:35], v[220:223], v[168:171], v[32:35]
	v_mfma_f32_16x16x32_bf16 v[20:23], v[192:195], v[176:179], v[20:23]
	v_mfma_f32_16x16x32_bf16 v[16:19], v[220:223], v[176:179], v[16:19]
	v_mfma_f32_16x16x32_bf16 v[4:7], v[192:195], v[184:187], v[4:7]
	v_mfma_f32_16x16x32_bf16 v[0:3], v[220:223], v[184:187], v[0:3]
	v_mfma_f32_16x16x32_bf16 v[52:55], v[196:199], v[164:167], v[52:55]
	v_mfma_f32_16x16x32_bf16 v[48:51], v[224:227], v[164:167], v[48:51]
	v_mfma_f32_16x16x32_bf16 v[36:39], v[196:199], v[172:175], v[36:39]
	v_mfma_f32_16x16x32_bf16 v[32:35], v[224:227], v[172:175], v[32:35]
	v_mfma_f32_16x16x32_bf16 v[20:23], v[196:199], v[180:183], v[20:23]
	v_mfma_f32_16x16x32_bf16 v[16:19], v[224:227], v[180:183], v[16:19]
	v_mfma_f32_16x16x32_bf16 v[4:7], v[196:199], v[188:191], v[4:7]
	v_mfma_f32_16x16x32_bf16 v[0:3], v[224:227], v[188:191], v[0:3]
	s_add_i32 s28, 0, 0x18000
	v_add_u32_e32 v156, s28, v142
	s_barrier
	ds_read_b128 v[144:147], v156
	ds_read_b128 v[148:151], v156 offset:1024
	ds_read_b128 v[152:155], v156 offset:2048
	ds_read_b128 v[156:159], v156 offset:3072
	s_add_u32 s2, s2, 0x84000
	s_addc_u32 s3, s3, 0
	s_mov_b32 m0, s22
	v_lshl_add_u64 v[192:193], s[2:3], 0, v[134:135]
	ds_read_b128 v[160:163], v143 offset:32768
	ds_read_b128 v[164:167], v143 offset:33792
	ds_read_b128 v[168:171], v143 offset:34816
	ds_read_b128 v[172:175], v143 offset:35840
	ds_read_b128 v[176:179], v143 offset:36864
	ds_read_b128 v[180:183], v143 offset:37888
	ds_read_b128 v[184:187], v143 offset:38912
	ds_read_b128 v[188:191], v143 offset:39936
	global_load_lds_dwordx4 v[192:193], off
	v_lshl_add_u64 v[192:193], s[2:3], 0, v[132:133]
	s_mov_b32 m0, s23
	s_nop 0
	global_load_lds_dwordx4 v[192:193], off
	s_waitcnt lgkmcnt(8)
	s_barrier
	s_waitcnt lgkmcnt(0)
	s_waitcnt lgkmcnt(0)
	v_mfma_f32_16x16x32_bf16 v[126:129], v[144:147], v[160:163], v[126:129]
	v_mfma_f32_16x16x32_bf16 v[122:125], v[152:155], v[160:163], v[122:125]
	v_mfma_f32_16x16x32_bf16 v[110:113], v[144:147], v[168:171], v[110:113]
	v_mfma_f32_16x16x32_bf16 v[106:109], v[152:155], v[168:171], v[106:109]
	v_mfma_f32_16x16x32_bf16 v[94:97], v[144:147], v[176:179], v[94:97]
	v_mfma_f32_16x16x32_bf16 v[90:93], v[152:155], v[176:179], v[90:93]
	v_mfma_f32_16x16x32_bf16 v[78:81], v[144:147], v[184:187], v[78:81]
	v_mfma_f32_16x16x32_bf16 v[74:77], v[152:155], v[184:187], v[74:77]
	v_mfma_f32_16x16x32_bf16 v[126:129], v[148:151], v[164:167], v[126:129]
	v_mfma_f32_16x16x32_bf16 v[122:125], v[156:159], v[164:167], v[122:125]
	v_mfma_f32_16x16x32_bf16 v[110:113], v[148:151], v[172:175], v[110:113]
	v_mfma_f32_16x16x32_bf16 v[106:109], v[156:159], v[172:175], v[106:109]
	v_mfma_f32_16x16x32_bf16 v[94:97], v[148:151], v[180:183], v[94:97]
	v_mfma_f32_16x16x32_bf16 v[90:93], v[156:159], v[180:183], v[90:93]
	v_mfma_f32_16x16x32_bf16 v[78:81], v[148:151], v[188:191], v[78:81]
	v_mfma_f32_16x16x32_bf16 v[74:77], v[156:159], v[188:191], v[74:77]
	s_barrier
	s_add_i32 s29, 0, 0x1c000
	s_add_i32 s2, s28, s15
	v_add_u32_e32 v208, s29, v142
	v_lshl_add_u64 v[228:229], v[228:229], 0, s[16:17]
	s_mov_b32 m0, s2
	ds_read_b128 v[192:195], v208
	ds_read_b128 v[196:199], v208 offset:1024
	ds_read_b128 v[220:223], v208 offset:2048
	ds_read_b128 v[224:227], v208 offset:3072
	global_load_lds_dwordx4 v[228:229], off
	v_lshl_add_u64 v[228:229], v[230:231], 0, s[16:17]
	s_add_i32 m0, s2, 0x2000
	s_nop 0
	global_load_lds_dwordx4 v[228:229], off
	s_barrier
	s_waitcnt lgkmcnt(0)
	s_waitcnt lgkmcnt(0)
	v_mfma_f32_16x16x32_bf16 v[118:121], v[192:195], v[160:163], v[118:121]
	v_mfma_f32_16x16x32_bf16 v[114:117], v[220:223], v[160:163], v[114:117]
	v_mfma_f32_16x16x32_bf16 v[102:105], v[192:195], v[168:171], v[102:105]
	v_mfma_f32_16x16x32_bf16 v[98:101], v[220:223], v[168:171], v[98:101]
	v_mfma_f32_16x16x32_bf16 v[86:89], v[192:195], v[176:179], v[86:89]
	v_mfma_f32_16x16x32_bf16 v[82:85], v[220:223], v[176:179], v[82:85]
	v_mfma_f32_16x16x32_bf16 v[70:73], v[192:195], v[184:187], v[70:73]
	v_mfma_f32_16x16x32_bf16 v[66:69], v[220:223], v[184:187], v[66:69]
	v_mfma_f32_16x16x32_bf16 v[118:121], v[196:199], v[164:167], v[118:121]
	v_mfma_f32_16x16x32_bf16 v[114:117], v[224:227], v[164:167], v[114:117]
	v_mfma_f32_16x16x32_bf16 v[102:105], v[196:199], v[172:175], v[102:105]
	v_mfma_f32_16x16x32_bf16 v[98:101], v[224:227], v[172:175], v[98:101]
	v_mfma_f32_16x16x32_bf16 v[86:89], v[196:199], v[180:183], v[86:89]
	v_mfma_f32_16x16x32_bf16 v[82:85], v[224:227], v[180:183], v[82:85]
	v_mfma_f32_16x16x32_bf16 v[70:73], v[196:199], v[188:191], v[70:73]
	v_mfma_f32_16x16x32_bf16 v[66:69], v[224:227], v[188:191], v[66:69]
	s_mov_b32 m0, s25
	v_lshl_add_u64 v[228:229], v[232:233], 0, s[16:17]
	s_barrier
	ds_read_b128 v[160:163], v143 offset:49152
	ds_read_b128 v[164:167], v143 offset:50176
	ds_read_b128 v[168:171], v143 offset:51200
	ds_read_b128 v[172:175], v143 offset:52224
	ds_read_b128 v[176:179], v143 offset:53248
	ds_read_b128 v[180:183], v143 offset:54272
	ds_read_b128 v[184:187], v143 offset:55296
	ds_read_b128 v[188:191], v143 offset:56320
	global_load_lds_dwordx4 v[228:229], off
	v_lshl_add_u64 v[228:229], v[234:235], 0, s[16:17]
	s_mov_b32 m0, s26
	s_nop 0
	global_load_lds_dwordx4 v[228:229], off
	s_barrier
; __device__ __forceinline__ unsigned cvt_pk_bf16(float lo, float hi) { unsigned r; asm volatile("v_cvt_pk_bf16_f32 %0, %1, %2" : "=v"(r) : "v"(lo), "v"(hi)); return r; }
; #define PG8_STAGE(bufoff, gbase, voff) do { _Pragma("unroll") for (int _i = 0; _i < 2; ++_i) \
;         __builtin_amdgcn_global_load_lds((const unsigned*)((const char*)(gbase) + (voff)[_i]), (LAS unsigned*)(lds + (bufoff) + ldsw + _i * 8192), 16, 0, 0); } while (0)
; #define PG8_MMA(ai, bj, At, Bt) do { __builtin_amdgcn_s_setprio(1); _Pragma("unroll") for (int m = 0; m < 4; ++m) _Pragma("unroll") for (int n = 0; n < 2; ++n) _Pragma("unroll") for (int k = 0; k < 2; ++k) \
;         acc[ai][bj][m][n] = __builtin_amdgcn_mfma_f32_16x16x32_bf16(Bt[n][k], At[m][k], acc[ai][bj][m][n], 0, 0, 0); __builtin_amdgcn_s_setprio(0); } while (0)
; #define PG8_WAIT_V(n) asm volatile("s_waitcnt vmcnt(" #n ")" ::: "memory")
; #define PG8_WAIT_L(n) asm volatile("s_waitcnt lgkmcnt(" #n ")" ::: "memory")
; #define PG8_BAR __builtin_amdgcn_s_barrier()
; #define PG8_SCHED __builtin_amdgcn_sched_barrier(0)
;     __device__ __forceinline__ void operator()(const f32x4 (&acc)[2][2][4][2], const Unit& u, int wr, int wc, int fr, int fq) const {
;         const int row0 = u.pm * BM + wr * 64 + fr, col0 = u.pn * BM + wc * 32 + 8 * fq;
; #pragma unroll
;         for (int ai = 0; ai < 2; ++ai)
; #pragma unroll
;             for (int m = 0; m < 4; ++m) { bf16_t* rowp = O + (size_t)(row0 + ai * HALF + m * 16) * LDF + col0;
; #pragma unroll
;                 for (int bj = 0; bj < 2; ++bj) { f32x4 v0 = acc[ai][bj][m][0], v1 = acc[ai][bj][m][1];
; #pragma unroll
;                     for (int j = 0; j < 4; ++j) { const float a = fmaxf(v0[j], 0.f), b = fmaxf(v1[j], 0.f); v0[j] = a * a; v1[j] = b * b; }
;                     u32x4 w; w.x = cvt_pk_bf16(v0[0], v0[1]); w.y = cvt_pk_bf16(v0[2], v0[3]); w.z = cvt_pk_bf16(v1[0], v1[1]); w.w = cvt_pk_bf16(v1[2], v1[3]);
;                     *(u32x4*)(rowp + bj * HALF) = w; } }
;     ...
;             PG8_BAR; PG8_WAIT_L(0); PG8_MMA(1, 0, At, B0); PG8_BAR; PG8_SCHED;
;             PG8_STAGE(PG8_SB(1, 1), b3 + hstep, voffB);
;             PG8_WAIT_V(6); PG8_BAR; PG8_MMA(1, 1, At, B1); PG8_BAR;
;         }
	s_waitcnt lgkmcnt(0)
	s_waitcnt lgkmcnt(0)
	v_mfma_f32_16x16x32_bf16 v[60:63], v[144:147], v[160:163], v[60:63]
	v_mfma_f32_16x16x32_bf16 v[56:59], v[152:155], v[160:163], v[56:59]
	v_mfma_f32_16x16x32_bf16 v[44:47], v[144:147], v[168:171], v[44:47]
	v_mfma_f32_16x16x32_bf16 v[40:43], v[152:155], v[168:171], v[40:43]
	v_mfma_f32_16x16x32_bf16 v[28:31], v[144:147], v[176:179], v[28:31]
	v_mfma_f32_16x16x32_bf16 v[24:27], v[152:155], v[176:179], v[24:27]
	v_mfma_f32_16x16x32_bf16 v[12:15], v[144:147], v[184:187], v[12:15]
	v_mfma_f32_16x16x32_bf16 v[8:11], v[152:155], v[184:187], v[8:11]
	v_mfma_f32_16x16x32_bf16 v[60:63], v[148:151], v[164:167], v[60:63]
	v_mfma_f32_16x16x32_bf16 v[56:59], v[156:159], v[164:167], v[56:59]
	v_mfma_f32_16x16x32_bf16 v[44:47], v[148:151], v[172:175], v[44:47]
	v_mfma_f32_16x16x32_bf16 v[40:43], v[156:159], v[172:175], v[40:43]
	v_mfma_f32_16x16x32_bf16 v[28:31], v[148:151], v[180:183], v[28:31]
	v_mfma_f32_16x16x32_bf16 v[24:27], v[156:159], v[180:183], v[24:27]
	v_mfma_f32_16x16x32_bf16 v[12:15], v[148:151], v[188:191], v[12:15]
	v_mfma_f32_16x16x32_bf16 v[8:11], v[156:159], v[188:191], v[8:11]
	s_barrier
	s_add_u32 s2, s10, 0x84080
	s_addc_u32 s3, s11, 0
	s_add_i32 s10, s29, s15
	v_lshl_add_u64 v[144:145], s[2:3], 0, v[64:65]
	s_mov_b32 m0, s10
	s_nop 0
	global_load_lds_dwordx4 v[144:145], off
	v_lshl_add_u64 v[144:145], s[2:3], 0, v[130:131]
	s_add_i32 m0, s10, 0x2000
	s_nop 0
	global_load_lds_dwordx4 v[144:145], off
	s_waitcnt vmcnt(6)
	s_barrier
	v_mfma_f32_16x16x32_bf16 v[52:55], v[192:195], v[160:163], v[52:55]
	v_mfma_f32_16x16x32_bf16 v[48:51], v[220:223], v[160:163], v[48:51]
	v_mfma_f32_16x16x32_bf16 v[36:39], v[192:195], v[168:171], v[36:39]
	v_mfma_f32_16x16x32_bf16 v[32:35], v[220:223], v[168:171], v[32:35]
	v_mfma_f32_16x16x32_bf16 v[20:23], v[192:195], v[176:179], v[20:23]
	v_mfma_f32_16x16x32_bf16 v[16:19], v[220:223], v[176:179], v[16:19]
	v_mfma_f32_16x16x32_bf16 v[4:7], v[192:195], v[184:187], v[4:7]
	v_mfma_f32_16x16x32_bf16 v[0:3], v[220:223], v[184:187], v[0:3]
	v_mfma_f32_16x16x32_bf16 v[52:55], v[196:199], v[164:167], v[52:55]
	v_mfma_f32_16x16x32_bf16 v[48:51], v[224:227], v[164:167], v[48:51]
	v_mfma_f32_16x16x32_bf16 v[36:39], v[196:199], v[172:175], v[36:39]
	v_mfma_f32_16x16x32_bf16 v[32:35], v[224:227], v[172:175], v[32:35]
	v_mfma_f32_16x16x32_bf16 v[20:23], v[196:199], v[180:183], v[20:23]
	v_mfma_f32_16x16x32_bf16 v[16:19], v[224:227], v[180:183], v[16:19]
	v_mfma_f32_16x16x32_bf16 v[4:7], v[196:199], v[188:191], v[4:7]
	v_mfma_f32_16x16x32_bf16 v[0:3], v[224:227], v[188:191], v[0:3]
	s_add_i32 s27, s27, 2
	s_add_u32 s8, s8, 0x100
	s_addc_u32 s9, s9, 0
	s_cmp_gt_u32 s27, 29
	s_barrier
	s_cbranch_scc0 .LBB0_146
	s_lshl_b32 s2, s19, 8
	v_max_f32_e32 v122, 0, v122
	s_or_b32 s2, s24, s2
	v_mul_f32_e32 v135, v122, v122
	v_max_f32_e32 v122, v127, v127
	v_max_f32_e32 v123, 0, v123
	v_max_f32_e32 v124, 0, v124
	v_lshl_add_u32 v134, s18, 8, v141
	v_or_b32_e32 v64, s2, v140
	v_mov_b64_e32 v[130:131], s[80:81]
	s_movk_i32 s4, 0x4080
	v_max_f32_e32 v122, 0, v122
	v_mul_f32_e32 v127, v123, v123
	v_max_f32_e32 v123, v128, v128
	v_mul_f32_e32 v128, v124, v124
	v_max_f32_e32 v124, v129, v129
	v_mad_i64_i32 v[132:133], s[2:3], v134, s4, v[130:131]
	v_lshlrev_b32_e32 v64, 1, v64
	v_max_f32_e32 v126, 0, v126
	v_mul_f32_e32 v122, v122, v122
	v_max_f32_e32 v123, 0, v123
	v_max_f32_e32 v124, 0, v124
	v_max_f32_e32 v125, 0, v125
	v_lshl_add_u64 v[132:133], v[132:133], 0, v[64:65]
	v_mul_f32_e32 v126, v126, v126
	v_mul_f32_e32 v123, v123, v123
	v_mul_f32_e32 v124, v124, v124
	v_mul_f32_e32 v125, v125, v125
	v_cvt_pk_bf16_f32 v122, v126, v122
	v_max_f32_e32 v114, 0, v114
	v_max_f32_e32 v115, 0, v115
	v_max_f32_e32 v116, 0, v116
	v_cvt_pk_bf16_f32 v123, v123, v124
	v_cvt_pk_bf16_f32 v124, v135, v127
	v_cvt_pk_bf16_f32 v125, v128, v125
	global_store_dwordx4 v[132:133], v[122:125], off
	s_nop 1
	v_mul_f32_e32 v122, v114, v114
	v_max_f32_e32 v114, v119, v119
	v_mul_f32_e32 v119, v115, v115
	v_max_f32_e32 v115, v120, v120
	v_mul_f32_e32 v120, v116, v116
	v_max_f32_e32 v116, v121, v121
	v_max_f32_e32 v114, 0, v114
	v_max_f32_e32 v115, 0, v115
	v_max_f32_e32 v116, 0, v116
	v_max_f32_e32 v118, 0, v118
	v_mul_f32_e32 v114, v114, v114
	v_mul_f32_e32 v115, v115, v115
	v_max_f32_e32 v117, 0, v117
	v_mul_f32_e32 v116, v116, v116
	v_mul_f32_e32 v118, v118, v118
	v_mul_f32_e32 v117, v117, v117
	v_cvt_pk_bf16_f32 v114, v118, v114
	v_cvt_pk_bf16_f32 v115, v115, v116
	v_cvt_pk_bf16_f32 v116, v122, v119
	v_max_f32_e32 v106, 0, v106
	v_cvt_pk_bf16_f32 v117, v120, v117
	global_store_dwordx4 v[132:133], v[114:117], off offset:256
	s_nop 1
	v_max_f32_e32 v107, 0, v107
	v_max_f32_e32 v108, 0, v108
	v_mul_f32_e32 v116, v106, v106
	v_max_f32_e32 v106, v111, v111
	v_or_b32_e32 v114, 16, v134
	v_max_f32_e32 v106, 0, v106
	v_mul_f32_e32 v111, v107, v107
	v_max_f32_e32 v107, v112, v112
	v_mul_f32_e32 v112, v108, v108
	v_max_f32_e32 v108, v113, v113
	v_mad_i64_i32 v[114:115], s[2:3], v114, s4, v[130:131]
	v_max_f32_e32 v110, 0, v110
	v_mul_f32_e32 v106, v106, v106
	v_max_f32_e32 v107, 0, v107
	v_max_f32_e32 v108, 0, v108
	v_max_f32_e32 v109, 0, v109
	v_lshl_add_u64 v[114:115], v[114:115], 0, v[64:65]
	v_mul_f32_e32 v110, v110, v110
	v_mul_f32_e32 v107, v107, v107
	v_mul_f32_e32 v108, v108, v108
	v_mul_f32_e32 v109, v109, v109
	v_cvt_pk_bf16_f32 v106, v110, v106
	v_max_f32_e32 v98, 0, v98
	v_max_f32_e32 v99, 0, v99
	v_max_f32_e32 v100, 0, v100
	v_cvt_pk_bf16_f32 v107, v107, v108
	v_cvt_pk_bf16_f32 v108, v116, v111
	v_cvt_pk_bf16_f32 v109, v112, v109
	global_store_dwordx4 v[114:115], v[106:109], off
	s_nop 1
	v_mul_f32_e32 v106, v98, v98
; __device__ __forceinline__ unsigned cvt_pk_bf16(float lo, float hi) { unsigned r; asm volatile("v_cvt_pk_bf16_f32 %0, %1, %2" : "=v"(r) : "v"(lo), "v"(hi)); return r; }
;     __device__ __forceinline__ void operator()(const f32x4 (&acc)[2][2][4][2], const Unit& u, int wr, int wc, int fr, int fq) const {
;         const int row0 = u.pm * BM + wr * 64 + fr, col0 = u.pn * BM + wc * 32 + 8 * fq;
; #pragma unroll
;         for (int ai = 0; ai < 2; ++ai)
; #pragma unroll
;             for (int m = 0; m < 4; ++m) { bf16_t* rowp = O + (size_t)(row0 + ai * HALF + m * 16) * LDF + col0;
; #pragma unroll
;                 for (int bj = 0; bj < 2; ++bj) { f32x4 v0 = acc[ai][bj][m][0], v1 = acc[ai][bj][m][1];
; #pragma unroll
;                     for (int j = 0; j < 4; ++j) { const float a = fmaxf(v0[j], 0.f), b = fmaxf(v1[j], 0.f); v0[j] = a * a; v1[j] = b * b; }
;                     u32x4 w; w.x = cvt_pk_bf16(v0[0], v0[1]); w.y = cvt_pk_bf16(v0[2], v0[3]); w.z = cvt_pk_bf16(v1[0], v1[1]); w.w = cvt_pk_bf16(v1[2], v1[3]);
;                     *(u32x4*)(rowp + bj * HALF) = w; } }
	v_max_f32_e32 v98, v103, v103
	v_mul_f32_e32 v103, v99, v99
	v_max_f32_e32 v99, v104, v104
	v_mul_f32_e32 v104, v100, v100
	v_max_f32_e32 v100, v105, v105
	v_max_f32_e32 v98, 0, v98
	v_max_f32_e32 v99, 0, v99
	v_max_f32_e32 v100, 0, v100
	v_max_f32_e32 v102, 0, v102
	v_mul_f32_e32 v98, v98, v98
	v_mul_f32_e32 v99, v99, v99
	v_max_f32_e32 v101, 0, v101
	v_mul_f32_e32 v100, v100, v100
	v_mul_f32_e32 v102, v102, v102
	v_mul_f32_e32 v101, v101, v101
	v_cvt_pk_bf16_f32 v98, v102, v98
	v_cvt_pk_bf16_f32 v99, v99, v100
	v_cvt_pk_bf16_f32 v100, v106, v103
	v_max_f32_e32 v90, 0, v90
	v_cvt_pk_bf16_f32 v101, v104, v101
	global_store_dwordx4 v[114:115], v[98:101], off offset:256
	s_nop 1
	v_max_f32_e32 v91, 0, v91
	v_max_f32_e32 v92, 0, v92
	v_mul_f32_e32 v100, v90, v90
	v_max_f32_e32 v90, v95, v95
	v_or_b32_e32 v98, 32, v134
	v_max_f32_e32 v90, 0, v90
	v_mul_f32_e32 v95, v91, v91
	v_max_f32_e32 v91, v96, v96
	v_mul_f32_e32 v96, v92, v92
	v_max_f32_e32 v92, v97, v97
	v_mad_i64_i32 v[98:99], s[2:3], v98, s4, v[130:131]
	v_max_f32_e32 v94, 0, v94
	v_mul_f32_e32 v90, v90, v90
	v_max_f32_e32 v91, 0, v91
	v_max_f32_e32 v92, 0, v92
	v_max_f32_e32 v93, 0, v93
	v_lshl_add_u64 v[98:99], v[98:99], 0, v[64:65]
	v_mul_f32_e32 v94, v94, v94
	v_mul_f32_e32 v91, v91, v91
	v_mul_f32_e32 v92, v92, v92
	v_mul_f32_e32 v93, v93, v93
	v_cvt_pk_bf16_f32 v90, v94, v90
	v_max_f32_e32 v82, 0, v82
	v_max_f32_e32 v83, 0, v83
	v_max_f32_e32 v84, 0, v84
	v_cvt_pk_bf16_f32 v91, v91, v92
	v_cvt_pk_bf16_f32 v92, v100, v95
	v_cvt_pk_bf16_f32 v93, v96, v93
	global_store_dwordx4 v[98:99], v[90:93], off
	s_nop 1
	v_mul_f32_e32 v90, v82, v82
	v_max_f32_e32 v82, v87, v87
	v_mul_f32_e32 v87, v83, v83
	v_max_f32_e32 v83, v88, v88
	v_mul_f32_e32 v88, v84, v84
	v_max_f32_e32 v84, v89, v89
	v_max_f32_e32 v82, 0, v82
	v_max_f32_e32 v83, 0, v83
	v_max_f32_e32 v84, 0, v84
	v_max_f32_e32 v86, 0, v86
	v_mul_f32_e32 v82, v82, v82
	v_mul_f32_e32 v83, v83, v83
	v_max_f32_e32 v85, 0, v85
	v_mul_f32_e32 v84, v84, v84
	v_mul_f32_e32 v86, v86, v86
	v_mul_f32_e32 v85, v85, v85
	v_cvt_pk_bf16_f32 v82, v86, v82
	v_cvt_pk_bf16_f32 v83, v83, v84
	v_cvt_pk_bf16_f32 v84, v90, v87
	v_max_f32_e32 v74, 0, v74
	v_cvt_pk_bf16_f32 v85, v88, v85
	global_store_dwordx4 v[98:99], v[82:85], off offset:256
	s_nop 1
	v_max_f32_e32 v75, 0, v75
	v_max_f32_e32 v76, 0, v76
	v_mul_f32_e32 v84, v74, v74
	v_max_f32_e32 v74, v79, v79
	v_or_b32_e32 v82, 48, v134
	v_max_f32_e32 v74, 0, v74
	v_mul_f32_e32 v79, v75, v75
	v_max_f32_e32 v75, v80, v80
	v_mul_f32_e32 v80, v76, v76
	v_max_f32_e32 v76, v81, v81
	v_mad_i64_i32 v[82:83], s[2:3], v82, s4, v[130:131]
	v_max_f32_e32 v78, 0, v78
	v_mul_f32_e32 v74, v74, v74
	v_max_f32_e32 v75, 0, v75
	v_max_f32_e32 v76, 0, v76
	v_max_f32_e32 v77, 0, v77
	v_lshl_add_u64 v[82:83], v[82:83], 0, v[64:65]
	v_mul_f32_e32 v78, v78, v78
	v_mul_f32_e32 v75, v75, v75
	v_mul_f32_e32 v76, v76, v76
	v_mul_f32_e32 v77, v77, v77
	v_cvt_pk_bf16_f32 v74, v78, v74
	v_max_f32_e32 v66, 0, v66
	v_max_f32_e32 v67, 0, v67
	v_max_f32_e32 v68, 0, v68
	v_cvt_pk_bf16_f32 v75, v75, v76
	v_cvt_pk_bf16_f32 v76, v84, v79
	v_cvt_pk_bf16_f32 v77, v80, v77
	global_store_dwordx4 v[82:83], v[74:77], off
	s_nop 1
	v_mul_f32_e32 v74, v66, v66
	v_max_f32_e32 v66, v71, v71
	v_mul_f32_e32 v71, v67, v67
	v_max_f32_e32 v67, v72, v72
	v_mul_f32_e32 v72, v68, v68
	v_max_f32_e32 v68, v73, v73
	v_max_f32_e32 v66, 0, v66
	v_max_f32_e32 v67, 0, v67
	v_max_f32_e32 v68, 0, v68
	v_max_f32_e32 v70, 0, v70
	v_mul_f32_e32 v66, v66, v66
	v_mul_f32_e32 v67, v67, v67
	v_max_f32_e32 v69, 0, v69
	v_mul_f32_e32 v68, v68, v68
	v_mul_f32_e32 v70, v70, v70
	v_mul_f32_e32 v69, v69, v69
	v_cvt_pk_bf16_f32 v66, v70, v66
	v_cvt_pk_bf16_f32 v67, v67, v68
	v_cvt_pk_bf16_f32 v68, v74, v71
	v_max_f32_e32 v56, 0, v56
	v_cvt_pk_bf16_f32 v69, v72, v69
	global_store_dwordx4 v[82:83], v[66:69], off offset:256
	s_nop 1
	v_max_f32_e32 v57, 0, v57
	v_max_f32_e32 v58, 0, v58
	v_mul_f32_e32 v68, v56, v56
	v_max_f32_e32 v56, v61, v61
	v_add_u32_e32 v66, 0x80, v134
	v_max_f32_e32 v56, 0, v56
	v_mul_f32_e32 v61, v57, v57
	v_max_f32_e32 v57, v62, v62
	v_mul_f32_e32 v62, v58, v58
	v_max_f32_e32 v58, v63, v63
	v_mad_i64_i32 v[66:67], s[2:3], v66, s4, v[130:131]
	v_max_f32_e32 v60, 0, v60
	v_mul_f32_e32 v56, v56, v56
	v_max_f32_e32 v57, 0, v57
	v_max_f32_e32 v58, 0, v58
	v_max_f32_e32 v59, 0, v59
	v_lshl_add_u64 v[66:67], v[66:67], 0, v[64:65]
	v_mul_f32_e32 v60, v60, v60
	v_mul_f32_e32 v57, v57, v57
	v_mul_f32_e32 v58, v58, v58
	v_mul_f32_e32 v59, v59, v59
	v_cvt_pk_bf16_f32 v56, v60, v56
	v_max_f32_e32 v48, 0, v48
	v_max_f32_e32 v49, 0, v49
	v_max_f32_e32 v50, 0, v50
	v_cvt_pk_bf16_f32 v57, v57, v58
	v_cvt_pk_bf16_f32 v58, v68, v61
	v_cvt_pk_bf16_f32 v59, v62, v59
	global_store_dwordx4 v[66:67], v[56:59], off
	s_nop 1
	v_mul_f32_e32 v56, v48, v48
	v_max_f32_e32 v48, v53, v53
	v_mul_f32_e32 v53, v49, v49
	v_max_f32_e32 v49, v54, v54
	v_mul_f32_e32 v54, v50, v50
	v_max_f32_e32 v50, v55, v55
	v_max_f32_e32 v48, 0, v48
	v_max_f32_e32 v49, 0, v49
	v_max_f32_e32 v50, 0, v50
	v_max_f32_e32 v52, 0, v52
	v_mul_f32_e32 v48, v48, v48
	v_mul_f32_e32 v49, v49, v49
; __device__ __forceinline__ unsigned cvt_pk_bf16(float lo, float hi) { unsigned r; asm volatile("v_cvt_pk_bf16_f32 %0, %1, %2" : "=v"(r) : "v"(lo), "v"(hi)); return r; }
; #define PG8_WAIT_V(n) asm volatile("s_waitcnt vmcnt(" #n ")" ::: "memory")
; #define PG8_BAR __builtin_amdgcn_s_barrier()
;     __device__ __forceinline__ void operator()(const f32x4 (&acc)[2][2][4][2], const Unit& u, int wr, int wc, int fr, int fq) const {
;         const int row0 = u.pm * BM + wr * 64 + fr, col0 = u.pn * BM + wc * 32 + 8 * fq;
; #pragma unroll
;         for (int ai = 0; ai < 2; ++ai)
; #pragma unroll
;             for (int m = 0; m < 4; ++m) { bf16_t* rowp = O + (size_t)(row0 + ai * HALF + m * 16) * LDF + col0;
; #pragma unroll
;                 for (int bj = 0; bj < 2; ++bj) { f32x4 v0 = acc[ai][bj][m][0], v1 = acc[ai][bj][m][1];
; #pragma unroll
;                     for (int j = 0; j < 4; ++j) { const float a = fmaxf(v0[j], 0.f), b = fmaxf(v1[j], 0.f); v0[j] = a * a; v1[j] = b * b; }
;                     u32x4 w; w.x = cvt_pk_bf16(v0[0], v0[1]); w.y = cvt_pk_bf16(v0[2], v0[3]); w.z = cvt_pk_bf16(v1[0], v1[1]); w.w = cvt_pk_bf16(v1[2], v1[3]);
;                     *(u32x4*)(rowp + bj * HALF) = w; } }
;     ...
;     PG8_WAIT_V(0);
;     if (wr == 0) PG8_BAR;
	v_max_f32_e32 v51, 0, v51
	v_mul_f32_e32 v50, v50, v50
	v_mul_f32_e32 v52, v52, v52
	v_mul_f32_e32 v51, v51, v51
	v_cvt_pk_bf16_f32 v48, v52, v48
	v_cvt_pk_bf16_f32 v49, v49, v50
	v_cvt_pk_bf16_f32 v50, v56, v53
	v_max_f32_e32 v40, 0, v40
	v_cvt_pk_bf16_f32 v51, v54, v51
	global_store_dwordx4 v[66:67], v[48:51], off offset:256
	s_nop 1
	v_max_f32_e32 v41, 0, v41
	v_max_f32_e32 v42, 0, v42
	v_mul_f32_e32 v50, v40, v40
	v_max_f32_e32 v40, v45, v45
	v_add_u32_e32 v48, 0x90, v134
	v_max_f32_e32 v40, 0, v40
	v_mul_f32_e32 v45, v41, v41
	v_max_f32_e32 v41, v46, v46
	v_mul_f32_e32 v46, v42, v42
	v_max_f32_e32 v42, v47, v47
	v_mad_i64_i32 v[48:49], s[2:3], v48, s4, v[130:131]
	v_max_f32_e32 v44, 0, v44
	v_mul_f32_e32 v40, v40, v40
	v_max_f32_e32 v41, 0, v41
	v_max_f32_e32 v42, 0, v42
	v_max_f32_e32 v43, 0, v43
	v_lshl_add_u64 v[48:49], v[48:49], 0, v[64:65]
	v_mul_f32_e32 v44, v44, v44
	v_mul_f32_e32 v41, v41, v41
	v_mul_f32_e32 v42, v42, v42
	v_mul_f32_e32 v43, v43, v43
	v_cvt_pk_bf16_f32 v40, v44, v40
	v_max_f32_e32 v32, 0, v32
	v_max_f32_e32 v33, 0, v33
	v_max_f32_e32 v34, 0, v34
	v_cvt_pk_bf16_f32 v41, v41, v42
	v_cvt_pk_bf16_f32 v42, v50, v45
	v_cvt_pk_bf16_f32 v43, v46, v43
	global_store_dwordx4 v[48:49], v[40:43], off
	s_nop 1
	v_mul_f32_e32 v40, v32, v32
	v_max_f32_e32 v32, v37, v37
	v_mul_f32_e32 v37, v33, v33
	v_max_f32_e32 v33, v38, v38
	v_mul_f32_e32 v38, v34, v34
	v_max_f32_e32 v34, v39, v39
	v_max_f32_e32 v32, 0, v32
	v_max_f32_e32 v33, 0, v33
	v_max_f32_e32 v34, 0, v34
	v_max_f32_e32 v36, 0, v36
	v_mul_f32_e32 v32, v32, v32
	v_mul_f32_e32 v33, v33, v33
	v_max_f32_e32 v35, 0, v35
	v_mul_f32_e32 v34, v34, v34
	v_mul_f32_e32 v36, v36, v36
	v_mul_f32_e32 v35, v35, v35
	v_cvt_pk_bf16_f32 v32, v36, v32
	v_cvt_pk_bf16_f32 v33, v33, v34
	v_cvt_pk_bf16_f32 v34, v40, v37
	v_max_f32_e32 v24, 0, v24
	v_cvt_pk_bf16_f32 v35, v38, v35
	global_store_dwordx4 v[48:49], v[32:35], off offset:256
	s_nop 1
	v_max_f32_e32 v25, 0, v25
	v_max_f32_e32 v26, 0, v26
	v_mul_f32_e32 v34, v24, v24
	v_max_f32_e32 v24, v29, v29
	v_add_u32_e32 v32, 0xa0, v134
	v_max_f32_e32 v24, 0, v24
	v_mul_f32_e32 v29, v25, v25
	v_max_f32_e32 v25, v30, v30
	v_mul_f32_e32 v30, v26, v26
	v_max_f32_e32 v26, v31, v31
	v_mad_i64_i32 v[32:33], s[2:3], v32, s4, v[130:131]
	v_max_f32_e32 v28, 0, v28
	v_mul_f32_e32 v24, v24, v24
	v_max_f32_e32 v25, 0, v25
	v_max_f32_e32 v26, 0, v26
	v_max_f32_e32 v27, 0, v27
	v_lshl_add_u64 v[32:33], v[32:33], 0, v[64:65]
	v_mul_f32_e32 v28, v28, v28
	v_mul_f32_e32 v25, v25, v25
	v_mul_f32_e32 v26, v26, v26
	v_mul_f32_e32 v27, v27, v27
	v_cvt_pk_bf16_f32 v24, v28, v24
	v_max_f32_e32 v16, 0, v16
	v_max_f32_e32 v17, 0, v17
	v_max_f32_e32 v18, 0, v18
	v_cvt_pk_bf16_f32 v25, v25, v26
	v_cvt_pk_bf16_f32 v26, v34, v29
	v_cvt_pk_bf16_f32 v27, v30, v27
	global_store_dwordx4 v[32:33], v[24:27], off
	s_nop 1
	v_mul_f32_e32 v24, v16, v16
	v_max_f32_e32 v16, v21, v21
	v_mul_f32_e32 v21, v17, v17
	v_max_f32_e32 v17, v22, v22
	v_mul_f32_e32 v22, v18, v18
	v_max_f32_e32 v18, v23, v23
	v_max_f32_e32 v16, 0, v16
	v_max_f32_e32 v17, 0, v17
	v_max_f32_e32 v18, 0, v18
	v_max_f32_e32 v20, 0, v20
	v_mul_f32_e32 v16, v16, v16
	v_mul_f32_e32 v17, v17, v17
	v_max_f32_e32 v19, 0, v19
	v_mul_f32_e32 v18, v18, v18
	v_mul_f32_e32 v20, v20, v20
	v_mul_f32_e32 v19, v19, v19
	v_cvt_pk_bf16_f32 v16, v20, v16
	v_cvt_pk_bf16_f32 v17, v17, v18
	v_cvt_pk_bf16_f32 v18, v24, v21
	v_max_f32_e32 v8, 0, v8
	v_cvt_pk_bf16_f32 v19, v22, v19
	global_store_dwordx4 v[32:33], v[16:19], off offset:256
	s_nop 1
	v_max_f32_e32 v9, 0, v9
	v_max_f32_e32 v10, 0, v10
	v_mul_f32_e32 v18, v8, v8
	v_max_f32_e32 v8, v13, v13
	v_add_u32_e32 v16, 0xb0, v134
	v_max_f32_e32 v8, 0, v8
	v_mul_f32_e32 v13, v9, v9
	v_max_f32_e32 v9, v14, v14
	v_mul_f32_e32 v14, v10, v10
	v_max_f32_e32 v10, v15, v15
	v_mad_i64_i32 v[16:17], s[2:3], v16, s4, v[130:131]
	v_max_f32_e32 v12, 0, v12
	v_mul_f32_e32 v8, v8, v8
	v_max_f32_e32 v9, 0, v9
	v_max_f32_e32 v10, 0, v10
	v_max_f32_e32 v11, 0, v11
	v_lshl_add_u64 v[16:17], v[16:17], 0, v[64:65]
	v_mul_f32_e32 v12, v12, v12
	v_mul_f32_e32 v9, v9, v9
	v_mul_f32_e32 v10, v10, v10
	v_mul_f32_e32 v11, v11, v11
	v_cvt_pk_bf16_f32 v8, v12, v8
	v_max_f32_e32 v0, 0, v0
	v_max_f32_e32 v1, 0, v1
	v_max_f32_e32 v2, 0, v2
	v_cvt_pk_bf16_f32 v9, v9, v10
	v_cvt_pk_bf16_f32 v10, v18, v13
	v_cvt_pk_bf16_f32 v11, v14, v11
	global_store_dwordx4 v[16:17], v[8:11], off
	s_nop 1
	v_mul_f32_e32 v8, v0, v0
	v_max_f32_e32 v0, v5, v5
	v_mul_f32_e32 v5, v1, v1
	v_max_f32_e32 v1, v6, v6
	v_mul_f32_e32 v6, v2, v2
	v_max_f32_e32 v2, v7, v7
	v_max_f32_e32 v0, 0, v0
	v_max_f32_e32 v1, 0, v1
	v_max_f32_e32 v2, 0, v2
	v_max_f32_e32 v3, 0, v3
	v_max_f32_e32 v4, 0, v4
	v_mul_f32_e32 v0, v0, v0
	v_mul_f32_e32 v1, v1, v1
	v_mul_f32_e32 v2, v2, v2
	v_mul_f32_e32 v3, v3, v3
	v_mul_f32_e32 v4, v4, v4
	v_cvt_pk_bf16_f32 v0, v4, v0
	v_cvt_pk_bf16_f32 v1, v1, v2
	v_cvt_pk_bf16_f32 v2, v8, v5
	v_cvt_pk_bf16_f32 v3, v6, v3
	global_store_dwordx4 v[16:17], v[0:3], off offset:256
	s_nop 1
	s_waitcnt vmcnt(0)
	s_cmpk_lt_u32 s14, 0x100
	s_movk_i32 s27, 0x1000
	s_cbranch_scc0 .LBB0_149
	s_barrier

; #define PG8_STAGE(bufoff, gbase, voff) do { _Pragma("unroll") for (int _i = 0; _i < 2; ++_i) \
;         __builtin_amdgcn_global_load_lds((const unsigned*)((const char*)(gbase) + (voff)[_i]), (LAS unsigned*)(lds + (bufoff) + ldsw + _i * 8192), 16, 0, 0); } while (0)
; #define PG8_LDA(dst, b, h) do { _Pragma("unroll") for (int m = 0; m < 4; ++m) _Pragma("unroll") for (int k = 0; k < 2; ++k) dst[m][k] = *(const LAS bf16x8*)(lds + PG8_SA(b, h) + aoff + m * 2048 + k * 1024); } while (0)
; #define PG8_LDB(dst, b, h) do { _Pragma("unroll") for (int n = 0; n < 2; ++n) _Pragma("unroll") for (int k = 0; k < 2; ++k) dst[n][k] = *(const LAS bf16x8*)(lds + PG8_SB(b, h) + boff + n * 2048 + k * 1024); } while (0)
; #define PG8_MMA(ai, bj, At, Bt) do { __builtin_amdgcn_s_setprio(1); _Pragma("unroll") for (int m = 0; m < 4; ++m) _Pragma("unroll") for (int n = 0; n < 2; ++n) _Pragma("unroll") for (int k = 0; k < 2; ++k) \
;         acc[ai][bj][m][n] = __builtin_amdgcn_mfma_f32_16x16x32_bf16(Bt[n][k], At[m][k], acc[ai][bj][m][n], 0, 0, 0); __builtin_amdgcn_s_setprio(0); } while (0)
; #define PG8_WAIT_L(n) asm volatile("s_waitcnt lgkmcnt(" #n ")" ::: "memory")
; #define PG8_BAR __builtin_amdgcn_s_barrier()
; #define PG8_SCHED __builtin_amdgcn_sched_barrier(0)
;     ...
;             const char* a1 = cA + (size_t)(t + 1) * kstep;
;             const char* a2 = last ? nA : cA + (size_t)(t + 2) * kstep; const char* b2 = last ? nB : cB + (size_t)(t + 2) * kstep;
;             const char* a3 = a2 + kstep; const char* b3 = b2 + kstep;
;             PG8_LDB(B0, 0, 0); PG8_SCHED; PG8_LDA(At, 0, 0); PG8_STAGE(PG8_SA(1, 1), a1 + hstep, voffA);
;             PG8_WAIT_L(8); PG8_BAR; PG8_WAIT_L(0); PG8_MMA(0, 0, At, B0); PG8_BAR; PG8_SCHED;
;             PG8_LDB(B1, 0, 1); PG8_STAGE(PG8_SB(0, 0), b2, voffB);
;             PG8_BAR; PG8_WAIT_L(0); PG8_MMA(0, 1, At, B1); PG8_BAR;
;             PG8_LDA(At, 0, 1); PG8_STAGE(PG8_SA(0, 0), a2, voffA);
;             PG8_BAR; PG8_WAIT_L(0); PG8_MMA(1, 0, At, B0); PG8_BAR; PG8_SCHED;
.LBB0_475:
	s_or_b32 s94, s12, 1
	s_add_i32 s12, s12, 2
	s_mov_b32 s13, s95
	s_lshl_b64 s[2:3], s[12:13], 7
	s_add_u32 s7, s24, s2
	s_addc_u32 s13, s25, s3
	s_and_b64 vcc, s[44:45], exec
	s_cselect_b32 vcc_hi, s85, s13
	s_cselect_b32 vcc_lo, s84, s7
	s_add_u32 s7, s42, s2
	s_addc_u32 s13, s43, s3
	s_add_i32 s35, 0, 0x10000
	v_add_u32_e32 v64, s35, v220
	ds_read_b128 v[134:137], v64
	ds_read_b128 v[138:141], v64 offset:1024
	ds_read_b128 v[142:145], v64 offset:2048
	ds_read_b128 v[146:149], v64 offset:3072
	s_and_b64 s[2:3], s[44:45], exec
	s_cselect_b32 s45, s9, s13
	s_cselect_b32 s44, s8, s7
	s_lshl_b64 s[2:3], s[94:95], 7
	s_add_u32 s2, s47, s2
	s_addc_u32 s3, s89, s3
	v_lshl_add_u64 v[182:183], s[2:3], 0, v[130:131]
	s_add_i32 m0, s19, 0xc000
	ds_read_b128 v[150:153], v229
	ds_read_b128 v[154:157], v229 offset:1024
	ds_read_b128 v[158:161], v229 offset:2048
	ds_read_b128 v[162:165], v229 offset:3072
	ds_read_b128 v[166:169], v229 offset:4096
	ds_read_b128 v[170:173], v229 offset:5120
	ds_read_b128 v[174:177], v229 offset:6144
	ds_read_b128 v[178:181], v229 offset:7168
	global_load_lds_dwordx4 v[182:183], off
	v_lshl_add_u64 v[182:183], s[2:3], 0, v[132:133]
	s_add_i32 m0, s19, 0xe000
	s_nop 0
	global_load_lds_dwordx4 v[182:183], off
	s_waitcnt lgkmcnt(8)
	s_barrier
	s_waitcnt lgkmcnt(0)
	s_waitcnt lgkmcnt(0)
	v_mfma_f32_16x16x32_bf16 v[118:121], v[134:137], v[150:153], v[118:121]
	v_mfma_f32_16x16x32_bf16 v[114:117], v[142:145], v[150:153], v[114:117]
	v_mfma_f32_16x16x32_bf16 v[102:105], v[134:137], v[158:161], v[102:105]
	v_mfma_f32_16x16x32_bf16 v[98:101], v[142:145], v[158:161], v[98:101]
	v_mfma_f32_16x16x32_bf16 v[86:89], v[134:137], v[166:169], v[86:89]
	v_mfma_f32_16x16x32_bf16 v[82:85], v[142:145], v[166:169], v[82:85]
	v_mfma_f32_16x16x32_bf16 v[70:73], v[134:137], v[174:177], v[70:73]
	v_mfma_f32_16x16x32_bf16 v[66:69], v[142:145], v[174:177], v[66:69]
	v_mfma_f32_16x16x32_bf16 v[118:121], v[138:141], v[154:157], v[118:121]
	v_mfma_f32_16x16x32_bf16 v[114:117], v[146:149], v[154:157], v[114:117]
	v_mfma_f32_16x16x32_bf16 v[102:105], v[138:141], v[162:165], v[102:105]
	v_mfma_f32_16x16x32_bf16 v[98:101], v[146:149], v[162:165], v[98:101]
	v_mfma_f32_16x16x32_bf16 v[86:89], v[138:141], v[170:173], v[86:89]
	v_mfma_f32_16x16x32_bf16 v[82:85], v[146:149], v[170:173], v[82:85]
	v_mfma_f32_16x16x32_bf16 v[70:73], v[138:141], v[178:181], v[70:73]
	v_mfma_f32_16x16x32_bf16 v[66:69], v[146:149], v[178:181], v[66:69]
	s_barrier
	s_add_i32 s7, 0, 0x14000
	s_add_i32 s2, s35, s18
	v_add_u32_e32 v64, s7, v220
	v_lshl_add_u64 v[198:199], s[44:45], 0, v[130:131]
	s_mov_b32 m0, s2
	ds_read_b128 v[182:185], v64
	ds_read_b128 v[186:189], v64 offset:1024
	ds_read_b128 v[190:193], v64 offset:2048
	ds_read_b128 v[194:197], v64 offset:3072
	global_load_lds_dwordx4 v[198:199], off
	v_lshl_add_u64 v[246:247], s[44:45], 0, v[132:133]
	s_add_i32 m0, s2, 0x2000
	s_nop 0
	global_load_lds_dwordx4 v[246:247], off
	s_barrier
	s_waitcnt lgkmcnt(0)
	s_waitcnt lgkmcnt(0)
	v_mfma_f32_16x16x32_bf16 v[126:129], v[182:185], v[150:153], v[126:129]
	v_mfma_f32_16x16x32_bf16 v[122:125], v[190:193], v[150:153], v[122:125]
	v_mfma_f32_16x16x32_bf16 v[110:113], v[182:185], v[158:161], v[110:113]
	v_mfma_f32_16x16x32_bf16 v[106:109], v[190:193], v[158:161], v[106:109]
	v_mfma_f32_16x16x32_bf16 v[94:97], v[182:185], v[166:169], v[94:97]
	v_mfma_f32_16x16x32_bf16 v[90:93], v[190:193], v[166:169], v[90:93]
	v_mfma_f32_16x16x32_bf16 v[78:81], v[182:185], v[174:177], v[78:81]
	v_mfma_f32_16x16x32_bf16 v[74:77], v[190:193], v[174:177], v[74:77]
	v_mfma_f32_16x16x32_bf16 v[126:129], v[186:189], v[154:157], v[126:129]
	v_mfma_f32_16x16x32_bf16 v[122:125], v[194:197], v[154:157], v[122:125]
	v_mfma_f32_16x16x32_bf16 v[110:113], v[186:189], v[162:165], v[110:113]
	v_mfma_f32_16x16x32_bf16 v[106:109], v[194:197], v[162:165], v[106:109]
	v_mfma_f32_16x16x32_bf16 v[94:97], v[186:189], v[170:173], v[94:97]
	v_mfma_f32_16x16x32_bf16 v[90:93], v[194:197], v[170:173], v[90:93]
	v_mfma_f32_16x16x32_bf16 v[78:81], v[186:189], v[178:181], v[78:81]
	v_mfma_f32_16x16x32_bf16 v[74:77], v[194:197], v[178:181], v[74:77]
	s_mov_b32 m0, s19
	v_lshl_add_u64 v[212:213], vcc, 0, v[130:131]
	s_barrier
	ds_read_b128 v[150:153], v229 offset:16384
	ds_read_b128 v[154:157], v229 offset:17408
	ds_read_b128 v[158:161], v229 offset:18432
	ds_read_b128 v[162:165], v229 offset:19456
	ds_read_b128 v[166:169], v229 offset:20480
	ds_read_b128 v[170:173], v229 offset:21504
	ds_read_b128 v[174:177], v229 offset:22528
	ds_read_b128 v[178:181], v229 offset:23552
	global_load_lds_dwordx4 v[212:213], off
	v_lshl_add_u64 v[208:209], vcc, 0, v[132:133]
	s_mov_b32 m0, s21
	s_nop 0
	global_load_lds_dwordx4 v[208:209], off
	s_barrier
	s_waitcnt lgkmcnt(0)
	s_waitcnt lgkmcnt(0)
	v_mfma_f32_16x16x32_bf16 v[52:55], v[134:137], v[150:153], v[52:55]
	v_mfma_f32_16x16x32_bf16 v[48:51], v[142:145], v[150:153], v[48:51]
	v_mfma_f32_16x16x32_bf16 v[36:39], v[134:137], v[158:161], v[36:39]
	v_mfma_f32_16x16x32_bf16 v[32:35], v[142:145], v[158:161], v[32:35]
	v_mfma_f32_16x16x32_bf16 v[20:23], v[134:137], v[166:169], v[20:23]
	v_mfma_f32_16x16x32_bf16 v[16:19], v[142:145], v[166:169], v[16:19]
	v_mfma_f32_16x16x32_bf16 v[4:7], v[134:137], v[174:177], v[4:7]
	v_mfma_f32_16x16x32_bf16 v[0:3], v[142:145], v[174:177], v[0:3]
	v_mfma_f32_16x16x32_bf16 v[52:55], v[138:141], v[154:157], v[52:55]
	v_mfma_f32_16x16x32_bf16 v[48:51], v[146:149], v[154:157], v[48:51]
	v_mfma_f32_16x16x32_bf16 v[36:39], v[138:141], v[162:165], v[36:39]
	v_mfma_f32_16x16x32_bf16 v[32:35], v[146:149], v[162:165], v[32:35]
	v_mfma_f32_16x16x32_bf16 v[20:23], v[138:141], v[170:173], v[20:23]
	v_mfma_f32_16x16x32_bf16 v[16:19], v[146:149], v[170:173], v[16:19]
	v_mfma_f32_16x16x32_bf16 v[4:7], v[138:141], v[178:181], v[4:7]
	v_mfma_f32_16x16x32_bf16 v[0:3], v[146:149], v[178:181], v[0:3]
	s_barrier
; #define PG8_STAGE(bufoff, gbase, voff) do { _Pragma("unroll") for (int _i = 0; _i < 2; ++_i) \
;         __builtin_amdgcn_global_load_lds((const unsigned*)((const char*)(gbase) + (voff)[_i]), (LAS unsigned*)(lds + (bufoff) + ldsw + _i * 8192), 16, 0, 0); } while (0)
; #define PG8_LDA(dst, b, h) do { _Pragma("unroll") for (int m = 0; m < 4; ++m) _Pragma("unroll") for (int k = 0; k < 2; ++k) dst[m][k] = *(const LAS bf16x8*)(lds + PG8_SA(b, h) + aoff + m * 2048 + k * 1024); } while (0)
; #define PG8_LDB(dst, b, h) do { _Pragma("unroll") for (int n = 0; n < 2; ++n) _Pragma("unroll") for (int k = 0; k < 2; ++k) dst[n][k] = *(const LAS bf16x8*)(lds + PG8_SB(b, h) + boff + n * 2048 + k * 1024); } while (0)
; #define PG8_MMA(ai, bj, At, Bt) do { __builtin_amdgcn_s_setprio(1); _Pragma("unroll") for (int m = 0; m < 4; ++m) _Pragma("unroll") for (int n = 0; n < 2; ++n) _Pragma("unroll") for (int k = 0; k < 2; ++k) \
;         acc[ai][bj][m][n] = __builtin_amdgcn_mfma_f32_16x16x32_bf16(Bt[n][k], At[m][k], acc[ai][bj][m][n], 0, 0, 0); __builtin_amdgcn_s_setprio(0); } while (0)
; #define PG8_WAIT_V(n) asm volatile("s_waitcnt vmcnt(" #n ")" ::: "memory")
; #define PG8_WAIT_L(n) asm volatile("s_waitcnt lgkmcnt(" #n ")" ::: "memory")
; #define PG8_BAR __builtin_amdgcn_s_barrier()
; #define PG8_SCHED __builtin_amdgcn_sched_barrier(0)
;     ...
;             PG8_STAGE(PG8_SB(0, 1), b2 + hstep, voffB);
;             PG8_WAIT_V(6); PG8_BAR; PG8_MMA(1, 1, At, B1); PG8_BAR;
;             PG8_LDB(B0, 1, 0); PG8_SCHED; PG8_LDA(At, 1, 0); PG8_STAGE(PG8_SA(0, 1), a2 + hstep, voffA);
;             PG8_WAIT_L(8); PG8_BAR; PG8_WAIT_L(0); PG8_MMA(0, 0, At, B0); PG8_BAR; PG8_SCHED;
;             PG8_LDB(B1, 1, 1); PG8_STAGE(PG8_SB(1, 0), b3, voffB);
;             PG8_BAR; PG8_WAIT_L(0); PG8_MMA(0, 1, At, B1); PG8_BAR;
;             PG8_LDA(At, 1, 1); PG8_STAGE(PG8_SA(1, 0), a3, voffA);
;             PG8_BAR; PG8_WAIT_L(0); PG8_MMA(1, 0, At, B0); PG8_BAR; PG8_SCHED;
	s_add_u32 s2, s44, s82
	s_addc_u32 s3, s45, 0
	s_add_i32 s7, s7, s18
	v_lshl_add_u64 v[210:211], s[2:3], 0, v[130:131]
	s_mov_b32 m0, s7
	v_lshl_add_u64 v[214:215], s[2:3], 0, v[132:133]
	global_load_lds_dwordx4 v[210:211], off
	s_add_i32 m0, s7, 0x2000
	s_nop 0
	global_load_lds_dwordx4 v[214:215], off
	s_waitcnt vmcnt(6)
	s_barrier
	v_mfma_f32_16x16x32_bf16 v[60:63], v[182:185], v[150:153], v[60:63]
	v_mfma_f32_16x16x32_bf16 v[56:59], v[190:193], v[150:153], v[56:59]
	v_mfma_f32_16x16x32_bf16 v[44:47], v[182:185], v[158:161], v[44:47]
	v_mfma_f32_16x16x32_bf16 v[40:43], v[190:193], v[158:161], v[40:43]
	v_mfma_f32_16x16x32_bf16 v[28:31], v[182:185], v[166:169], v[28:31]
	v_mfma_f32_16x16x32_bf16 v[24:27], v[190:193], v[166:169], v[24:27]
	v_mfma_f32_16x16x32_bf16 v[12:15], v[182:185], v[174:177], v[12:15]
	v_mfma_f32_16x16x32_bf16 v[8:11], v[190:193], v[174:177], v[8:11]
	v_mfma_f32_16x16x32_bf16 v[60:63], v[186:189], v[154:157], v[60:63]
	v_mfma_f32_16x16x32_bf16 v[56:59], v[194:197], v[154:157], v[56:59]
	v_mfma_f32_16x16x32_bf16 v[44:47], v[186:189], v[162:165], v[44:47]
	v_mfma_f32_16x16x32_bf16 v[40:43], v[194:197], v[162:165], v[40:43]
	v_mfma_f32_16x16x32_bf16 v[28:31], v[186:189], v[170:173], v[28:31]
	v_mfma_f32_16x16x32_bf16 v[24:27], v[194:197], v[170:173], v[24:27]
	v_mfma_f32_16x16x32_bf16 v[12:15], v[186:189], v[178:181], v[12:15]
	v_mfma_f32_16x16x32_bf16 v[8:11], v[194:197], v[178:181], v[8:11]
	s_add_i32 s7, 0, 0x18000
	v_add_u32_e32 v64, s7, v220
	s_barrier
	ds_read_b128 v[134:137], v64
	ds_read_b128 v[138:141], v64 offset:1024
	ds_read_b128 v[142:145], v64 offset:2048
	ds_read_b128 v[146:149], v64 offset:3072
	s_add_u32 s2, vcc_lo, s82
	s_addc_u32 s3, vcc_hi, 0
	s_mov_b32 m0, s31
	v_lshl_add_u64 v[182:183], s[2:3], 0, v[130:131]
	ds_read_b128 v[150:153], v229 offset:32768
	ds_read_b128 v[154:157], v229 offset:33792
	ds_read_b128 v[158:161], v229 offset:34816
	ds_read_b128 v[162:165], v229 offset:35840
	ds_read_b128 v[166:169], v229 offset:36864
	ds_read_b128 v[170:173], v229 offset:37888
	ds_read_b128 v[174:177], v229 offset:38912
	ds_read_b128 v[178:181], v229 offset:39936
	global_load_lds_dwordx4 v[182:183], off
	v_lshl_add_u64 v[182:183], s[2:3], 0, v[132:133]
	s_mov_b32 m0, s83
	s_nop 0
	global_load_lds_dwordx4 v[182:183], off
	s_waitcnt lgkmcnt(8)
	s_barrier
	s_waitcnt lgkmcnt(0)
	s_waitcnt lgkmcnt(0)
	v_mfma_f32_16x16x32_bf16 v[118:121], v[134:137], v[150:153], v[118:121]
	v_mfma_f32_16x16x32_bf16 v[114:117], v[142:145], v[150:153], v[114:117]
	v_mfma_f32_16x16x32_bf16 v[102:105], v[134:137], v[158:161], v[102:105]
	v_mfma_f32_16x16x32_bf16 v[98:101], v[142:145], v[158:161], v[98:101]
	v_mfma_f32_16x16x32_bf16 v[86:89], v[134:137], v[166:169], v[86:89]
	v_mfma_f32_16x16x32_bf16 v[82:85], v[142:145], v[166:169], v[82:85]
	v_mfma_f32_16x16x32_bf16 v[70:73], v[134:137], v[174:177], v[70:73]
	v_mfma_f32_16x16x32_bf16 v[66:69], v[142:145], v[174:177], v[66:69]
	v_mfma_f32_16x16x32_bf16 v[118:121], v[138:141], v[154:157], v[118:121]
	v_mfma_f32_16x16x32_bf16 v[114:117], v[146:149], v[154:157], v[114:117]
	v_mfma_f32_16x16x32_bf16 v[102:105], v[138:141], v[162:165], v[102:105]
	v_mfma_f32_16x16x32_bf16 v[98:101], v[146:149], v[162:165], v[98:101]
	v_mfma_f32_16x16x32_bf16 v[86:89], v[138:141], v[170:173], v[86:89]
	v_mfma_f32_16x16x32_bf16 v[82:85], v[146:149], v[170:173], v[82:85]
	v_mfma_f32_16x16x32_bf16 v[70:73], v[138:141], v[178:181], v[70:73]
	v_mfma_f32_16x16x32_bf16 v[66:69], v[146:149], v[178:181], v[66:69]
	s_barrier
	s_add_i32 s2, 0, 0x1c000
	s_add_i32 s3, s7, s18
	v_add_u32_e32 v64, s2, v220
	v_lshl_add_u64 v[198:199], v[198:199], 0, s[16:17]
	s_mov_b32 m0, s3
	ds_read_b128 v[182:185], v64
	ds_read_b128 v[186:189], v64 offset:1024
	ds_read_b128 v[190:193], v64 offset:2048
	ds_read_b128 v[194:197], v64 offset:3072
	global_load_lds_dwordx4 v[198:199], off
	v_lshl_add_u64 v[198:199], v[246:247], 0, s[16:17]
	s_add_i32 m0, s3, 0x2000
	s_nop 0
	global_load_lds_dwordx4 v[198:199], off
	s_barrier
; #define PG8_STAGE(bufoff, gbase, voff) do { _Pragma("unroll") for (int _i = 0; _i < 2; ++_i) \
;         __builtin_amdgcn_global_load_lds((const unsigned*)((const char*)(gbase) + (voff)[_i]), (LAS unsigned*)(lds + (bufoff) + ldsw + _i * 8192), 16, 0, 0); } while (0)
; #define PG8_MMA(ai, bj, At, Bt) do { __builtin_amdgcn_s_setprio(1); _Pragma("unroll") for (int m = 0; m < 4; ++m) _Pragma("unroll") for (int n = 0; n < 2; ++n) _Pragma("unroll") for (int k = 0; k < 2; ++k) \
;         acc[ai][bj][m][n] = __builtin_amdgcn_mfma_f32_16x16x32_bf16(Bt[n][k], At[m][k], acc[ai][bj][m][n], 0, 0, 0); __builtin_amdgcn_s_setprio(0); } while (0)
; #define PG8_WAIT_V(n) asm volatile("s_waitcnt vmcnt(" #n ")" ::: "memory")
; #define PG8_WAIT_L(n) asm volatile("s_waitcnt lgkmcnt(" #n ")" ::: "memory")
; #define PG8_BAR __builtin_amdgcn_s_barrier()
; #define PG8_SCHED __builtin_amdgcn_sched_barrier(0)
;     ...
;             PG8_BAR; PG8_WAIT_L(0); PG8_MMA(1, 0, At, B0); PG8_BAR; PG8_SCHED;
;             PG8_STAGE(PG8_SB(1, 1), b3 + hstep, voffB);
;             PG8_WAIT_V(6); PG8_BAR; PG8_MMA(1, 1, At, B1); PG8_BAR;
;         }
	s_waitcnt lgkmcnt(0)
	s_waitcnt lgkmcnt(0)
	v_mfma_f32_16x16x32_bf16 v[126:129], v[182:185], v[150:153], v[126:129]
	v_mfma_f32_16x16x32_bf16 v[122:125], v[190:193], v[150:153], v[122:125]
	v_mfma_f32_16x16x32_bf16 v[110:113], v[182:185], v[158:161], v[110:113]
	v_mfma_f32_16x16x32_bf16 v[106:109], v[190:193], v[158:161], v[106:109]
	v_mfma_f32_16x16x32_bf16 v[94:97], v[182:185], v[166:169], v[94:97]
	v_mfma_f32_16x16x32_bf16 v[90:93], v[190:193], v[166:169], v[90:93]
	v_mfma_f32_16x16x32_bf16 v[78:81], v[182:185], v[174:177], v[78:81]
	v_mfma_f32_16x16x32_bf16 v[74:77], v[190:193], v[174:177], v[74:77]
	v_mfma_f32_16x16x32_bf16 v[126:129], v[186:189], v[154:157], v[126:129]
	v_mfma_f32_16x16x32_bf16 v[122:125], v[194:197], v[154:157], v[122:125]
	v_mfma_f32_16x16x32_bf16 v[110:113], v[186:189], v[162:165], v[110:113]
	v_mfma_f32_16x16x32_bf16 v[106:109], v[194:197], v[162:165], v[106:109]
	v_mfma_f32_16x16x32_bf16 v[94:97], v[186:189], v[170:173], v[94:97]
	v_mfma_f32_16x16x32_bf16 v[90:93], v[194:197], v[170:173], v[90:93]
	v_mfma_f32_16x16x32_bf16 v[78:81], v[186:189], v[178:181], v[78:81]
	v_mfma_f32_16x16x32_bf16 v[74:77], v[194:197], v[178:181], v[74:77]
	s_mov_b32 m0, s36
	v_lshl_add_u64 v[198:199], v[212:213], 0, s[16:17]
	s_barrier
	ds_read_b128 v[150:153], v229 offset:49152
	ds_read_b128 v[154:157], v229 offset:50176
	ds_read_b128 v[158:161], v229 offset:51200
	ds_read_b128 v[162:165], v229 offset:52224
	ds_read_b128 v[166:169], v229 offset:53248
	ds_read_b128 v[170:173], v229 offset:54272
	ds_read_b128 v[174:177], v229 offset:55296
	ds_read_b128 v[178:181], v229 offset:56320
	global_load_lds_dwordx4 v[198:199], off
	v_lshl_add_u64 v[198:199], v[208:209], 0, s[16:17]
	s_mov_b32 m0, s37
	s_nop 0
	global_load_lds_dwordx4 v[198:199], off
	s_barrier
	s_waitcnt lgkmcnt(0)
	s_waitcnt lgkmcnt(0)
	v_mfma_f32_16x16x32_bf16 v[52:55], v[134:137], v[150:153], v[52:55]
	v_mfma_f32_16x16x32_bf16 v[48:51], v[142:145], v[150:153], v[48:51]
	v_mfma_f32_16x16x32_bf16 v[36:39], v[134:137], v[158:161], v[36:39]
	v_mfma_f32_16x16x32_bf16 v[32:35], v[142:145], v[158:161], v[32:35]
	v_mfma_f32_16x16x32_bf16 v[20:23], v[134:137], v[166:169], v[20:23]
	v_mfma_f32_16x16x32_bf16 v[16:19], v[142:145], v[166:169], v[16:19]
	v_mfma_f32_16x16x32_bf16 v[4:7], v[134:137], v[174:177], v[4:7]
	v_mfma_f32_16x16x32_bf16 v[0:3], v[142:145], v[174:177], v[0:3]
	v_mfma_f32_16x16x32_bf16 v[52:55], v[138:141], v[154:157], v[52:55]
	v_mfma_f32_16x16x32_bf16 v[48:51], v[146:149], v[154:157], v[48:51]
	v_mfma_f32_16x16x32_bf16 v[36:39], v[138:141], v[162:165], v[36:39]
	v_mfma_f32_16x16x32_bf16 v[32:35], v[146:149], v[162:165], v[32:35]
	v_mfma_f32_16x16x32_bf16 v[20:23], v[138:141], v[170:173], v[20:23]
	v_mfma_f32_16x16x32_bf16 v[16:19], v[146:149], v[170:173], v[16:19]
	v_mfma_f32_16x16x32_bf16 v[4:7], v[138:141], v[178:181], v[4:7]
	v_mfma_f32_16x16x32_bf16 v[0:3], v[146:149], v[178:181], v[0:3]
	s_barrier
	s_add_i32 s2, s2, s18
	v_lshl_add_u64 v[134:135], v[210:211], 0, s[16:17]
	s_mov_b32 m0, s2
	s_nop 0
	global_load_lds_dwordx4 v[134:135], off
	v_lshl_add_u64 v[134:135], v[214:215], 0, s[16:17]
	s_add_i32 m0, s2, 0x2000
	s_nop 0
	global_load_lds_dwordx4 v[134:135], off
	s_waitcnt vmcnt(6)
	s_barrier
	v_mfma_f32_16x16x32_bf16 v[60:63], v[182:185], v[150:153], v[60:63]
	v_mfma_f32_16x16x32_bf16 v[56:59], v[190:193], v[150:153], v[56:59]
	v_mfma_f32_16x16x32_bf16 v[44:47], v[182:185], v[158:161], v[44:47]
	v_mfma_f32_16x16x32_bf16 v[40:43], v[190:193], v[158:161], v[40:43]
	v_mfma_f32_16x16x32_bf16 v[28:31], v[182:185], v[166:169], v[28:31]
	v_mfma_f32_16x16x32_bf16 v[24:27], v[190:193], v[166:169], v[24:27]
	v_mfma_f32_16x16x32_bf16 v[12:15], v[182:185], v[174:177], v[12:15]
	v_mfma_f32_16x16x32_bf16 v[8:11], v[190:193], v[174:177], v[8:11]
	v_mfma_f32_16x16x32_bf16 v[60:63], v[186:189], v[154:157], v[60:63]
	v_mfma_f32_16x16x32_bf16 v[56:59], v[194:197], v[154:157], v[56:59]
	v_mfma_f32_16x16x32_bf16 v[44:47], v[186:189], v[162:165], v[44:47]
	v_mfma_f32_16x16x32_bf16 v[40:43], v[194:197], v[162:165], v[40:43]
	v_mfma_f32_16x16x32_bf16 v[28:31], v[186:189], v[170:173], v[28:31]
	v_mfma_f32_16x16x32_bf16 v[24:27], v[194:197], v[170:173], v[24:27]
	v_mfma_f32_16x16x32_bf16 v[12:15], v[186:189], v[178:181], v[12:15]
	v_mfma_f32_16x16x32_bf16 v[8:11], v[194:197], v[178:181], v[8:11]
	s_cmp_ge_u32 s12, s6
	s_barrier
	s_cbranch_scc1 .LBB0_482

; #define PG8_STAGE(bufoff, gbase, voff) do { _Pragma("unroll") for (int _i = 0; _i < 2; ++_i) \
;         __builtin_amdgcn_global_load_lds((const unsigned*)((const char*)(gbase) + (voff)[_i]), (LAS unsigned*)(lds + (bufoff) + ldsw + _i * 8192), 16, 0, 0); } while (0)
; #define PG8_LDA(dst, b, h) do { _Pragma("unroll") for (int m = 0; m < 4; ++m) _Pragma("unroll") for (int k = 0; k < 2; ++k) dst[m][k] = *(const LAS bf16x8*)(lds + PG8_SA(b, h) + aoff + m * 2048 + k * 1024); } while (0)
; #define PG8_LDB(dst, b, h) do { _Pragma("unroll") for (int n = 0; n < 2; ++n) _Pragma("unroll") for (int k = 0; k < 2; ++k) dst[n][k] = *(const LAS bf16x8*)(lds + PG8_SB(b, h) + boff + n * 2048 + k * 1024); } while (0)
; #define PG8_WAIT_L(n) asm volatile("s_waitcnt lgkmcnt(" #n ")" ::: "memory")
; #define PG8_BAR __builtin_amdgcn_s_barrier()
; #define PG8_SCHED __builtin_amdgcn_sched_barrier(0)
;     ...
;         for (int t = 0; t < nt; t += 2) {
;             const bool last = (t == nt - 2);
;             if (last && has_next && gate != nullptr && nxt.pm >= 32) {
;                 if (tid < 64) { unsigned sp = 0;
;                     while ((unsigned)__builtin_amdgcn_readfirstlane(__hip_atomic_load(gate, __ATOMIC_RELAXED, __HIP_MEMORY_SCOPE_AGENT)) < gate_need) { __builtin_amdgcn_s_sleep(2); if (++sp > (1u << 20)) break; }
;                     __builtin_amdgcn_fence(__ATOMIC_ACQUIRE, "agent"); asm volatile("s_waitcnt vmcnt(0)" ::: "memory"); }
;                 asm volatile("" ::: "memory"); PG8_BAR; asm volatile("" ::: "memory");
;             }
;             const char* a1 = cA + (size_t)(t + 1) * kstep;
;             const char* a2 = last ? nA : cA + (size_t)(t + 2) * kstep; const char* b2 = last ? nB : cB + (size_t)(t + 2) * kstep;
;             const char* a3 = a2 + kstep; const char* b3 = b2 + kstep;
;             PG8_LDB(B0, 0, 0); PG8_SCHED; PG8_LDA(At, 0, 0); PG8_STAGE(PG8_SA(1, 1), a1 + hstep, voffA);
;             PG8_WAIT_L(8); PG8_BAR; PG8_WAIT_L(0); PG8_MMA(0, 0, At, B0); PG8_BAR; PG8_SCHED;
;             PG8_LDB(B1, 0, 1); PG8_STAGE(PG8_SB(0, 0), b2, voffB);
;             PG8_BAR; PG8_WAIT_L(0); PG8_MMA(0, 1, At, B1); PG8_BAR;
;             PG8_LDA(At, 0, 1); PG8_STAGE(PG8_SA(0, 0), a2, voffA);
;             PG8_BAR; PG8_WAIT_L(0); PG8_MMA(1, 0, At, B0); PG8_BAR; PG8_SCHED;
.LBB0_1275:
	s_add_u32 s2, s6, 0xe767c080
	s_addc_u32 s3, s7, -1
	s_cmp_lg_u32 s23, 28
	s_cselect_b32 s8, s2, 0
	s_cselect_b32 s9, s3, 0
	s_add_u32 s2, s4, s8
	s_addc_u32 s3, s5, s9
	s_add_i32 s24, 0, 0x10000
	v_add_u32_e32 v152, s24, v138
	ds_read_b128 v[140:143], v152
	ds_read_b128 v[144:147], v152 offset:1024
	ds_read_b128 v[148:151], v152 offset:2048
	ds_read_b128 v[152:155], v152 offset:3072
	s_add_u32 s8, s0, s8
	s_addc_u32 s9, s1, s9
	v_lshl_add_u64 v[188:189], v[132:133], 0, s[6:7]
	s_add_i32 m0, s15, 0xc000
	ds_read_b128 v[156:159], v139
	ds_read_b128 v[160:163], v139 offset:1024
	ds_read_b128 v[164:167], v139 offset:2048
	ds_read_b128 v[168:171], v139 offset:3072
	ds_read_b128 v[172:175], v139 offset:4096
	ds_read_b128 v[176:179], v139 offset:5120
	ds_read_b128 v[180:183], v139 offset:6144
	ds_read_b128 v[184:187], v139 offset:7168
	global_load_lds_dwordx4 v[188:189], off
	v_lshl_add_u64 v[188:189], v[134:135], 0, s[6:7]
	s_add_i32 m0, s15, 0xe000
	s_nop 0
	global_load_lds_dwordx4 v[188:189], off
	s_waitcnt lgkmcnt(8)
	s_barrier
	s_waitcnt lgkmcnt(0)
	s_waitcnt lgkmcnt(0)
	v_mfma_f32_16x16x32_bf16 v[126:129], v[140:143], v[156:159], v[126:129]
	v_mfma_f32_16x16x32_bf16 v[122:125], v[148:151], v[156:159], v[122:125]
	v_mfma_f32_16x16x32_bf16 v[110:113], v[140:143], v[164:167], v[110:113]
	v_mfma_f32_16x16x32_bf16 v[106:109], v[148:151], v[164:167], v[106:109]
	v_mfma_f32_16x16x32_bf16 v[94:97], v[140:143], v[172:175], v[94:97]
	v_mfma_f32_16x16x32_bf16 v[90:93], v[148:151], v[172:175], v[90:93]
	v_mfma_f32_16x16x32_bf16 v[78:81], v[140:143], v[180:183], v[78:81]
	v_mfma_f32_16x16x32_bf16 v[74:77], v[148:151], v[180:183], v[74:77]
	v_mfma_f32_16x16x32_bf16 v[126:129], v[144:147], v[160:163], v[126:129]
	v_mfma_f32_16x16x32_bf16 v[122:125], v[152:155], v[160:163], v[122:125]
	v_mfma_f32_16x16x32_bf16 v[110:113], v[144:147], v[168:171], v[110:113]
	v_mfma_f32_16x16x32_bf16 v[106:109], v[152:155], v[168:171], v[106:109]
	v_mfma_f32_16x16x32_bf16 v[94:97], v[144:147], v[176:179], v[94:97]
	v_mfma_f32_16x16x32_bf16 v[90:93], v[152:155], v[176:179], v[90:93]
	v_mfma_f32_16x16x32_bf16 v[78:81], v[144:147], v[184:187], v[78:81]
	v_mfma_f32_16x16x32_bf16 v[74:77], v[152:155], v[184:187], v[74:77]
	s_barrier
	s_add_i32 s26, 0, 0x14000
	s_add_i32 s24, s24, s14
	v_add_u32_e32 v208, s26, v138
	v_lshl_add_u64 v[224:225], s[8:9], 0, v[64:65]
	s_mov_b32 m0, s24
	ds_read_b128 v[188:191], v208
	ds_read_b128 v[192:195], v208 offset:1024
	ds_read_b128 v[196:199], v208 offset:2048
	ds_read_b128 v[220:223], v208 offset:3072
	global_load_lds_dwordx4 v[224:225], off
	v_lshl_add_u64 v[226:227], s[8:9], 0, v[130:131]
	s_add_i32 m0, s24, 0x2000
	s_nop 0
	global_load_lds_dwordx4 v[226:227], off
	s_barrier
	s_waitcnt lgkmcnt(0)
	s_waitcnt lgkmcnt(0)
	v_mfma_f32_16x16x32_bf16 v[118:121], v[188:191], v[156:159], v[118:121]
	v_mfma_f32_16x16x32_bf16 v[114:117], v[196:199], v[156:159], v[114:117]
	v_mfma_f32_16x16x32_bf16 v[102:105], v[188:191], v[164:167], v[102:105]
	v_mfma_f32_16x16x32_bf16 v[98:101], v[196:199], v[164:167], v[98:101]
	v_mfma_f32_16x16x32_bf16 v[86:89], v[188:191], v[172:175], v[86:89]
	v_mfma_f32_16x16x32_bf16 v[82:85], v[196:199], v[172:175], v[82:85]
	v_mfma_f32_16x16x32_bf16 v[70:73], v[188:191], v[180:183], v[70:73]
	v_mfma_f32_16x16x32_bf16 v[66:69], v[196:199], v[180:183], v[66:69]
	v_mfma_f32_16x16x32_bf16 v[118:121], v[192:195], v[160:163], v[118:121]
	v_mfma_f32_16x16x32_bf16 v[114:117], v[220:223], v[160:163], v[114:117]
	v_mfma_f32_16x16x32_bf16 v[102:105], v[192:195], v[168:171], v[102:105]
	v_mfma_f32_16x16x32_bf16 v[98:101], v[220:223], v[168:171], v[98:101]
	v_mfma_f32_16x16x32_bf16 v[86:89], v[192:195], v[176:179], v[86:89]
	v_mfma_f32_16x16x32_bf16 v[82:85], v[220:223], v[176:179], v[82:85]
	v_mfma_f32_16x16x32_bf16 v[70:73], v[192:195], v[184:187], v[70:73]
	v_mfma_f32_16x16x32_bf16 v[66:69], v[220:223], v[184:187], v[66:69]
	s_mov_b32 m0, s15
	v_lshl_add_u64 v[228:229], s[2:3], 0, v[64:65]
	s_barrier
	ds_read_b128 v[156:159], v139 offset:16384
	ds_read_b128 v[160:163], v139 offset:17408
	ds_read_b128 v[164:167], v139 offset:18432
	ds_read_b128 v[168:171], v139 offset:19456
	ds_read_b128 v[172:175], v139 offset:20480
	ds_read_b128 v[176:179], v139 offset:21504
	ds_read_b128 v[180:183], v139 offset:22528
	ds_read_b128 v[184:187], v139 offset:23552
	global_load_lds_dwordx4 v[228:229], off
	v_lshl_add_u64 v[230:231], s[2:3], 0, v[130:131]
	s_mov_b32 m0, s18
	s_nop 0
	global_load_lds_dwordx4 v[230:231], off
	s_barrier
	s_waitcnt lgkmcnt(0)
	s_waitcnt lgkmcnt(0)
	v_mfma_f32_16x16x32_bf16 v[60:63], v[140:143], v[156:159], v[60:63]
	v_mfma_f32_16x16x32_bf16 v[56:59], v[148:151], v[156:159], v[56:59]
	v_mfma_f32_16x16x32_bf16 v[44:47], v[140:143], v[164:167], v[44:47]
	v_mfma_f32_16x16x32_bf16 v[40:43], v[148:151], v[164:167], v[40:43]
	v_mfma_f32_16x16x32_bf16 v[28:31], v[140:143], v[172:175], v[28:31]
	v_mfma_f32_16x16x32_bf16 v[24:27], v[148:151], v[172:175], v[24:27]
	v_mfma_f32_16x16x32_bf16 v[12:15], v[140:143], v[180:183], v[12:15]
	v_mfma_f32_16x16x32_bf16 v[8:11], v[148:151], v[180:183], v[8:11]
	v_mfma_f32_16x16x32_bf16 v[60:63], v[144:147], v[160:163], v[60:63]
	v_mfma_f32_16x16x32_bf16 v[56:59], v[152:155], v[160:163], v[56:59]
	v_mfma_f32_16x16x32_bf16 v[44:47], v[144:147], v[168:171], v[44:47]
	v_mfma_f32_16x16x32_bf16 v[40:43], v[152:155], v[168:171], v[40:43]
	v_mfma_f32_16x16x32_bf16 v[28:31], v[144:147], v[176:179], v[28:31]
	v_mfma_f32_16x16x32_bf16 v[24:27], v[152:155], v[176:179], v[24:27]
	v_mfma_f32_16x16x32_bf16 v[12:15], v[144:147], v[184:187], v[12:15]
	v_mfma_f32_16x16x32_bf16 v[8:11], v[152:155], v[184:187], v[8:11]
	s_barrier
; #define PG8_STAGE(bufoff, gbase, voff) do { _Pragma("unroll") for (int _i = 0; _i < 2; ++_i) \
;         __builtin_amdgcn_global_load_lds((const unsigned*)((const char*)(gbase) + (voff)[_i]), (LAS unsigned*)(lds + (bufoff) + ldsw + _i * 8192), 16, 0, 0); } while (0)
; #define PG8_LDA(dst, b, h) do { _Pragma("unroll") for (int m = 0; m < 4; ++m) _Pragma("unroll") for (int k = 0; k < 2; ++k) dst[m][k] = *(const LAS bf16x8*)(lds + PG8_SA(b, h) + aoff + m * 2048 + k * 1024); } while (0)
; #define PG8_LDB(dst, b, h) do { _Pragma("unroll") for (int n = 0; n < 2; ++n) _Pragma("unroll") for (int k = 0; k < 2; ++k) dst[n][k] = *(const LAS bf16x8*)(lds + PG8_SB(b, h) + boff + n * 2048 + k * 1024); } while (0)
; #define PG8_MMA(ai, bj, At, Bt) do { __builtin_amdgcn_s_setprio(1); _Pragma("unroll") for (int m = 0; m < 4; ++m) _Pragma("unroll") for (int n = 0; n < 2; ++n) _Pragma("unroll") for (int k = 0; k < 2; ++k) \
;         acc[ai][bj][m][n] = __builtin_amdgcn_mfma_f32_16x16x32_bf16(Bt[n][k], At[m][k], acc[ai][bj][m][n], 0, 0, 0); __builtin_amdgcn_s_setprio(0); } while (0)
; #define PG8_WAIT_V(n) asm volatile("s_waitcnt vmcnt(" #n ")" ::: "memory")
; #define PG8_WAIT_L(n) asm volatile("s_waitcnt lgkmcnt(" #n ")" ::: "memory")
; #define PG8_BAR __builtin_amdgcn_s_barrier()
; #define PG8_SCHED __builtin_amdgcn_sched_barrier(0)
;     ...
;             PG8_BAR; PG8_WAIT_L(0); PG8_MMA(1, 0, At, B0); PG8_BAR; PG8_SCHED;
;             PG8_STAGE(PG8_SB(0, 1), b2 + hstep, voffB);
;             PG8_WAIT_V(6); PG8_BAR; PG8_MMA(1, 1, At, B1); PG8_BAR;
;             PG8_LDB(B0, 1, 0); PG8_SCHED; PG8_LDA(At, 1, 0); PG8_STAGE(PG8_SA(0, 1), a2 + hstep, voffA);
;             PG8_WAIT_L(8); PG8_BAR; PG8_WAIT_L(0); PG8_MMA(0, 0, At, B0); PG8_BAR; PG8_SCHED;
;             PG8_LDB(B1, 1, 1); PG8_STAGE(PG8_SB(1, 0), b3, voffB);
;             PG8_BAR; PG8_WAIT_L(0); PG8_MMA(0, 1, At, B1); PG8_BAR;
;             PG8_LDA(At, 1, 1); PG8_STAGE(PG8_SA(1, 0), a3, voffA);
;             PG8_BAR; PG8_WAIT_L(0); PG8_MMA(1, 0, At, B0); PG8_BAR; PG8_SCHED;
	s_add_u32 s24, s8, 0x84000
	s_addc_u32 s25, s9, 0
	s_add_i32 s26, s26, s14
	v_lshl_add_u64 v[140:141], s[24:25], 0, v[64:65]
	s_mov_b32 m0, s26
	s_nop 0
	global_load_lds_dwordx4 v[140:141], off
	v_lshl_add_u64 v[140:141], s[24:25], 0, v[130:131]
	s_add_i32 m0, s26, 0x2000
	s_nop 0
	global_load_lds_dwordx4 v[140:141], off
	s_waitcnt vmcnt(6)
	s_barrier
	v_mfma_f32_16x16x32_bf16 v[52:55], v[188:191], v[156:159], v[52:55]
	v_mfma_f32_16x16x32_bf16 v[48:51], v[196:199], v[156:159], v[48:51]
	v_mfma_f32_16x16x32_bf16 v[36:39], v[188:191], v[164:167], v[36:39]
	v_mfma_f32_16x16x32_bf16 v[32:35], v[196:199], v[164:167], v[32:35]
	v_mfma_f32_16x16x32_bf16 v[20:23], v[188:191], v[172:175], v[20:23]
	v_mfma_f32_16x16x32_bf16 v[16:19], v[196:199], v[172:175], v[16:19]
	v_mfma_f32_16x16x32_bf16 v[4:7], v[188:191], v[180:183], v[4:7]
	v_mfma_f32_16x16x32_bf16 v[0:3], v[196:199], v[180:183], v[0:3]
	v_mfma_f32_16x16x32_bf16 v[52:55], v[192:195], v[160:163], v[52:55]
	v_mfma_f32_16x16x32_bf16 v[48:51], v[220:223], v[160:163], v[48:51]
	v_mfma_f32_16x16x32_bf16 v[36:39], v[192:195], v[168:171], v[36:39]
	v_mfma_f32_16x16x32_bf16 v[32:35], v[220:223], v[168:171], v[32:35]
	v_mfma_f32_16x16x32_bf16 v[20:23], v[192:195], v[176:179], v[20:23]
	v_mfma_f32_16x16x32_bf16 v[16:19], v[220:223], v[176:179], v[16:19]
	v_mfma_f32_16x16x32_bf16 v[4:7], v[192:195], v[184:187], v[4:7]
	v_mfma_f32_16x16x32_bf16 v[0:3], v[220:223], v[184:187], v[0:3]
	s_add_i32 s24, 0, 0x18000
	v_add_u32_e32 v152, s24, v138
	s_barrier
	ds_read_b128 v[140:143], v152
	ds_read_b128 v[144:147], v152 offset:1024
	ds_read_b128 v[148:151], v152 offset:2048
	ds_read_b128 v[152:155], v152 offset:3072
	s_add_u32 s2, s2, 0x84000
	s_addc_u32 s3, s3, 0
	s_mov_b32 m0, s19
	v_lshl_add_u64 v[188:189], s[2:3], 0, v[64:65]
	ds_read_b128 v[156:159], v139 offset:32768
	ds_read_b128 v[160:163], v139 offset:33792
	ds_read_b128 v[164:167], v139 offset:34816
	ds_read_b128 v[168:171], v139 offset:35840
	ds_read_b128 v[172:175], v139 offset:36864
	ds_read_b128 v[176:179], v139 offset:37888
	ds_read_b128 v[180:183], v139 offset:38912
	ds_read_b128 v[184:187], v139 offset:39936
	global_load_lds_dwordx4 v[188:189], off
	v_lshl_add_u64 v[188:189], s[2:3], 0, v[130:131]
	s_mov_b32 m0, s20
	s_nop 0
	global_load_lds_dwordx4 v[188:189], off
	s_waitcnt lgkmcnt(8)
	s_barrier
	s_waitcnt lgkmcnt(0)
	s_waitcnt lgkmcnt(0)
	v_mfma_f32_16x16x32_bf16 v[126:129], v[140:143], v[156:159], v[126:129]
	v_mfma_f32_16x16x32_bf16 v[122:125], v[148:151], v[156:159], v[122:125]
	v_mfma_f32_16x16x32_bf16 v[110:113], v[140:143], v[164:167], v[110:113]
	v_mfma_f32_16x16x32_bf16 v[106:109], v[148:151], v[164:167], v[106:109]
	v_mfma_f32_16x16x32_bf16 v[94:97], v[140:143], v[172:175], v[94:97]
	v_mfma_f32_16x16x32_bf16 v[90:93], v[148:151], v[172:175], v[90:93]
	v_mfma_f32_16x16x32_bf16 v[78:81], v[140:143], v[180:183], v[78:81]
	v_mfma_f32_16x16x32_bf16 v[74:77], v[148:151], v[180:183], v[74:77]
	v_mfma_f32_16x16x32_bf16 v[126:129], v[144:147], v[160:163], v[126:129]
	v_mfma_f32_16x16x32_bf16 v[122:125], v[152:155], v[160:163], v[122:125]
	v_mfma_f32_16x16x32_bf16 v[110:113], v[144:147], v[168:171], v[110:113]
	v_mfma_f32_16x16x32_bf16 v[106:109], v[152:155], v[168:171], v[106:109]
	v_mfma_f32_16x16x32_bf16 v[94:97], v[144:147], v[176:179], v[94:97]
	v_mfma_f32_16x16x32_bf16 v[90:93], v[152:155], v[176:179], v[90:93]
	v_mfma_f32_16x16x32_bf16 v[78:81], v[144:147], v[184:187], v[78:81]
	v_mfma_f32_16x16x32_bf16 v[74:77], v[152:155], v[184:187], v[74:77]
	s_barrier
	s_add_i32 s25, 0, 0x1c000
	s_add_i32 s2, s24, s14
	v_add_u32_e32 v208, s25, v138
	v_lshl_add_u64 v[224:225], v[224:225], 0, s[16:17]
	s_mov_b32 m0, s2
	ds_read_b128 v[188:191], v208
	ds_read_b128 v[192:195], v208 offset:1024
	ds_read_b128 v[196:199], v208 offset:2048
	ds_read_b128 v[220:223], v208 offset:3072
	global_load_lds_dwordx4 v[224:225], off
	v_lshl_add_u64 v[224:225], v[226:227], 0, s[16:17]
	s_add_i32 m0, s2, 0x2000
	s_nop 0
	global_load_lds_dwordx4 v[224:225], off
	s_barrier
	s_waitcnt lgkmcnt(0)
	s_waitcnt lgkmcnt(0)
	v_mfma_f32_16x16x32_bf16 v[118:121], v[188:191], v[156:159], v[118:121]
	v_mfma_f32_16x16x32_bf16 v[114:117], v[196:199], v[156:159], v[114:117]
	v_mfma_f32_16x16x32_bf16 v[102:105], v[188:191], v[164:167], v[102:105]
	v_mfma_f32_16x16x32_bf16 v[98:101], v[196:199], v[164:167], v[98:101]
	v_mfma_f32_16x16x32_bf16 v[86:89], v[188:191], v[172:175], v[86:89]
	v_mfma_f32_16x16x32_bf16 v[82:85], v[196:199], v[172:175], v[82:85]
	v_mfma_f32_16x16x32_bf16 v[70:73], v[188:191], v[180:183], v[70:73]
	v_mfma_f32_16x16x32_bf16 v[66:69], v[196:199], v[180:183], v[66:69]
	v_mfma_f32_16x16x32_bf16 v[118:121], v[192:195], v[160:163], v[118:121]
	v_mfma_f32_16x16x32_bf16 v[114:117], v[220:223], v[160:163], v[114:117]
	v_mfma_f32_16x16x32_bf16 v[102:105], v[192:195], v[168:171], v[102:105]
	v_mfma_f32_16x16x32_bf16 v[98:101], v[220:223], v[168:171], v[98:101]
	v_mfma_f32_16x16x32_bf16 v[86:89], v[192:195], v[176:179], v[86:89]
	v_mfma_f32_16x16x32_bf16 v[82:85], v[220:223], v[176:179], v[82:85]
	v_mfma_f32_16x16x32_bf16 v[70:73], v[192:195], v[184:187], v[70:73]
	v_mfma_f32_16x16x32_bf16 v[66:69], v[220:223], v[184:187], v[66:69]
	s_mov_b32 m0, s21
	v_lshl_add_u64 v[224:225], v[228:229], 0, s[16:17]
	s_barrier
; #define PG8_STAGE(bufoff, gbase, voff) do { _Pragma("unroll") for (int _i = 0; _i < 2; ++_i) \
;         __builtin_amdgcn_global_load_lds((const unsigned*)((const char*)(gbase) + (voff)[_i]), (LAS unsigned*)(lds + (bufoff) + ldsw + _i * 8192), 16, 0, 0); } while (0)
; #define PG8_MMA(ai, bj, At, Bt) do { __builtin_amdgcn_s_setprio(1); _Pragma("unroll") for (int m = 0; m < 4; ++m) _Pragma("unroll") for (int n = 0; n < 2; ++n) _Pragma("unroll") for (int k = 0; k < 2; ++k) \
;         acc[ai][bj][m][n] = __builtin_amdgcn_mfma_f32_16x16x32_bf16(Bt[n][k], At[m][k], acc[ai][bj][m][n], 0, 0, 0); __builtin_amdgcn_s_setprio(0); } while (0)
; #define PG8_WAIT_V(n) asm volatile("s_waitcnt vmcnt(" #n ")" ::: "memory")
; #define PG8_WAIT_L(n) asm volatile("s_waitcnt lgkmcnt(" #n ")" ::: "memory")
; #define PG8_BAR __builtin_amdgcn_s_barrier()
; #define PG8_SCHED __builtin_amdgcn_sched_barrier(0)
; __device__ __forceinline__ f32x4 gelu4(const f32x4 x) {
;     const f32x4 t = x * x, a = x * (t * -0.10294324f + -2.3022082f);
;     f32x4 e; e[0] = __builtin_amdgcn_exp2f(a[0]); e[1] = __builtin_amdgcn_exp2f(a[1]); e[2] = __builtin_amdgcn_exp2f(a[2]); e[3] = __builtin_amdgcn_exp2f(a[3]);
;     const f32x4 d = e + 1.0f;
;     f32x4 r; r[0] = __builtin_amdgcn_rcpf(d[0]); r[1] = __builtin_amdgcn_rcpf(d[1]); r[2] = __builtin_amdgcn_rcpf(d[2]); r[3] = __builtin_amdgcn_rcpf(d[3]);
;     return x * r;
; }
;     ...
;             PG8_BAR; PG8_WAIT_L(0); PG8_MMA(1, 0, At, B0); PG8_BAR; PG8_SCHED;
;             PG8_STAGE(PG8_SB(1, 1), b3 + hstep, voffB);
;             PG8_WAIT_V(6); PG8_BAR; PG8_MMA(1, 1, At, B1); PG8_BAR;
;         }
	ds_read_b128 v[156:159], v139 offset:49152
	ds_read_b128 v[160:163], v139 offset:50176
	ds_read_b128 v[164:167], v139 offset:51200
	ds_read_b128 v[168:171], v139 offset:52224
	ds_read_b128 v[172:175], v139 offset:53248
	ds_read_b128 v[176:179], v139 offset:54272
	ds_read_b128 v[180:183], v139 offset:55296
	ds_read_b128 v[184:187], v139 offset:56320
	global_load_lds_dwordx4 v[224:225], off
	v_lshl_add_u64 v[224:225], v[230:231], 0, s[16:17]
	s_mov_b32 m0, s22
	s_nop 0
	global_load_lds_dwordx4 v[224:225], off
	s_barrier
	s_waitcnt lgkmcnt(0)
	s_waitcnt lgkmcnt(0)
	v_mfma_f32_16x16x32_bf16 v[60:63], v[140:143], v[156:159], v[60:63]
	v_mfma_f32_16x16x32_bf16 v[56:59], v[148:151], v[156:159], v[56:59]
	v_mfma_f32_16x16x32_bf16 v[44:47], v[140:143], v[164:167], v[44:47]
	v_mfma_f32_16x16x32_bf16 v[40:43], v[148:151], v[164:167], v[40:43]
	v_mfma_f32_16x16x32_bf16 v[28:31], v[140:143], v[172:175], v[28:31]
	v_mfma_f32_16x16x32_bf16 v[24:27], v[148:151], v[172:175], v[24:27]
	v_mfma_f32_16x16x32_bf16 v[12:15], v[140:143], v[180:183], v[12:15]
	v_mfma_f32_16x16x32_bf16 v[8:11], v[148:151], v[180:183], v[8:11]
	v_mfma_f32_16x16x32_bf16 v[60:63], v[144:147], v[160:163], v[60:63]
	v_mfma_f32_16x16x32_bf16 v[56:59], v[152:155], v[160:163], v[56:59]
	v_mfma_f32_16x16x32_bf16 v[44:47], v[144:147], v[168:171], v[44:47]
	v_mfma_f32_16x16x32_bf16 v[40:43], v[152:155], v[168:171], v[40:43]
	v_mfma_f32_16x16x32_bf16 v[28:31], v[144:147], v[176:179], v[28:31]
	v_mfma_f32_16x16x32_bf16 v[24:27], v[152:155], v[176:179], v[24:27]
	v_mfma_f32_16x16x32_bf16 v[12:15], v[144:147], v[184:187], v[12:15]
	v_mfma_f32_16x16x32_bf16 v[8:11], v[152:155], v[184:187], v[8:11]
	s_barrier
	s_add_u32 s2, s8, 0x84080
	s_addc_u32 s3, s9, 0
	s_add_i32 s8, s25, s14
	v_lshl_add_u64 v[140:141], s[2:3], 0, v[64:65]
	s_mov_b32 m0, s8
	s_nop 0
	global_load_lds_dwordx4 v[140:141], off
	v_lshl_add_u64 v[140:141], s[2:3], 0, v[130:131]
	s_add_i32 m0, s8, 0x2000
	s_nop 0
	global_load_lds_dwordx4 v[140:141], off
	s_waitcnt vmcnt(6)
	s_barrier
	v_mfma_f32_16x16x32_bf16 v[52:55], v[188:191], v[156:159], v[52:55]
	v_mfma_f32_16x16x32_bf16 v[48:51], v[196:199], v[156:159], v[48:51]
	v_mfma_f32_16x16x32_bf16 v[36:39], v[188:191], v[164:167], v[36:39]
	v_mfma_f32_16x16x32_bf16 v[32:35], v[196:199], v[164:167], v[32:35]
	v_mfma_f32_16x16x32_bf16 v[20:23], v[188:191], v[172:175], v[20:23]
	v_mfma_f32_16x16x32_bf16 v[16:19], v[196:199], v[172:175], v[16:19]
	v_mfma_f32_16x16x32_bf16 v[4:7], v[188:191], v[180:183], v[4:7]
	v_mfma_f32_16x16x32_bf16 v[0:3], v[196:199], v[180:183], v[0:3]
	v_mfma_f32_16x16x32_bf16 v[52:55], v[192:195], v[160:163], v[52:55]
	v_mfma_f32_16x16x32_bf16 v[48:51], v[220:223], v[160:163], v[48:51]
	v_mfma_f32_16x16x32_bf16 v[36:39], v[192:195], v[168:171], v[36:39]
	v_mfma_f32_16x16x32_bf16 v[32:35], v[220:223], v[168:171], v[32:35]
	v_mfma_f32_16x16x32_bf16 v[20:23], v[192:195], v[176:179], v[20:23]
	v_mfma_f32_16x16x32_bf16 v[16:19], v[220:223], v[176:179], v[16:19]
	v_mfma_f32_16x16x32_bf16 v[4:7], v[192:195], v[184:187], v[4:7]
	v_mfma_f32_16x16x32_bf16 v[0:3], v[220:223], v[184:187], v[0:3]
	s_add_i32 s23, s23, 2
	s_add_u32 s6, s6, 0x100
	s_addc_u32 s7, s7, 0
	s_cmp_gt_u32 s23, 29
	s_barrier
	s_cbranch_scc0 .LBB0_1275
	s_add_i32 s0, s11, -2
	s_cmp_lt_u32 s0, 8
	s_cselect_b64 s[2:3], -1, 0
	s_cmp_gt_u32 s0, 7
	s_cbranch_scc1 .LBB0_1278
	s_mov_b32 s0, 0xc0135761
	v_pk_mul_f32 v[130:131], v[128:129], v[128:129]
	v_pk_mul_f32 v[132:133], v[126:127], v[126:127]
	v_mov_b64_e32 v[134:135], s[0:1]
	s_mov_b32 s0, 0xbdd2d3e8
	v_pk_fma_f32 v[130:131], v[130:131], s[0:1], v[134:135] op_sel_hi:[1,0,0]
	v_pk_fma_f32 v[132:133], v[132:133], s[0:1], v[134:135] op_sel_hi:[1,0,0]
	v_pk_mul_f32 v[130:131], v[128:129], v[130:131]
	v_pk_mul_f32 v[132:133], v[126:127], v[132:133]
	v_exp_f32_e32 v130, v130
	v_exp_f32_e32 v132, v132
	v_exp_f32_e32 v131, v131
	v_exp_f32_e32 v133, v133
	v_pk_add_f32 v[130:131], v[130:131], 1.0 op_sel_hi:[1,0]
	v_pk_add_f32 v[132:133], v[132:133], 1.0 op_sel_hi:[1,0]
	v_rcp_f32_e32 v130, v130
	v_rcp_f32_e32 v132, v132
	v_rcp_f32_e32 v131, v131
	v_rcp_f32_e32 v133, v133
	v_pk_mul_f32 v[128:129], v[128:129], v[130:131]
	v_pk_mul_f32 v[126:127], v[126:127], v[132:133]

; #define PG8_STAGE(bufoff, gbase, voff) do { _Pragma("unroll") for (int _i = 0; _i < 2; ++_i) \
;         __builtin_amdgcn_global_load_lds((const unsigned*)((const char*)(gbase) + (voff)[_i]), (LAS unsigned*)(lds + (bufoff) + ldsw + _i * 8192), 16, 0, 0); } while (0)
; #define PG8_LDA(dst, b, h) do { _Pragma("unroll") for (int m = 0; m < 4; ++m) _Pragma("unroll") for (int k = 0; k < 2; ++k) dst[m][k] = *(const LAS bf16x8*)(lds + PG8_SA(b, h) + aoff + m * 2048 + k * 1024); } while (0)
; #define PG8_LDB(dst, b, h) do { _Pragma("unroll") for (int n = 0; n < 2; ++n) _Pragma("unroll") for (int k = 0; k < 2; ++k) dst[n][k] = *(const LAS bf16x8*)(lds + PG8_SB(b, h) + boff + n * 2048 + k * 1024); } while (0)
; #define PG8_WAIT_L(n) asm volatile("s_waitcnt lgkmcnt(" #n ")" ::: "memory")
; #define PG8_BAR __builtin_amdgcn_s_barrier()
; #define PG8_SCHED __builtin_amdgcn_sched_barrier(0)
;     ...
;         for (int t = 0; t < nt; t += 2) {
;             const bool last = (t == nt - 2);
;             if (last && has_next && gate != nullptr && nxt.pm >= 32) {
;                 if (tid < 64) { unsigned sp = 0;
;                     while ((unsigned)__builtin_amdgcn_readfirstlane(__hip_atomic_load(gate, __ATOMIC_RELAXED, __HIP_MEMORY_SCOPE_AGENT)) < gate_need) { __builtin_amdgcn_s_sleep(2); if (++sp > (1u << 20)) break; }
;                     __builtin_amdgcn_fence(__ATOMIC_ACQUIRE, "agent"); asm volatile("s_waitcnt vmcnt(0)" ::: "memory"); }
;                 asm volatile("" ::: "memory"); PG8_BAR; asm volatile("" ::: "memory");
;             }
;             const char* a1 = cA + (size_t)(t + 1) * kstep;
;             const char* a2 = last ? nA : cA + (size_t)(t + 2) * kstep; const char* b2 = last ? nB : cB + (size_t)(t + 2) * kstep;
;             const char* a3 = a2 + kstep; const char* b3 = b2 + kstep;
;             PG8_LDB(B0, 0, 0); PG8_SCHED; PG8_LDA(At, 0, 0); PG8_STAGE(PG8_SA(1, 1), a1 + hstep, voffA);
;             PG8_WAIT_L(8); PG8_BAR; PG8_WAIT_L(0); PG8_MMA(0, 0, At, B0); PG8_BAR; PG8_SCHED;
;             PG8_LDB(B1, 0, 1); PG8_STAGE(PG8_SB(0, 0), b2, voffB);
;             PG8_BAR; PG8_WAIT_L(0); PG8_MMA(0, 1, At, B1); PG8_BAR;
;             PG8_LDA(At, 0, 1); PG8_STAGE(PG8_SA(0, 0), a2, voffA);
;             PG8_BAR; PG8_WAIT_L(0); PG8_MMA(1, 0, At, B0); PG8_BAR; PG8_SCHED;
.LBB0_1441:
	s_add_u32 s4, s0, 0x100
	s_addc_u32 s5, s1, 0
	s_add_i32 s43, 0, 0x10000
	v_add_u32_e32 v140, s43, v143
	ds_read_b128 v[136:139], v140
	ds_read_b128 v[146:149], v140 offset:1024
	ds_read_b128 v[150:153], v140 offset:2048
	ds_read_b128 v[154:157], v140 offset:3072
	s_cmp_eq_u32 s42, 28
	s_cselect_b32 s3, s21, s5
	s_cselect_b32 s2, s20, s4
	s_cselect_b32 s9, s23, s41
	s_cselect_b32 s8, s22, s40
	v_lshl_add_u64 v[140:141], s[0:1], 0, v[132:133]
	s_add_i32 m0, s12, 0xc000
	ds_read_b128 v[158:161], v145
	ds_read_b128 v[162:165], v145 offset:1024
	ds_read_b128 v[166:169], v145 offset:2048
	ds_read_b128 v[170:173], v145 offset:3072
	ds_read_b128 v[174:177], v145 offset:4096
	ds_read_b128 v[178:181], v145 offset:5120
	ds_read_b128 v[182:185], v145 offset:6144
	ds_read_b128 v[186:189], v145 offset:7168
	global_load_lds_dwordx4 v[140:141], off
	v_lshl_add_u64 v[140:141], s[0:1], 0, v[134:135]
	s_add_i32 m0, s12, 0xe000
	s_nop 0
	global_load_lds_dwordx4 v[140:141], off
	s_waitcnt lgkmcnt(8)
	s_barrier
	s_waitcnt lgkmcnt(0)
	s_waitcnt lgkmcnt(0)
	v_mfma_f32_16x16x32_bf16 v[126:129], v[136:139], v[158:161], v[126:129]
	v_mfma_f32_16x16x32_bf16 v[122:125], v[150:153], v[158:161], v[122:125]
	v_mfma_f32_16x16x32_bf16 v[110:113], v[136:139], v[166:169], v[110:113]
	v_mfma_f32_16x16x32_bf16 v[106:109], v[150:153], v[166:169], v[106:109]
	v_mfma_f32_16x16x32_bf16 v[94:97], v[136:139], v[174:177], v[94:97]
	v_mfma_f32_16x16x32_bf16 v[90:93], v[150:153], v[174:177], v[90:93]
	v_mfma_f32_16x16x32_bf16 v[78:81], v[136:139], v[182:185], v[78:81]
	v_mfma_f32_16x16x32_bf16 v[74:77], v[150:153], v[182:185], v[74:77]
	v_mfma_f32_16x16x32_bf16 v[126:129], v[146:149], v[162:165], v[126:129]
	v_mfma_f32_16x16x32_bf16 v[122:125], v[154:157], v[162:165], v[122:125]
	v_mfma_f32_16x16x32_bf16 v[110:113], v[146:149], v[170:173], v[110:113]
	v_mfma_f32_16x16x32_bf16 v[106:109], v[154:157], v[170:173], v[106:109]
	v_mfma_f32_16x16x32_bf16 v[94:97], v[146:149], v[178:181], v[94:97]
	v_mfma_f32_16x16x32_bf16 v[90:93], v[154:157], v[178:181], v[90:93]
	v_mfma_f32_16x16x32_bf16 v[78:81], v[146:149], v[186:189], v[78:81]
	v_mfma_f32_16x16x32_bf16 v[74:77], v[154:157], v[186:189], v[74:77]
	s_barrier
	s_add_i32 s44, 0, 0x14000
	v_add_u32_e32 v140, s44, v143
	s_add_i32 s0, s43, s11
	ds_read_b128 v[190:193], v140
	ds_read_b128 v[194:197], v140 offset:1024
	ds_read_b128 v[220:223], v140 offset:2048
	ds_read_b128 v[224:227], v140 offset:3072
	v_lshl_add_u64 v[140:141], s[8:9], 0, v[64:65]
	s_mov_b32 m0, s0
	v_lshl_add_u64 v[198:199], s[8:9], 0, v[130:131]
	global_load_lds_dwordx4 v[140:141], off
	s_add_i32 m0, s0, 0x2000
	s_nop 0
	global_load_lds_dwordx4 v[198:199], off
	s_barrier
	s_waitcnt lgkmcnt(0)
	s_waitcnt lgkmcnt(0)
	v_mfma_f32_16x16x32_bf16 v[118:121], v[190:193], v[158:161], v[118:121]
	v_mfma_f32_16x16x32_bf16 v[114:117], v[220:223], v[158:161], v[114:117]
	v_mfma_f32_16x16x32_bf16 v[102:105], v[190:193], v[166:169], v[102:105]
	v_mfma_f32_16x16x32_bf16 v[98:101], v[220:223], v[166:169], v[98:101]
	v_mfma_f32_16x16x32_bf16 v[86:89], v[190:193], v[174:177], v[86:89]
	v_mfma_f32_16x16x32_bf16 v[82:85], v[220:223], v[174:177], v[82:85]
	v_mfma_f32_16x16x32_bf16 v[70:73], v[190:193], v[182:185], v[70:73]
	v_mfma_f32_16x16x32_bf16 v[66:69], v[220:223], v[182:185], v[66:69]
	v_mfma_f32_16x16x32_bf16 v[118:121], v[194:197], v[162:165], v[118:121]
	v_mfma_f32_16x16x32_bf16 v[114:117], v[224:227], v[162:165], v[114:117]
	v_mfma_f32_16x16x32_bf16 v[102:105], v[194:197], v[170:173], v[102:105]
	v_mfma_f32_16x16x32_bf16 v[98:101], v[224:227], v[170:173], v[98:101]
	v_mfma_f32_16x16x32_bf16 v[86:89], v[194:197], v[178:181], v[86:89]
	v_mfma_f32_16x16x32_bf16 v[82:85], v[224:227], v[178:181], v[82:85]
	v_mfma_f32_16x16x32_bf16 v[70:73], v[194:197], v[186:189], v[70:73]
	v_mfma_f32_16x16x32_bf16 v[66:69], v[224:227], v[186:189], v[66:69]
	s_mov_b32 m0, s12
	v_lshl_add_u64 v[228:229], s[2:3], 0, v[64:65]
	s_barrier
	ds_read_b128 v[158:161], v145 offset:16384
	ds_read_b128 v[162:165], v145 offset:17408
	ds_read_b128 v[166:169], v145 offset:18432
	ds_read_b128 v[170:173], v145 offset:19456
	ds_read_b128 v[174:177], v145 offset:20480
	ds_read_b128 v[178:181], v145 offset:21504
	ds_read_b128 v[182:185], v145 offset:22528
	ds_read_b128 v[186:189], v145 offset:23552
	global_load_lds_dwordx4 v[228:229], off
	v_lshl_add_u64 v[230:231], s[2:3], 0, v[130:131]
	s_mov_b32 m0, s13
	s_nop 0
	global_load_lds_dwordx4 v[230:231], off
	s_barrier
	s_waitcnt lgkmcnt(0)
	s_waitcnt lgkmcnt(0)
	v_mfma_f32_16x16x32_bf16 v[60:63], v[136:139], v[158:161], v[60:63]
	v_mfma_f32_16x16x32_bf16 v[56:59], v[150:153], v[158:161], v[56:59]
	v_mfma_f32_16x16x32_bf16 v[44:47], v[136:139], v[166:169], v[44:47]
	v_mfma_f32_16x16x32_bf16 v[40:43], v[150:153], v[166:169], v[40:43]
	v_mfma_f32_16x16x32_bf16 v[28:31], v[136:139], v[174:177], v[28:31]
	v_mfma_f32_16x16x32_bf16 v[24:27], v[150:153], v[174:177], v[24:27]
	v_mfma_f32_16x16x32_bf16 v[12:15], v[136:139], v[182:185], v[12:15]
	v_mfma_f32_16x16x32_bf16 v[8:11], v[150:153], v[182:185], v[8:11]
	v_mfma_f32_16x16x32_bf16 v[60:63], v[146:149], v[162:165], v[60:63]
	v_mfma_f32_16x16x32_bf16 v[56:59], v[154:157], v[162:165], v[56:59]
	v_mfma_f32_16x16x32_bf16 v[44:47], v[146:149], v[170:173], v[44:47]
	v_mfma_f32_16x16x32_bf16 v[40:43], v[154:157], v[170:173], v[40:43]
	v_mfma_f32_16x16x32_bf16 v[28:31], v[146:149], v[178:181], v[28:31]
	v_mfma_f32_16x16x32_bf16 v[24:27], v[154:157], v[178:181], v[24:27]
	v_mfma_f32_16x16x32_bf16 v[12:15], v[146:149], v[186:189], v[12:15]
	v_mfma_f32_16x16x32_bf16 v[8:11], v[154:157], v[186:189], v[8:11]
	s_barrier
; #define PG8_STAGE(bufoff, gbase, voff) do { _Pragma("unroll") for (int _i = 0; _i < 2; ++_i) \
;         __builtin_amdgcn_global_load_lds((const unsigned*)((const char*)(gbase) + (voff)[_i]), (LAS unsigned*)(lds + (bufoff) + ldsw + _i * 8192), 16, 0, 0); } while (0)
; #define PG8_LDA(dst, b, h) do { _Pragma("unroll") for (int m = 0; m < 4; ++m) _Pragma("unroll") for (int k = 0; k < 2; ++k) dst[m][k] = *(const LAS bf16x8*)(lds + PG8_SA(b, h) + aoff + m * 2048 + k * 1024); } while (0)
; #define PG8_LDB(dst, b, h) do { _Pragma("unroll") for (int n = 0; n < 2; ++n) _Pragma("unroll") for (int k = 0; k < 2; ++k) dst[n][k] = *(const LAS bf16x8*)(lds + PG8_SB(b, h) + boff + n * 2048 + k * 1024); } while (0)
; #define PG8_MMA(ai, bj, At, Bt) do { __builtin_amdgcn_s_setprio(1); _Pragma("unroll") for (int m = 0; m < 4; ++m) _Pragma("unroll") for (int n = 0; n < 2; ++n) _Pragma("unroll") for (int k = 0; k < 2; ++k) \
;         acc[ai][bj][m][n] = __builtin_amdgcn_mfma_f32_16x16x32_bf16(Bt[n][k], At[m][k], acc[ai][bj][m][n], 0, 0, 0); __builtin_amdgcn_s_setprio(0); } while (0)
; #define PG8_WAIT_V(n) asm volatile("s_waitcnt vmcnt(" #n ")" ::: "memory")
; #define PG8_WAIT_L(n) asm volatile("s_waitcnt lgkmcnt(" #n ")" ::: "memory")
; #define PG8_BAR __builtin_amdgcn_s_barrier()
; #define PG8_SCHED __builtin_amdgcn_sched_barrier(0)
;     ...
;             PG8_STAGE(PG8_SB(0, 1), b2 + hstep, voffB);
;             PG8_WAIT_V(6); PG8_BAR; PG8_MMA(1, 1, At, B1); PG8_BAR;
;             PG8_LDB(B0, 1, 0); PG8_SCHED; PG8_LDA(At, 1, 0); PG8_STAGE(PG8_SA(0, 1), a2 + hstep, voffA);
;             PG8_WAIT_L(8); PG8_BAR; PG8_WAIT_L(0); PG8_MMA(0, 0, At, B0); PG8_BAR; PG8_SCHED;
;             PG8_LDB(B1, 1, 1); PG8_STAGE(PG8_SB(1, 0), b3, voffB);
;             PG8_BAR; PG8_WAIT_L(0); PG8_MMA(0, 1, At, B1); PG8_BAR;
;             PG8_LDA(At, 1, 1); PG8_STAGE(PG8_SA(1, 0), a3, voffA);
;             PG8_BAR; PG8_WAIT_L(0); PG8_MMA(1, 0, At, B0); PG8_BAR; PG8_SCHED;
;             PG8_STAGE(PG8_SB(1, 1), b3 + hstep, voffB);
;             PG8_WAIT_V(6); PG8_BAR; PG8_MMA(1, 1, At, B1); PG8_BAR;
	s_add_u32 s0, s8, 0x84000
	s_addc_u32 s1, s9, 0
	s_add_i32 s43, s44, s11
	v_lshl_add_u64 v[136:137], s[0:1], 0, v[64:65]
	s_mov_b32 m0, s43
	s_nop 0
	global_load_lds_dwordx4 v[136:137], off
	v_lshl_add_u64 v[136:137], s[0:1], 0, v[130:131]
	s_add_i32 m0, s43, 0x2000
	s_nop 0
	global_load_lds_dwordx4 v[136:137], off
	s_waitcnt vmcnt(6)
	s_barrier
	v_mfma_f32_16x16x32_bf16 v[52:55], v[190:193], v[158:161], v[52:55]
	v_mfma_f32_16x16x32_bf16 v[48:51], v[220:223], v[158:161], v[48:51]
	v_mfma_f32_16x16x32_bf16 v[36:39], v[190:193], v[166:169], v[36:39]
	v_mfma_f32_16x16x32_bf16 v[32:35], v[220:223], v[166:169], v[32:35]
	v_mfma_f32_16x16x32_bf16 v[20:23], v[190:193], v[174:177], v[20:23]
	v_mfma_f32_16x16x32_bf16 v[16:19], v[220:223], v[174:177], v[16:19]
	v_mfma_f32_16x16x32_bf16 v[4:7], v[190:193], v[182:185], v[4:7]
	v_mfma_f32_16x16x32_bf16 v[0:3], v[220:223], v[182:185], v[0:3]
	v_mfma_f32_16x16x32_bf16 v[52:55], v[194:197], v[162:165], v[52:55]
	v_mfma_f32_16x16x32_bf16 v[48:51], v[224:227], v[162:165], v[48:51]
	v_mfma_f32_16x16x32_bf16 v[36:39], v[194:197], v[170:173], v[36:39]
	v_mfma_f32_16x16x32_bf16 v[32:35], v[224:227], v[170:173], v[32:35]
	v_mfma_f32_16x16x32_bf16 v[20:23], v[194:197], v[178:181], v[20:23]
	v_mfma_f32_16x16x32_bf16 v[16:19], v[224:227], v[178:181], v[16:19]
	v_mfma_f32_16x16x32_bf16 v[4:7], v[194:197], v[186:189], v[4:7]
	v_mfma_f32_16x16x32_bf16 v[0:3], v[224:227], v[186:189], v[0:3]
	s_add_i32 s43, 0, 0x18000
	v_add_u32_e32 v154, s43, v143
	s_barrier
	ds_read_b128 v[136:139], v154
	ds_read_b128 v[146:149], v154 offset:1024
	ds_read_b128 v[150:153], v154 offset:2048
	ds_read_b128 v[154:157], v154 offset:3072
	s_add_u32 s0, s2, 0x84000
	s_addc_u32 s1, s3, 0
	s_mov_b32 m0, s14
	v_lshl_add_u64 v[190:191], s[0:1], 0, v[64:65]
	ds_read_b128 v[158:161], v145 offset:32768
	ds_read_b128 v[162:165], v145 offset:33792
	ds_read_b128 v[166:169], v145 offset:34816
	ds_read_b128 v[170:173], v145 offset:35840
	ds_read_b128 v[174:177], v145 offset:36864
	ds_read_b128 v[178:181], v145 offset:37888
	ds_read_b128 v[182:185], v145 offset:38912
	ds_read_b128 v[186:189], v145 offset:39936
	global_load_lds_dwordx4 v[190:191], off
	v_lshl_add_u64 v[190:191], s[0:1], 0, v[130:131]
	s_mov_b32 m0, s15
	s_nop 0
	global_load_lds_dwordx4 v[190:191], off
	s_waitcnt lgkmcnt(8)
	s_barrier
	s_waitcnt lgkmcnt(0)
	s_waitcnt lgkmcnt(0)
	v_mfma_f32_16x16x32_bf16 v[126:129], v[136:139], v[158:161], v[126:129]
	v_mfma_f32_16x16x32_bf16 v[122:125], v[150:153], v[158:161], v[122:125]
	v_mfma_f32_16x16x32_bf16 v[110:113], v[136:139], v[166:169], v[110:113]
	v_mfma_f32_16x16x32_bf16 v[106:109], v[150:153], v[166:169], v[106:109]
	v_mfma_f32_16x16x32_bf16 v[94:97], v[136:139], v[174:177], v[94:97]
	v_mfma_f32_16x16x32_bf16 v[90:93], v[150:153], v[174:177], v[90:93]
	v_mfma_f32_16x16x32_bf16 v[78:81], v[136:139], v[182:185], v[78:81]
	v_mfma_f32_16x16x32_bf16 v[74:77], v[150:153], v[182:185], v[74:77]
	v_mfma_f32_16x16x32_bf16 v[126:129], v[146:149], v[162:165], v[126:129]
	v_mfma_f32_16x16x32_bf16 v[122:125], v[154:157], v[162:165], v[122:125]
	v_mfma_f32_16x16x32_bf16 v[110:113], v[146:149], v[170:173], v[110:113]
	v_mfma_f32_16x16x32_bf16 v[106:109], v[154:157], v[170:173], v[106:109]
	v_mfma_f32_16x16x32_bf16 v[94:97], v[146:149], v[178:181], v[94:97]
	v_mfma_f32_16x16x32_bf16 v[90:93], v[154:157], v[178:181], v[90:93]
	v_mfma_f32_16x16x32_bf16 v[78:81], v[146:149], v[186:189], v[78:81]
	v_mfma_f32_16x16x32_bf16 v[74:77], v[154:157], v[186:189], v[74:77]
	s_barrier
	s_add_i32 s2, 0, 0x1c000
	s_add_i32 s0, s43, s11
	v_add_u32_e32 v208, s2, v143
	v_lshl_add_u64 v[140:141], v[140:141], 0, s[16:17]
	s_mov_b32 m0, s0
	ds_read_b128 v[190:193], v208
	ds_read_b128 v[194:197], v208 offset:1024
	ds_read_b128 v[220:223], v208 offset:2048
	ds_read_b128 v[224:227], v208 offset:3072
	global_load_lds_dwordx4 v[140:141], off
	v_lshl_add_u64 v[140:141], v[198:199], 0, s[16:17]
	s_add_i32 m0, s0, 0x2000
	s_nop 0
	global_load_lds_dwordx4 v[140:141], off
	s_barrier
	s_waitcnt lgkmcnt(0)
	s_waitcnt lgkmcnt(0)
	v_mfma_f32_16x16x32_bf16 v[118:121], v[190:193], v[158:161], v[118:121]
	v_mfma_f32_16x16x32_bf16 v[114:117], v[220:223], v[158:161], v[114:117]
	v_mfma_f32_16x16x32_bf16 v[102:105], v[190:193], v[166:169], v[102:105]
	v_mfma_f32_16x16x32_bf16 v[98:101], v[220:223], v[166:169], v[98:101]
	v_mfma_f32_16x16x32_bf16 v[86:89], v[190:193], v[174:177], v[86:89]
	v_mfma_f32_16x16x32_bf16 v[82:85], v[220:223], v[174:177], v[82:85]
	v_mfma_f32_16x16x32_bf16 v[70:73], v[190:193], v[182:185], v[70:73]
	v_mfma_f32_16x16x32_bf16 v[66:69], v[220:223], v[182:185], v[66:69]
	v_mfma_f32_16x16x32_bf16 v[118:121], v[194:197], v[162:165], v[118:121]
	v_mfma_f32_16x16x32_bf16 v[114:117], v[224:227], v[162:165], v[114:117]
	v_mfma_f32_16x16x32_bf16 v[102:105], v[194:197], v[170:173], v[102:105]
	v_mfma_f32_16x16x32_bf16 v[98:101], v[224:227], v[170:173], v[98:101]
	v_mfma_f32_16x16x32_bf16 v[86:89], v[194:197], v[178:181], v[86:89]
	v_mfma_f32_16x16x32_bf16 v[82:85], v[224:227], v[178:181], v[82:85]
	v_mfma_f32_16x16x32_bf16 v[70:73], v[194:197], v[186:189], v[70:73]
	v_mfma_f32_16x16x32_bf16 v[66:69], v[224:227], v[186:189], v[66:69]
	s_mov_b32 m0, s24
	v_lshl_add_u64 v[140:141], v[228:229], 0, s[16:17]
	s_barrier
; #define PG8_STAGE(bufoff, gbase, voff) do { _Pragma("unroll") for (int _i = 0; _i < 2; ++_i) \
;         __builtin_amdgcn_global_load_lds((const unsigned*)((const char*)(gbase) + (voff)[_i]), (LAS unsigned*)(lds + (bufoff) + ldsw + _i * 8192), 16, 0, 0); } while (0)
; #define PG8_LDA(dst, b, h) do { _Pragma("unroll") for (int m = 0; m < 4; ++m) _Pragma("unroll") for (int k = 0; k < 2; ++k) dst[m][k] = *(const LAS bf16x8*)(lds + PG8_SA(b, h) + aoff + m * 2048 + k * 1024); } while (0)
; #define PG8_LDB(dst, b, h) do { _Pragma("unroll") for (int n = 0; n < 2; ++n) _Pragma("unroll") for (int k = 0; k < 2; ++k) dst[n][k] = *(const LAS bf16x8*)(lds + PG8_SB(b, h) + boff + n * 2048 + k * 1024); } while (0)
; #define PG8_WAIT_V(n) asm volatile("s_waitcnt vmcnt(" #n ")" ::: "memory")
; #define PG8_WAIT_L(n) asm volatile("s_waitcnt lgkmcnt(" #n ")" ::: "memory")
; #define PG8_BAR __builtin_amdgcn_s_barrier()
; #define PG8_SCHED __builtin_amdgcn_sched_barrier(0)
; __device__ __forceinline__ f32x4 gelu4(const f32x4 x) {
;     const f32x4 t = x * x, a = x * (t * -0.10294324f + -2.3022082f);
;     f32x4 e; e[0] = __builtin_amdgcn_exp2f(a[0]); e[1] = __builtin_amdgcn_exp2f(a[1]); e[2] = __builtin_amdgcn_exp2f(a[2]); e[3] = __builtin_amdgcn_exp2f(a[3]);
;     const f32x4 d = e + 1.0f;
;     f32x4 r; r[0] = __builtin_amdgcn_rcpf(d[0]); r[1] = __builtin_amdgcn_rcpf(d[1]); r[2] = __builtin_amdgcn_rcpf(d[2]); r[3] = __builtin_amdgcn_rcpf(d[3]);
;     return x * r;
; }
;     ...
;             PG8_BAR; PG8_WAIT_L(0); PG8_MMA(1, 0, At, B0); PG8_BAR; PG8_SCHED;
;             PG8_STAGE(PG8_SB(0, 1), b2 + hstep, voffB);
;             PG8_WAIT_V(6); PG8_BAR; PG8_MMA(1, 1, At, B1); PG8_BAR;
;             PG8_LDB(B0, 1, 0); PG8_SCHED; PG8_LDA(At, 1, 0); PG8_STAGE(PG8_SA(0, 1), a2 + hstep, voffA);
;             PG8_WAIT_L(8); PG8_BAR; PG8_WAIT_L(0); PG8_MMA(0, 0, At, B0); PG8_BAR; PG8_SCHED;
;             PG8_LDB(B1, 1, 1); PG8_STAGE(PG8_SB(1, 0), b3, voffB);
;             PG8_BAR; PG8_WAIT_L(0); PG8_MMA(0, 1, At, B1); PG8_BAR;
;             PG8_LDA(At, 1, 1); PG8_STAGE(PG8_SA(1, 0), a3, voffA);
;             PG8_BAR; PG8_WAIT_L(0); PG8_MMA(1, 0, At, B0); PG8_BAR; PG8_SCHED;
;             PG8_STAGE(PG8_SB(1, 1), b3 + hstep, voffB);
;             PG8_WAIT_V(6); PG8_BAR; PG8_MMA(1, 1, At, B1); PG8_BAR;
	ds_read_b128 v[158:161], v145 offset:49152
	ds_read_b128 v[162:165], v145 offset:50176
	ds_read_b128 v[166:169], v145 offset:51200
	ds_read_b128 v[170:173], v145 offset:52224
	ds_read_b128 v[174:177], v145 offset:53248
	ds_read_b128 v[178:181], v145 offset:54272
	ds_read_b128 v[182:185], v145 offset:55296
	ds_read_b128 v[186:189], v145 offset:56320
	global_load_lds_dwordx4 v[140:141], off
	v_lshl_add_u64 v[140:141], v[230:231], 0, s[16:17]
	s_mov_b32 m0, s25
	s_nop 0
	global_load_lds_dwordx4 v[140:141], off
	s_barrier
	s_waitcnt lgkmcnt(0)
	s_waitcnt lgkmcnt(0)
	v_mfma_f32_16x16x32_bf16 v[60:63], v[136:139], v[158:161], v[60:63]
	v_mfma_f32_16x16x32_bf16 v[56:59], v[150:153], v[158:161], v[56:59]
	v_mfma_f32_16x16x32_bf16 v[44:47], v[136:139], v[166:169], v[44:47]
	v_mfma_f32_16x16x32_bf16 v[40:43], v[150:153], v[166:169], v[40:43]
	v_mfma_f32_16x16x32_bf16 v[28:31], v[136:139], v[174:177], v[28:31]
	v_mfma_f32_16x16x32_bf16 v[24:27], v[150:153], v[174:177], v[24:27]
	v_mfma_f32_16x16x32_bf16 v[12:15], v[136:139], v[182:185], v[12:15]
	v_mfma_f32_16x16x32_bf16 v[8:11], v[150:153], v[182:185], v[8:11]
	v_mfma_f32_16x16x32_bf16 v[60:63], v[146:149], v[162:165], v[60:63]
	v_mfma_f32_16x16x32_bf16 v[56:59], v[154:157], v[162:165], v[56:59]
	v_mfma_f32_16x16x32_bf16 v[44:47], v[146:149], v[170:173], v[44:47]
	v_mfma_f32_16x16x32_bf16 v[40:43], v[154:157], v[170:173], v[40:43]
	v_mfma_f32_16x16x32_bf16 v[28:31], v[146:149], v[178:181], v[28:31]
	v_mfma_f32_16x16x32_bf16 v[24:27], v[154:157], v[178:181], v[24:27]
	v_mfma_f32_16x16x32_bf16 v[12:15], v[146:149], v[186:189], v[12:15]
	v_mfma_f32_16x16x32_bf16 v[8:11], v[154:157], v[186:189], v[8:11]
	s_barrier
	s_add_u32 s0, s8, 0x84080
	s_addc_u32 s1, s9, 0
	s_add_i32 s2, s2, s11
	v_lshl_add_u64 v[136:137], s[0:1], 0, v[64:65]
	s_mov_b32 m0, s2
	s_nop 0
	global_load_lds_dwordx4 v[136:137], off
	v_lshl_add_u64 v[136:137], s[0:1], 0, v[130:131]
	s_add_i32 m0, s2, 0x2000
	s_nop 0
	global_load_lds_dwordx4 v[136:137], off
	s_waitcnt vmcnt(6)
	s_barrier
	v_mfma_f32_16x16x32_bf16 v[52:55], v[190:193], v[158:161], v[52:55]
	v_mfma_f32_16x16x32_bf16 v[48:51], v[220:223], v[158:161], v[48:51]
	v_mfma_f32_16x16x32_bf16 v[36:39], v[190:193], v[166:169], v[36:39]
	v_mfma_f32_16x16x32_bf16 v[32:35], v[220:223], v[166:169], v[32:35]
	v_mfma_f32_16x16x32_bf16 v[20:23], v[190:193], v[174:177], v[20:23]
	v_mfma_f32_16x16x32_bf16 v[16:19], v[220:223], v[174:177], v[16:19]
	v_mfma_f32_16x16x32_bf16 v[4:7], v[190:193], v[182:185], v[4:7]
	v_mfma_f32_16x16x32_bf16 v[0:3], v[220:223], v[182:185], v[0:3]
	v_mfma_f32_16x16x32_bf16 v[52:55], v[194:197], v[162:165], v[52:55]
	v_mfma_f32_16x16x32_bf16 v[48:51], v[224:227], v[162:165], v[48:51]
	v_mfma_f32_16x16x32_bf16 v[36:39], v[194:197], v[170:173], v[36:39]
	v_mfma_f32_16x16x32_bf16 v[32:35], v[224:227], v[170:173], v[32:35]
	v_mfma_f32_16x16x32_bf16 v[20:23], v[194:197], v[178:181], v[20:23]
	v_mfma_f32_16x16x32_bf16 v[16:19], v[224:227], v[178:181], v[16:19]
	v_mfma_f32_16x16x32_bf16 v[4:7], v[194:197], v[186:189], v[4:7]
	v_mfma_f32_16x16x32_bf16 v[0:3], v[224:227], v[186:189], v[0:3]
	s_add_i32 s42, s42, 2
	s_add_u32 s40, s40, 0x100
	s_addc_u32 s41, s41, 0
	s_cmp_gt_u32 s42, 29
	s_mov_b64 s[0:1], s[4:5]
	s_barrier
	s_cbranch_scc0 .LBB0_1441
	s_add_i32 s0, s38, -2
	s_cmp_lt_u32 s0, 8
	s_cselect_b64 s[2:3], -1, 0
	s_cmp_gt_u32 s0, 7
	s_cbranch_scc1 .LBB0_1444
	s_mov_b32 s40, 0xc0135761
	v_pk_mul_f32 v[136:137], v[128:129], v[128:129]
	v_pk_mul_f32 v[138:139], v[126:127], v[126:127]
	v_mov_b64_e32 v[140:141], s[40:41]
	s_mov_b32 s0, 0xbdd2d3e8
	v_pk_fma_f32 v[136:137], v[136:137], s[0:1], v[140:141] op_sel_hi:[1,0,0]
	v_pk_fma_f32 v[138:139], v[138:139], s[0:1], v[140:141] op_sel_hi:[1,0,0]
	v_pk_mul_f32 v[136:137], v[128:129], v[136:137]
	v_pk_mul_f32 v[138:139], v[126:127], v[138:139]
	v_exp_f32_e32 v136, v136
	v_exp_f32_e32 v138, v138
	v_exp_f32_e32 v137, v137
	v_exp_f32_e32 v139, v139
	v_pk_add_f32 v[136:137], v[136:137], 1.0 op_sel_hi:[1,0]
	v_pk_add_f32 v[138:139], v[138:139], 1.0 op_sel_hi:[1,0]
	v_rcp_f32_e32 v136, v136
	v_rcp_f32_e32 v138, v138
	v_rcp_f32_e32 v137, v137
	v_rcp_f32_e32 v139, v139
	v_pk_mul_f32 v[128:129], v[128:129], v[136:137]
	v_pk_mul_f32 v[126:127], v[126:127], v[138:139]
	s_branch .LBB0_1445
